# X3: MFMA-chain LDS reads issued ahead + pipelined S.V loops + tail loads hoisted; SWA attention (both copies): LDS fragment reads of QK/PV chains issued 6 ahead with counted waits
# baseline (speedup 1.0000x reference)
; DI int fresh_lane() { int l; asm volatile("v_mbcnt_lo_u32_b32 %0, -1, 0\n\tv_mbcnt_hi_u32_b32 %0, -1, %0" : "=v"(l)); return l; }
; template <int D, int MODE, int NSUB>
; DI void attn_item(const bf16* QKV, int pitch, int qcol0, int kcol0, const bf16* VT, bf16* O, int ocol0, const float* sink,
;                   LAS unsigned char* lds, int item, int tid_in, int lane_in, int wave) {
;     ...
;     int tid = wave * 64 + fresh_lane(); asm volatile("" : "+v"(tid)); const int lane = tid & 63;
;     constexpr int KT = 64 * NSUB, KP = D + 8, VP = KT + 4, KBYTES = KT * KP * 2, VBYTES = D * VP * 2, BUF = KBYTES + VBYTES, NPT = NSUB * D / 64, NKS = D / 16, NDT = D / 32, CPR = D / 8, VCR = 8 * NSUB;
;     static_assert(2 * BUF <= LDS_BYTES - 16, "attention LDS");
;     const int r = lane & 31, h = lane >> 5;
;     int b, kvh, head, qrow, qpos = 0, nt, wstart = 0;
;     if (MODE == 0) { const int qb = item & 15; head = (item >> 4) & 7; b = item >> 7; kvh = head >> 2; qrow = NCTX + b * SEQ + qb * 256 + 32 * wave; nt = KVLEN / KT; }
;     else if (MODE == 1) { const int nb = item & 31, hp = (item >> 5) & 1; kvh = (item >> 6) & 1; b = item >> 7; head = kvh * 4 + hp * 2 + (wave >> 2);
;         qpos = nb * 128 + (wave & 3) * 32 + r; qrow = NCTX + b * SEQ + nb * 128 + (wave & 3) * 32;
;         wstart = nb > 0 ? (nb - 1) * 128 : 0; const int wend = nb < 31 ? (nb + 2) * 128 : SEQ; nt = (CTXL + wend - wstart) / KT; }
;     else { const int qh = item & 1, hp = (item >> 1) & 1; kvh = (item >> 2) & 1; b = item >> 3; head = kvh * 4 + hp * 2 + (wave >> 2); qrow = b * 256 + qh * 128 + (wave & 3) * 32; nt = CTXL / KT; }
;     const bf16* VTb = VT + (size_t)(b * 2 + kvh) * D * KVLEN;
;     const int kcol = kcol0 + kvh * D;
;     bf16x8 qf[NKS];
;     { const bf16* qp = QKV + (size_t)(qrow + r) * pitch + qcol0 + head * D + 8 * h;
; #pragma unroll
;         for (int ks = 0; ks < NKS; ++ks) qf[ks] = *(const bf16x8*)(qp + 16 * ks); }
;     const float scl = (D == 64 ? 0.125f : 0.08838834764831845f) * LOG2E;
;     constexpr float THR2 = 11.0f;
;     float mrun, lrun;
;     if (MODE == 0) { mrun = -INFINITY; lrun = 0.f; } else { mrun = sink[head] * LOG2E; lrun = h == 0 ? 1.f : 0.f; }
;     f32x16 o[NDT];
; #pragma unroll
;     for (int dt = 0; dt < NDT; ++dt) o[dt] = zero16();
;     u32x4 kr[NPT], vr[NPT];
;     ...
;     ATT_LOAD(0); ATT_STORE(0);
;     __syncthreads();
.LBB0_490:
	s_cmpk_gt_i32 s47, 0x3ff
	s_mov_b64 s[4:5], -1
	s_cbranch_scc0 .LBB0_502
	s_add_i32 s0, s47, 0xfffffc00
	s_and_b32 s4, s47, 2
	s_bfe_u32 s12, s47, 0x10002
	v_readlane_b32 s7, v254, 29
	s_lshr_b32 s5, s0, 3
	s_lshl_b32 s6, s12, 2
	s_add_i32 s4, s4, s7
	s_lshl_b32 s0, s0, 7
	s_add_i32 s6, s4, s6
	s_and_b32 s10, s0, 0x80
	s_lshl_b32 s0, s5, 7
	s_lshl_b32 s4, s12, 6
	s_or_b32 s0, s4, s0
	s_mulk_i32 s0, 0x1100
	s_lshl_b32 s7, s5, 8
	s_lshl_b64 s[4:5], s[0:1], 1
	v_readlane_b32 s22, v254, 14
	v_readlane_b32 s23, v254, 15
	s_add_u32 s4, s22, s4
	v_readlane_b32 s0, v254, 27
	v_mbcnt_lo_u32_b32 v0, -1, 0
	v_mbcnt_hi_u32_b32 v0, -1, v0
	s_addc_u32 s5, s23, s5
	v_add_u32_e32 v16, s86, v0
	s_or_b32 s0, s10, s0
	s_or_b32 s0, s0, s7
	v_and_b32_e32 v15, 31, v16
	v_or_b32_e32 v14, s0, v15
	v_mov_b64_e32 v[2:3], s[82:83]
	v_mad_u64_u32 v[2:3], s[10:11], v14, s8, v[2:3]
	s_lshl_b32 s0, s6, 7
	v_lshl_add_u64 v[2:3], v[2:3], 0, s[0:1]
	s_lshl_b32 s0, s6, 2
	v_ashrrev_i32_e32 v22, 31, v16
	v_mov_b32_e32 v17, s0
	s_lshl_b32 s0, s12, 7
	v_lshrrev_b32_e32 v18, 29, v22
	s_add_u32 s0, s82, s0
	v_add_u32_e32 v20, v16, v18
	s_addc_u32 s11, s83, 0
	v_ashrrev_i32_e32 v44, 3, v20
	v_and_b32_e32 v20, -8, v20
	s_waitcnt vmcnt(9)
	v_bfe_u32 v102, v16, 5, 1
	s_add_u32 s10, s0, 0x1400
	v_sub_u32_e32 v45, v16, v20
	v_lshrrev_b32_e32 v22, 28, v22
	v_lshlrev_b32_e32 v0, 4, v102
	s_addc_u32 s11, s11, 0
	v_lshlrev_b32_e32 v20, 3, v45
	v_add_u32_e32 v24, v16, v22
	v_lshl_add_u64 v[2:3], v[2:3], 0, v[0:1]
	v_add_u32_e32 v18, s7, v44
	v_mov_b64_e32 v[34:35], s[10:11]
	v_ashrrev_i32_e32 v21, 31, v20
	v_ashrrev_i32_e32 v46, 4, v24
	v_and_b32_e32 v24, -16, v24
	v_lshl_add_u64 v[4:5], v[2:3], 0, s[18:19]
	v_add_co_u32_e32 v2, vcc, s9, v2
	v_mad_i64_i32 v[18:19], s[10:11], v18, s8, v[34:35]
	v_lshlrev_b64 v[36:37], 1, v[20:21]
	v_sub_u32_e32 v47, v16, v24
	v_add_u32_e32 v16, 0x200, v16
	v_addc_co_u32_e32 v3, vcc, 0, v3, vcc
	v_lshl_add_u64 v[18:19], v[18:19], 0, v[36:37]
	v_ashrrev_i32_e32 v32, 31, v16
	global_load_dwordx4 v[80:83], v[2:3], off
	global_load_dwordx4 v[10:13], v[4:5], off offset:32
	global_load_dwordx4 v[6:9], v[4:5], off offset:64
	s_nop 0
	global_load_dwordx4 v[2:5], v[4:5], off offset:96
	v_mov_b64_e32 v[30:31], s[4:5]
	global_load_dwordx4 v[18:21], v[18:19], off
	v_lshlrev_b32_e32 v24, 3, v47
	v_lshrrev_b32_e32 v26, 29, v32
	v_mad_i64_i32 v[22:23], s[4:5], v46, s14, v[30:31]
	v_ashrrev_i32_e32 v25, 31, v24
	v_add_u32_e32 v28, v16, v26
	v_lshrrev_b32_e32 v32, 28, v32
	v_lshl_add_u64 v[38:39], v[24:25], 1, v[22:23]
	v_ashrrev_i32_e32 v48, 3, v28
	v_and_b32_e32 v28, -8, v28
	v_add_u32_e32 v32, v16, v32
	global_load_dwordx4 v[22:25], v[38:39], off
	v_sub_u32_e32 v49, v16, v28
	v_ashrrev_i32_e32 v50, 4, v32
	v_and_b32_e32 v32, -16, v32
	v_lshlrev_b32_e32 v28, 3, v49
	v_sub_u32_e32 v16, v16, v32
	v_add_u32_e32 v26, s7, v48
	v_ashrrev_i32_e32 v29, 31, v28
	v_lshlrev_b32_e32 v32, 3, v16
	v_mad_i64_i32 v[26:27], s[4:5], v26, s8, v[34:35]
	v_lshlrev_b64 v[40:41], 1, v[28:29]
	v_mad_i64_i32 v[30:31], s[4:5], v50, s14, v[30:31]
	v_ashrrev_i32_e32 v33, 31, v32
	v_lshl_add_u64 v[26:27], v[26:27], 0, v[40:41]
	v_lshl_add_u64 v[42:43], v[32:33], 1, v[30:31]
	global_load_dwordx4 v[26:29], v[26:27], off
	v_mul_lo_u32 v51, v44, s15
	global_load_dwordx4 v[30:33], v[42:43], off
	v_add_u32_e32 v51, 0, v51
	v_lshlrev_b32_e32 v45, 4, v45
	v_add_u32_e32 v104, v51, v45
	v_lshlrev_b32_e32 v106, 4, v47
	v_cmp_eq_u32_e32 vcc, 0, v102
	s_waitcnt vmcnt(16)
	v_lshlrev_b32_e32 v109, 4, v16
	s_bitset1_b32 s7, 7
	v_cndmask_b32_e64 v64, 0, 1.0, vcc
	v_cmp_lt_i32_e32 vcc, v127, v128
	v_readlane_b32 s60, v253, 29
	v_add_u32_e32 v0, 0, v0
	v_readlane_b32 s70, v253, 39
	v_readlane_b32 s71, v253, 40
	v_readlane_b32 s61, v253, 30
	v_readlane_b32 s62, v253, 31
	v_readlane_b32 s63, v253, 32
	v_readlane_b32 s64, v253, 33
	v_readlane_b32 s65, v253, 34
	global_load_dword v17, v17, s[70:71]
	v_readlane_b32 s66, v253, 35
	v_readlane_b32 s67, v253, 36
	v_readlane_b32 s68, v253, 37
	v_readlane_b32 s69, v253, 38
	v_readlane_b32 s72, v253, 41
	v_readlane_b32 s73, v253, 42
	v_readlane_b32 s74, v253, 43
	v_readlane_b32 s75, v253, 44
	s_waitcnt vmcnt(4)
	ds_write_b128 v104, v[18:21]
	v_mul_lo_u32 v18, v46, s16
	v_add_u32_e32 v105, 0, v18
	v_add3_u32 v18, v105, v106, s17
	v_lshlrev_b32_e32 v19, 4, v49
	s_waitcnt vmcnt(3)
	ds_write2_b64 v18, v[22:23], v[24:25] offset1:1
	v_mul_lo_u32 v18, v48, s15
	v_add_u32_e32 v18, 0, v18
	v_add_u32_e32 v107, v18, v19
	v_mul_lo_u32 v18, v50, s16
	v_add_u32_e32 v108, 0, v18
	v_add3_u32 v16, v108, v109, s17
	s_waitcnt vmcnt(2)
	ds_write_b128 v107, v[26:29]
	s_waitcnt vmcnt(1)
	ds_write2_b64 v16, v[30:31], v[32:33] offset1:1
	v_cndmask_b32_e32 v16, v126, v127, vcc
	v_lshlrev_b32_e32 v103, 2, v16
	v_add_u32_e32 v16, s7, v48
	v_mad_i64_i32 v[18:19], s[4:5], v16, s8, v[34:35]
	v_add_u32_e32 v16, s7, v44
	v_mad_i64_i32 v[20:21], s[4:5], v16, s8, v[34:35]
	v_lshl_add_u64 v[18:19], v[18:19], 0, v[40:41]
	v_lshl_add_u64 v[20:21], v[20:21], 0, v[36:37]
	v_mad_u32_u24 v16, v15, s15, v0
	s_waitcnt lgkmcnt(0)
	s_barrier
; #define LAS __attribute__((address_space(3)))
; template <int D, int MODE, int NSUB>
; DI void attn_item(const bf16* QKV, int pitch, int qcol0, int kcol0, const bf16* VT, bf16* O, int ocol0, const float* sink,
;                   LAS unsigned char* lds, int item, int tid_in, int lane_in, int wave) {
;     ...
;         for (int sub = 0; sub < NSUB; ++sub) {
;         f32x16 s[2];
; #pragma unroll
;         for (int q = 0; q < 2; ++q) { s[q] = zero16(); const LAS bf16* kp = Kt + (64 * sub + 32 * q + r) * KP + 8 * h;
; #pragma unroll
;             for (int ks = 0; ks < NKS; ++ks) s[q] = MFMA32(*(const LAS bf16x8*)(kp + 16 * ks), qf[ks], s[q]); }
;         if (MODE == 1 && KT * t >= CTXL) { const int kp0 = wstart + KT * t + 64 * sub - CTXL - qpos;
; #pragma unroll
;             for (int q = 0; q < 2; ++q)
; #pragma unroll
;                 for (int i = 0; i < 16; ++i) { const int d0 = kp0 + 32 * q + crow(i, h); if (d0 > 128 || d0 < -128) s[q][i] = -INFINITY; } }
;         float mx = s[0][0];
; #pragma unroll
;         for (int q = 0; q < 2; ++q)
; #pragma unroll
;             for (int i = 0; i < 16; ++i) mx = fmaxf(mx, s[q][i]);
;         mx = fmaxf(mx, __shfl_xor(mx, 32)) * scl;
;         if (!__all(mx - mrun <= THR2)) {
;             const float mnew = fmaxf(mrun, mx), alpha = __builtin_amdgcn_exp2f(mrun - mnew);
;             lrun *= alpha; mrun = mnew;
; #pragma unroll
;             for (int dt = 0; dt < NDT; ++dt)
; #pragma unroll
;                 for (int i = 0; i < 16; ++i) o[dt][i] *= alpha;
;         }
;         float ls = 0.f; const float nm = -mrun;
; #pragma unroll
;         for (int q = 0; q < 2; ++q)
; #pragma unroll
;             for (int i = 0; i < 16; ++i) { s[q][i] = __builtin_amdgcn_exp2f(fmaf(s[q][i], scl, nm)); ls += s[q][i]; }
;         lrun += ls;
; #pragma unroll
;         for (int q = 0; q < 2; ++q)
; #pragma unroll
;             for (int s2 = 0; s2 < 2; ++s2) {
;                 u32x4 pw; pw.x = cvtpk(s[q][8 * s2], s[q][8 * s2 + 1]); pw.y = cvtpk(s[q][8 * s2 + 2], s[q][8 * s2 + 3]); pw.z = cvtpk(s[q][8 * s2 + 4], s[q][8 * s2 + 5]); pw.w = cvtpk(s[q][8 * s2 + 6], s[q][8 * s2 + 7]);
;                 const bf16x8 pb = __builtin_bit_cast(bf16x8, pw);
; #pragma unroll
;                 for (int dt = 0; dt < NDT; ++dt) { const LAS bf16* vp = Vt + (32 * dt + r) * VP + 64 * sub + 32 * q + 16 * s2 + 4 * h;
	global_load_dwordx4 v[96:99], v[20:21], off
	global_load_dwordx4 v[88:91], v[38:39], off offset:256
	global_load_dwordx4 v[92:95], v[18:19], off
	global_load_dwordx4 v[84:87], v[42:43], off offset:256
	ds_read_b128 v[172:175], v16
	ds_read_b128 v[176:179], v16 offset:32
	s_waitcnt lgkmcnt(1)
	v_mfma_f32_32x32x16_bf16 v[48:63], v[172:175], v[80:83], 0
	ds_read_b128 v[180:183], v16 offset:64
	s_waitcnt lgkmcnt(1)
	v_mfma_f32_32x32x16_bf16 v[48:63], v[176:179], v[10:13], v[48:63]
	s_waitcnt lgkmcnt(0)
	v_mfma_f32_32x32x16_bf16 v[48:63], v[180:183], v[6:9], v[48:63]
	ds_read_b128 v[184:187], v16 offset:96
	s_waitcnt lgkmcnt(0)
	v_mfma_f32_32x32x16_bf16 v[48:63], v[184:187], v[2:5], v[48:63]
	ds_read_b128 v[192:195], v16 offset:4608
	s_waitcnt lgkmcnt(0)
	v_mfma_f32_32x32x16_bf16 v[32:47], v[192:195], v[80:83], 0
	ds_read_b128 v[196:199], v16 offset:4640
	s_waitcnt lgkmcnt(0)
	v_mfma_f32_32x32x16_bf16 v[32:47], v[196:199], v[10:13], v[32:47]
	ds_read_b128 v[200:203], v16 offset:4672
	s_waitcnt lgkmcnt(0)
	v_mfma_f32_32x32x16_bf16 v[32:47], v[200:203], v[6:9], v[32:47]
	ds_read_b128 v[204:207], v16 offset:4704
	s_nop 1
	v_max_f32_e32 v16, v49, v49
	s_waitcnt lgkmcnt(0)
	v_mfma_f32_32x32x16_bf16 v[32:47], v[204:207], v[2:5], v[32:47]
	v_max_f32_e32 v18, v48, v48
	v_max_f32_e32 v16, v18, v16
	v_max3_f32 v16, v16, v50, v51
	v_max3_f32 v16, v16, v52, v53
	v_max3_f32 v16, v16, v54, v55
	v_max3_f32 v16, v16, v56, v57
	v_max3_f32 v16, v16, v58, v59
	v_max3_f32 v16, v16, v60, v61
	v_max3_f32 v16, v16, v62, v63
	s_nop 2
	v_max3_f32 v16, v16, v32, v33
	v_max3_f32 v16, v16, v34, v35
	v_max3_f32 v16, v16, v36, v37
	v_max3_f32 v16, v16, v38, v39
	v_max3_f32 v16, v16, v40, v41
	v_max3_f32 v16, v16, v42, v43
	v_max3_f32 v16, v16, v44, v45
	v_max3_f32 v16, v16, v46, v47
	ds_bpermute_b32 v18, v103, v16
	s_waitcnt lgkmcnt(0)
	v_max_f32_e32 v18, v18, v18
	v_max_f32_e32 v16, v16, v18
	s_waitcnt vmcnt(4)
	v_pk_mul_f32 v[100:101], v[16:17], s[20:21]
	s_nop 0
	v_sub_f32_e32 v16, v100, v101
	v_cmp_ge_f32_e32 vcc, s38, v16
	v_mov_b32_e32 v16, 0
	s_cmp_eq_u64 vcc, exec
	s_cbranch_scc1 .LBB0_493
	v_max_f32_e32 v16, v101, v101
	v_max_f32_e32 v17, v100, v100
	v_max_f32_e32 v17, v16, v17
	v_sub_f32_e32 v16, v101, v17
	v_exp_f32_e32 v18, v16
	v_mov_b32_e32 v101, v17
	v_mul_f32_e32 v16, 0, v18
	v_mul_f32_e32 v64, v64, v18
.LBB0_493:
	v_fma_f32 v48, v48, s20, -v101
	v_exp_f32_e32 v48, v48
	v_fma_f32 v49, v49, s20, -v101
	v_exp_f32_e32 v49, v49
	v_fma_f32 v50, v50, s20, -v101
	v_exp_f32_e32 v50, v50
	v_fma_f32 v51, v51, s20, -v101
	v_exp_f32_e32 v51, v51
	v_fma_f32 v52, v52, s20, -v101
	v_add_f32_e32 v67, 0, v48
	v_exp_f32_e32 v52, v52
	v_fma_f32 v53, v53, s20, -v101
	v_add_f32_e32 v67, v49, v67
	v_exp_f32_e32 v53, v53
	v_fma_f32 v54, v54, s20, -v101
	v_add_f32_e32 v67, v50, v67
	v_exp_f32_e32 v54, v54
	v_fma_f32 v55, v55, s20, -v101
	v_add_f32_e32 v67, v51, v67
	v_exp_f32_e32 v55, v55
	v_fma_f32 v56, v56, s20, -v101
	v_add_f32_e32 v67, v52, v67
	v_exp_f32_e32 v68, v56
	v_add_f32_e32 v67, v53, v67
	v_add_f32_e32 v67, v54, v67
	v_fma_f32 v32, v32, s20, -v101
	v_add_f32_e32 v67, v55, v67
	v_fma_f32 v57, v57, s20, -v101
	v_exp_f32_e32 v72, v32
	v_fma_f32 v32, v33, s20, -v101
	v_add_f32_e32 v56, v68, v67
	v_exp_f32_e32 v67, v57
	v_fma_f32 v57, v58, s20, -v101
	v_exp_f32_e32 v73, v32
	v_fma_f32 v32, v34, s20, -v101
	v_exp_f32_e32 v69, v57
	v_fma_f32 v57, v59, s20, -v101
	v_exp_f32_e32 v74, v32
	v_fma_f32 v32, v35, s20, -v101
	v_exp_f32_e32 v70, v57
	v_fma_f32 v57, v60, s20, -v101
	v_exp_f32_e32 v75, v32
	v_fma_f32 v32, v36, s20, -v101
	v_exp_f32_e32 v60, v57
	v_fma_f32 v57, v61, s20, -v101
	v_exp_f32_e32 v76, v32
	v_fma_f32 v32, v37, s20, -v101
	v_add_f32_e32 v56, v67, v56
	v_exp_f32_e32 v61, v57
	v_fma_f32 v57, v62, s20, -v101
	v_exp_f32_e32 v77, v32
	v_fma_f32 v32, v38, s20, -v101
	v_add_f32_e32 v56, v69, v56
	v_exp_f32_e32 v62, v57
	v_fma_f32 v57, v63, s20, -v101
	v_exp_f32_e32 v78, v32
	v_fma_f32 v32, v39, s20, -v101
	v_lshlrev_b32_e32 v17, 3, v102
	v_add_f32_e32 v56, v70, v56
	v_exp_f32_e32 v63, v57
	v_exp_f32_e32 v79, v32
	v_fma_f32 v32, v40, s20, -v101
	v_sub_u32_e32 v66, v0, v17
	v_add_f32_e32 v56, v60, v56
	v_exp_f32_e32 v111, v32
	v_fma_f32 v32, v41, s20, -v101
	v_mul_u32_u24_e32 v65, 0x90, v15
	v_add_f32_e32 v56, v61, v56
	v_exp_f32_e32 v112, v32
	v_fma_f32 v32, v42, s20, -v101
	v_mad_u32_u24 v15, v15, s16, v66
	v_add_f32_e32 v56, v62, v56
	v_exp_f32_e32 v113, v32
	v_fma_f32 v32, v43, s20, -v101
	v_add_u32_e32 v100, 0x4800, v15
	v_add_f32_e32 v71, v63, v56
	v_exp_f32_e32 v114, v32
	v_fma_f32 v32, v44, s20, -v101
	v_cvt_pk_bf16_f32 v48, v48, v49
	v_cvt_pk_bf16_f32 v49, v50, v51
	v_cvt_pk_bf16_f32 v50, v52, v53
	v_cvt_pk_bf16_f32 v51, v54, v55
	ds_read2_b64 v[172:175], v100 offset1:2
	ds_read2_b64 v[176:179], v100 offset0:4 offset1:6
	v_exp_f32_e32 v115, v32
	v_fma_f32 v32, v45, s20, -v101
	v_exp_f32_e32 v116, v32
	v_fma_f32 v32, v46, s20, -v101
	v_mov_b32_e32 v17, v16
	v_mov_b32_e32 v18, v16
	v_mov_b32_e32 v19, v16
	v_mov_b32_e32 v20, v16
	v_mov_b32_e32 v21, v16
	v_mov_b32_e32 v22, v16
	v_mov_b32_e32 v23, v16
	v_mov_b32_e32 v24, v16
	v_mov_b32_e32 v25, v16
	v_mov_b32_e32 v26, v16
	v_mov_b32_e32 v27, v16
	v_mov_b32_e32 v28, v16
	v_mov_b32_e32 v29, v16
	v_mov_b32_e32 v30, v16
	v_mov_b32_e32 v31, v16
	v_exp_f32_e32 v117, v32
	v_fma_f32 v32, v47, s20, -v101
	v_add_u32_e32 v110, 0x6800, v15
	ds_read2_b64 v[180:183], v110 offset0:32 offset1:34
	ds_read2_b64 v[184:187], v110 offset0:36 offset1:38
	ds_read2_b64 v[192:195], v100 offset0:8 offset1:10
	ds_read2_b64 v[196:199], v110 offset0:40 offset1:42
	v_exp_f32_e32 v118, v32
	s_waitcnt lgkmcnt(5)
; #define LAS __attribute__((address_space(3)))
; template <int D, int MODE, int NSUB>
; DI void attn_item(const bf16* QKV, int pitch, int qcol0, int kcol0, const bf16* VT, bf16* O, int ocol0, const float* sink,
;                   LAS unsigned char* lds, int item, int tid_in, int lane_in, int wave) {
;     ...
;         for (int sub = 0; sub < NSUB; ++sub) {
;         f32x16 s[2];
; #pragma unroll
;         for (int q = 0; q < 2; ++q) { s[q] = zero16(); const LAS bf16* kp = Kt + (64 * sub + 32 * q + r) * KP + 8 * h;
; #pragma unroll
;             for (int ks = 0; ks < NKS; ++ks) s[q] = MFMA32(*(const LAS bf16x8*)(kp + 16 * ks), qf[ks], s[q]); }
;         if (MODE == 1 && KT * t >= CTXL) { const int kp0 = wstart + KT * t + 64 * sub - CTXL - qpos;
; #pragma unroll
;             for (int q = 0; q < 2; ++q)
; #pragma unroll
;                 for (int i = 0; i < 16; ++i) { const int d0 = kp0 + 32 * q + crow(i, h); if (d0 > 128 || d0 < -128) s[q][i] = -INFINITY; } }
;         float mx = s[0][0];
; #pragma unroll
;         for (int q = 0; q < 2; ++q)
; #pragma unroll
;             for (int i = 0; i < 16; ++i) mx = fmaxf(mx, s[q][i]);
;         mx = fmaxf(mx, __shfl_xor(mx, 32)) * scl;
;         if (!__all(mx - mrun <= THR2)) {
;             const float mnew = fmaxf(mrun, mx), alpha = __builtin_amdgcn_exp2f(mrun - mnew);
;             lrun *= alpha; mrun = mnew;
; #pragma unroll
;             for (int dt = 0; dt < NDT; ++dt)
; #pragma unroll
;                 for (int i = 0; i < 16; ++i) o[dt][i] *= alpha;
;         }
;         float ls = 0.f; const float nm = -mrun;
; #pragma unroll
;         for (int q = 0; q < 2; ++q)
; #pragma unroll
;             for (int i = 0; i < 16; ++i) { s[q][i] = __builtin_amdgcn_exp2f(fmaf(s[q][i], scl, nm)); ls += s[q][i]; }
;         lrun += ls;
; #pragma unroll
;         for (int q = 0; q < 2; ++q)
; #pragma unroll
;             for (int s2 = 0; s2 < 2; ++s2) {
;                 u32x4 pw; pw.x = cvtpk(s[q][8 * s2], s[q][8 * s2 + 1]); pw.y = cvtpk(s[q][8 * s2 + 2], s[q][8 * s2 + 3]); pw.z = cvtpk(s[q][8 * s2 + 4], s[q][8 * s2 + 5]); pw.w = cvtpk(s[q][8 * s2 + 6], s[q][8 * s2 + 7]);
;                 const bf16x8 pb = __builtin_bit_cast(bf16x8, pw);
; #pragma unroll
;                 for (int dt = 0; dt < NDT; ++dt) { const LAS bf16* vp = Vt + (32 * dt + r) * VP + 64 * sub + 32 * q + 16 * s2 + 4 * h;
	v_mfma_f32_32x32x16_bf16 v[32:47], v[172:175], v[48:51], v[16:31]
	ds_read2_b64 v[200:203], v100 offset0:12 offset1:14
	v_add_u32_e32 v0, v0, v65
	s_mov_b32 s75, s33
	v_readlane_b32 s54, v254, 26
	v_readlane_b32 s55, v254, 25
	s_waitcnt lgkmcnt(4)
	v_mfma_f32_32x32x16_bf16 v[16:31], v[180:183], v[48:51], v[16:31]
	ds_read2_b64 v[204:207], v110 offset0:44 offset1:46
	v_cvt_pk_bf16_f32 v48, v68, v67
	v_cvt_pk_bf16_f32 v49, v69, v70
	v_cvt_pk_bf16_f32 v50, v60, v61
	v_cvt_pk_bf16_f32 v51, v62, v63
	s_nop 0
	s_waitcnt lgkmcnt(4)
	v_mfma_f32_32x32x16_bf16 v[16:31], v[184:187], v[48:51], v[16:31]
	s_waitcnt lgkmcnt(6)
	v_mfma_f32_32x32x16_bf16 v[32:47], v[176:179], v[48:51], v[32:47]
	v_cvt_pk_bf16_f32 v48, v72, v73
	v_cvt_pk_bf16_f32 v49, v74, v75
	v_cvt_pk_bf16_f32 v50, v76, v77
	v_cvt_pk_bf16_f32 v51, v78, v79
	s_nop 0
	s_waitcnt lgkmcnt(3)
	v_mfma_f32_32x32x16_bf16 v[32:47], v[192:195], v[48:51], v[32:47]
	s_waitcnt lgkmcnt(2)
	v_mfma_f32_32x32x16_bf16 v[16:31], v[196:199], v[48:51], v[16:31]
	v_cvt_pk_bf16_f32 v48, v111, v112
	v_cvt_pk_bf16_f32 v49, v113, v114
	v_cvt_pk_bf16_f32 v50, v115, v116
	v_cvt_pk_bf16_f32 v51, v117, v118
	s_nop 0
	s_waitcnt lgkmcnt(1)
	v_mfma_f32_32x32x16_bf16 v[32:47], v[200:203], v[48:51], v[32:47]
	s_waitcnt lgkmcnt(0)
	v_mfma_f32_32x32x16_bf16 v[16:31], v[204:207], v[48:51], v[16:31]
	v_add_f32_e32 v48, v72, v71
	v_add_f32_e32 v48, v73, v48
	v_add_f32_e32 v48, v74, v48
	v_add_f32_e32 v48, v75, v48
	v_add_f32_e32 v48, v76, v48
	v_add_f32_e32 v48, v77, v48
	v_add_f32_e32 v48, v78, v48
	v_add_f32_e32 v48, v79, v48
	v_add_f32_e32 v48, v111, v48
	v_add_f32_e32 v48, v112, v48
	v_add_f32_e32 v48, v113, v48
	v_add_f32_e32 v48, v114, v48
	v_add_f32_e32 v48, v115, v48
	v_add_f32_e32 v48, v116, v48
	v_add_f32_e32 v48, v117, v48
	v_add_f32_e32 v48, v118, v48
	v_add_f32_e32 v111, v64, v48
	ds_read_b128 v[172:175], v0 offset:9216
	ds_read_b128 v[176:179], v0 offset:9248
	ds_read_b128 v[180:183], v0 offset:9280
	ds_read_b128 v[184:187], v0 offset:13856
	ds_read_b128 v[192:195], v0 offset:9312
	ds_read_b128 v[196:199], v0 offset:13824
	s_waitcnt lgkmcnt(5)
	v_mfma_f32_32x32x16_bf16 v[64:79], v[172:175], v[80:83], 0
	ds_read_b128 v[200:203], v0 offset:13888
	s_waitcnt lgkmcnt(5)
	v_mfma_f32_32x32x16_bf16 v[64:79], v[176:179], v[10:13], v[64:79]
	ds_read_b128 v[204:207], v0 offset:13920
	s_waitcnt lgkmcnt(5)
	v_mfma_f32_32x32x16_bf16 v[64:79], v[180:183], v[6:9], v[64:79]
	s_waitcnt lgkmcnt(3)
	v_mfma_f32_32x32x16_bf16 v[64:79], v[192:195], v[2:5], v[64:79]
	s_waitcnt lgkmcnt(2)
	v_mfma_f32_32x32x16_bf16 v[48:63], v[196:199], v[80:83], 0
	s_waitcnt lgkmcnt(4)
	v_mfma_f32_32x32x16_bf16 v[48:63], v[184:187], v[10:13], v[48:63]
	s_waitcnt lgkmcnt(1)
	v_mfma_f32_32x32x16_bf16 v[48:63], v[200:203], v[6:9], v[48:63]
	s_waitcnt lgkmcnt(0)
	v_mfma_f32_32x32x16_bf16 v[48:63], v[204:207], v[2:5], v[48:63]
	s_nop 1
	v_max_f32_e32 v112, v65, v65
	v_max_f32_e32 v113, v64, v64
	v_max_f32_e32 v112, v113, v112
	v_max3_f32 v112, v112, v66, v67
	v_max3_f32 v112, v112, v68, v69
	v_max3_f32 v112, v112, v70, v71
	v_max3_f32 v112, v112, v72, v73
	v_max3_f32 v112, v112, v74, v75
	v_max3_f32 v112, v112, v76, v77
	v_max3_f32 v112, v112, v78, v79
	v_max3_f32 v112, v112, v48, v49
	v_max3_f32 v112, v112, v50, v51
	v_max3_f32 v112, v112, v52, v53
	v_max3_f32 v112, v112, v54, v55
	v_max3_f32 v112, v112, v56, v57
	v_max3_f32 v112, v112, v58, v59
	v_max3_f32 v112, v112, v60, v61
	v_max3_f32 v112, v112, v62, v63
	ds_bpermute_b32 v113, v103, v112
	s_waitcnt lgkmcnt(0)
	v_max_f32_e32 v113, v113, v113
	v_max_f32_e32 v112, v112, v113
	v_fma_f32 v113, v112, s20, -v101
	v_cmp_ge_f32_e32 vcc, s38, v113
	s_cmp_eq_u64 vcc, exec
	s_cbranch_scc1 .LBB0_495
	v_mul_f32_e32 v112, 0x3e38aa3b, v112
	v_max_f32_e32 v112, v112, v112
	v_max_f32_e32 v113, v101, v101
	v_max_f32_e32 v113, v113, v112
	v_sub_f32_e32 v101, v101, v113
	v_exp_f32_e32 v112, v101
	v_mov_b32_e32 v101, v113
	v_pk_mul_f32 v[46:47], v[46:47], v[112:113] op_sel_hi:[1,0]
	v_pk_mul_f32 v[44:45], v[44:45], v[112:113] op_sel_hi:[1,0]
	v_pk_mul_f32 v[42:43], v[42:43], v[112:113] op_sel_hi:[1,0]
	v_pk_mul_f32 v[40:41], v[40:41], v[112:113] op_sel_hi:[1,0]
	v_pk_mul_f32 v[38:39], v[38:39], v[112:113] op_sel_hi:[1,0]
	v_pk_mul_f32 v[36:37], v[36:37], v[112:113] op_sel_hi:[1,0]
	v_pk_mul_f32 v[34:35], v[34:35], v[112:113] op_sel_hi:[1,0]
	v_pk_mul_f32 v[32:33], v[32:33], v[112:113] op_sel_hi:[1,0]
	v_pk_mul_f32 v[30:31], v[30:31], v[112:113] op_sel_hi:[1,0]
	v_pk_mul_f32 v[28:29], v[28:29], v[112:113] op_sel_hi:[1,0]
	v_pk_mul_f32 v[26:27], v[26:27], v[112:113] op_sel_hi:[1,0]
	v_pk_mul_f32 v[24:25], v[24:25], v[112:113] op_sel_hi:[1,0]
	v_pk_mul_f32 v[22:23], v[22:23], v[112:113] op_sel_hi:[1,0]
	v_pk_mul_f32 v[20:21], v[20:21], v[112:113] op_sel_hi:[1,0]
	v_pk_mul_f32 v[18:19], v[18:19], v[112:113] op_sel_hi:[1,0]
	v_pk_mul_f32 v[16:17], v[16:17], v[112:113] op_sel_hi:[1,0]
	v_mul_f32_e32 v111, v111, v112
	v_xor_b32_e32 v112, 0x80000000, v113
	s_branch .LBB0_496

; #define LAS __attribute__((address_space(3)))
; #define MFMA32(a, b, c) __builtin_amdgcn_mfma_f32_32x32x16_bf16((a), (b), (c), 0, 0, 0)
; DI unsigned cvtpk(float lo, float hi) { f32x2 v = {lo, hi}; bf16x2_t b = __builtin_convertvector(v, bf16x2_t); return __builtin_bit_cast(unsigned, b); }
; template <int D, int MODE, int NSUB>
; DI void attn_item(const bf16* QKV, int pitch, int qcol0, int kcol0, const bf16* VT, bf16* O, int ocol0, const float* sink,
;                   LAS unsigned char* lds, int item, int tid_in, int lane_in, int wave) {
;     ...
;         float ls = 0.f; const float nm = -mrun;
; #pragma unroll
;         for (int q = 0; q < 2; ++q)
; #pragma unroll
;             for (int i = 0; i < 16; ++i) { s[q][i] = __builtin_amdgcn_exp2f(fmaf(s[q][i], scl, nm)); ls += s[q][i]; }
;         lrun += ls;
; #pragma unroll
;         for (int q = 0; q < 2; ++q)
; #pragma unroll
;             for (int s2 = 0; s2 < 2; ++s2) {
;                 u32x4 pw; pw.x = cvtpk(s[q][8 * s2], s[q][8 * s2 + 1]); pw.y = cvtpk(s[q][8 * s2 + 2], s[q][8 * s2 + 3]); pw.z = cvtpk(s[q][8 * s2 + 4], s[q][8 * s2 + 5]); pw.w = cvtpk(s[q][8 * s2 + 6], s[q][8 * s2 + 7]);
;                 const bf16x8 pb = __builtin_bit_cast(bf16x8, pw);
; #pragma unroll
;                 for (int dt = 0; dt < NDT; ++dt) { const LAS bf16* vp = Vt + (32 * dt + r) * VP + 64 * sub + 32 * q + 16 * s2 + 4 * h;
;                     const s16x4 lo = *(const LAS s16x4*)vp, hi = *(const LAS s16x4*)(vp + 8);
;                     const bf16x8 a = __builtin_shufflevector(lo, hi, 0, 1, 2, 3, 4, 5, 6, 7);
;                     o[dt] = MFMA32(a, pb, o[dt]); }
;             }
;         }
;         if (t + 1 < nt) ATT_STORE((t + 1) & 1);
;         __syncthreads();
.LBB0_496:
	v_fmamk_f32 v48, v48, 0x3e38aa3b, v112
	v_exp_f32_e32 v114, v48
	v_fmamk_f32 v48, v49, 0x3e38aa3b, v112
	v_exp_f32_e32 v115, v48
	v_fmamk_f32 v48, v50, 0x3e38aa3b, v112
	v_exp_f32_e32 v116, v48
	v_fmamk_f32 v48, v51, 0x3e38aa3b, v112
	v_exp_f32_e32 v117, v48
	v_fmamk_f32 v48, v52, 0x3e38aa3b, v112
	v_exp_f32_e32 v118, v48
	v_fmamk_f32 v48, v53, 0x3e38aa3b, v112
	v_exp_f32_e32 v119, v48
	v_fmamk_f32 v48, v54, 0x3e38aa3b, v112
	v_exp_f32_e32 v120, v48
	v_fmamk_f32 v48, v55, 0x3e38aa3b, v112
	v_exp_f32_e32 v121, v48
	v_fmamk_f32 v48, v56, 0x3e38aa3b, v112
	v_exp_f32_e32 v122, v48
	v_fmamk_f32 v48, v57, 0x3e38aa3b, v112
	v_fmamk_f32 v64, v64, 0x3e38aa3b, v112
	v_fmamk_f32 v65, v65, 0x3e38aa3b, v112
	v_fmamk_f32 v66, v66, 0x3e38aa3b, v112
	v_fmamk_f32 v67, v67, 0x3e38aa3b, v112
	v_fmamk_f32 v68, v68, 0x3e38aa3b, v112
	v_fmamk_f32 v69, v69, 0x3e38aa3b, v112
	v_fmamk_f32 v70, v70, 0x3e38aa3b, v112
	v_fmamk_f32 v71, v71, 0x3e38aa3b, v112
	v_exp_f32_e32 v123, v48
	v_fmamk_f32 v48, v58, 0x3e38aa3b, v112
	v_exp_f32_e32 v64, v64
	v_exp_f32_e32 v65, v65
	v_exp_f32_e32 v66, v66
	v_exp_f32_e32 v67, v67
	v_exp_f32_e32 v68, v68
	v_exp_f32_e32 v69, v69
	v_exp_f32_e32 v70, v70
	v_exp_f32_e32 v71, v71
	v_exp_f32_e32 v124, v48
	v_fmamk_f32 v48, v59, 0x3e38aa3b, v112
	v_exp_f32_e32 v125, v48
	v_fmamk_f32 v48, v60, 0x3e38aa3b, v112
	ds_read2_b64 v[172:175], v100 offset0:16 offset1:18
	ds_read2_b64 v[176:179], v100 offset0:20 offset1:22
	ds_read2_b64 v[180:183], v110 offset0:48 offset1:50
	ds_read2_b64 v[184:187], v110 offset0:52 offset1:54
	ds_read2_b64 v[192:195], v100 offset0:24 offset1:26
	ds_read2_b64 v[196:199], v110 offset0:56 offset1:58
	v_exp_f32_e32 v60, v48
	v_fmamk_f32 v48, v61, 0x3e38aa3b, v112
	v_exp_f32_e32 v61, v48
	v_fmamk_f32 v48, v62, 0x3e38aa3b, v112
	v_exp_f32_e32 v62, v48
	v_cvt_pk_bf16_f32 v48, v64, v65
	v_cvt_pk_bf16_f32 v49, v66, v67
	v_cvt_pk_bf16_f32 v50, v68, v69
	v_cvt_pk_bf16_f32 v51, v70, v71
	v_fmamk_f32 v72, v72, 0x3e38aa3b, v112
	v_fmamk_f32 v73, v73, 0x3e38aa3b, v112
	s_waitcnt lgkmcnt(5)
	v_mfma_f32_32x32x16_bf16 v[32:47], v[172:175], v[48:51], v[32:47]
	ds_read2_b64 v[200:203], v100 offset0:28 offset1:30
	v_fmamk_f32 v74, v74, 0x3e38aa3b, v112
	v_fmamk_f32 v75, v75, 0x3e38aa3b, v112
	v_fmamk_f32 v76, v76, 0x3e38aa3b, v112
	v_fmamk_f32 v77, v77, 0x3e38aa3b, v112
	v_fmamk_f32 v78, v78, 0x3e38aa3b, v112
	v_fmamk_f32 v79, v79, 0x3e38aa3b, v112
	s_waitcnt lgkmcnt(4)
	v_mfma_f32_32x32x16_bf16 v[16:31], v[180:183], v[48:51], v[16:31]
	v_exp_f32_e32 v72, v72
	v_exp_f32_e32 v73, v73
	v_exp_f32_e32 v74, v74
	v_exp_f32_e32 v75, v75
	v_exp_f32_e32 v76, v76
	v_exp_f32_e32 v77, v77
	v_exp_f32_e32 v78, v78
	v_exp_f32_e32 v79, v79
	v_cvt_pk_bf16_f32 v48, v72, v73
	v_cvt_pk_bf16_f32 v49, v74, v75
	v_cvt_pk_bf16_f32 v50, v76, v77
	v_cvt_pk_bf16_f32 v51, v78, v79
	v_add_f32_e32 v113, 0, v64
	v_add_f32_e32 v113, v65, v113
	s_waitcnt lgkmcnt(3)
	v_mfma_f32_32x32x16_bf16 v[16:31], v[184:187], v[48:51], v[16:31]
	v_fmac_f32_e32 v112, 0x3e38aa3b, v63
	v_add_f32_e32 v113, v66, v113
	v_exp_f32_e32 v63, v112
	v_add_f32_e32 v113, v67, v113
	v_add_f32_e32 v113, v68, v113
	v_add_f32_e32 v113, v69, v113
	s_waitcnt lgkmcnt(5)
	v_mfma_f32_32x32x16_bf16 v[32:47], v[176:179], v[48:51], v[32:47]
	v_cvt_pk_bf16_f32 v48, v114, v115
	v_cvt_pk_bf16_f32 v49, v116, v117
	v_cvt_pk_bf16_f32 v50, v118, v119
	v_cvt_pk_bf16_f32 v51, v120, v121
	v_add_f32_e32 v113, v70, v113
	v_add_f32_e32 v113, v71, v113
	v_add_f32_e32 v113, v72, v113
	s_waitcnt lgkmcnt(2)
	v_mfma_f32_32x32x16_bf16 v[32:47], v[192:195], v[48:51], v[32:47]
	v_add_f32_e32 v113, v73, v113
	v_add_f32_e32 v113, v74, v113
	v_add_f32_e32 v113, v75, v113
	v_add_f32_e32 v113, v76, v113
	v_add_f32_e32 v113, v77, v113
	v_add_f32_e32 v113, v78, v113
	s_waitcnt lgkmcnt(1)
	v_mfma_f32_32x32x16_bf16 v[16:31], v[196:199], v[48:51], v[16:31]
	v_cvt_pk_bf16_f32 v48, v122, v123
	v_cvt_pk_bf16_f32 v49, v124, v125
	v_cvt_pk_bf16_f32 v50, v60, v61
	v_cvt_pk_bf16_f32 v51, v62, v63
	v_add_f32_e32 v113, v79, v113
	s_waitcnt lgkmcnt(0)
	v_mfma_f32_32x32x16_bf16 v[32:47], v[200:203], v[48:51], v[32:47]
	ds_read2_b64 v[52:55], v110 offset0:60 offset1:62
	s_waitcnt vmcnt(3)
	ds_write_b128 v104, v[96:99] offset:35328
	s_waitcnt lgkmcnt(1)
	v_mfma_f32_32x32x16_bf16 v[16:31], v[52:55], v[48:51], v[16:31]
	v_add_f32_e32 v48, v114, v113
	v_add_f32_e32 v48, v115, v48
	v_add_f32_e32 v48, v116, v48
	v_add_f32_e32 v48, v117, v48
	v_add_f32_e32 v48, v118, v48
	v_add_f32_e32 v48, v119, v48
	v_add_f32_e32 v48, v120, v48
	v_add_f32_e32 v48, v121, v48
	v_add_f32_e32 v48, v122, v48
	v_add_f32_e32 v48, v123, v48
	v_add_f32_e32 v48, v124, v48
	v_add_f32_e32 v48, v125, v48
	v_add_f32_e32 v48, v60, v48
	v_add_f32_e32 v48, v61, v48
	v_add_f32_e32 v48, v62, v48
	v_add_f32_e32 v48, v63, v48
	v_add_f32_e32 v100, v111, v48
	v_add3_u32 v48, v105, v106, s39
	s_waitcnt vmcnt(2)
	ds_write2_b64 v48, v[88:89], v[90:91] offset1:1
	s_waitcnt vmcnt(1)
	ds_write_b128 v107, v[92:95] offset:35328
	v_add3_u32 v48, v108, v109, s39
	s_waitcnt vmcnt(0)
	ds_write2_b64 v48, v[84:85], v[86:87] offset1:1
	s_waitcnt lgkmcnt(0)
	s_barrier
; #define LAS __attribute__((address_space(3)))
; template <int D, int MODE, int NSUB>
; DI void attn_item(const bf16* QKV, int pitch, int qcol0, int kcol0, const bf16* VT, bf16* O, int ocol0, const float* sink,
;                   LAS unsigned char* lds, int item, int tid_in, int lane_in, int wave) {
;     ...
;         for (int sub = 0; sub < NSUB; ++sub) {
;         f32x16 s[2];
; #pragma unroll
;         for (int q = 0; q < 2; ++q) { s[q] = zero16(); const LAS bf16* kp = Kt + (64 * sub + 32 * q + r) * KP + 8 * h;
; #pragma unroll
;             for (int ks = 0; ks < NKS; ++ks) s[q] = MFMA32(*(const LAS bf16x8*)(kp + 16 * ks), qf[ks], s[q]); }
;         if (MODE == 1 && KT * t >= CTXL) { const int kp0 = wstart + KT * t + 64 * sub - CTXL - qpos;
; #pragma unroll
;             for (int q = 0; q < 2; ++q)
; #pragma unroll
;                 for (int i = 0; i < 16; ++i) { const int d0 = kp0 + 32 * q + crow(i, h); if (d0 > 128 || d0 < -128) s[q][i] = -INFINITY; } }
;         float mx = s[0][0];
; #pragma unroll
;         for (int q = 0; q < 2; ++q)
; #pragma unroll
;             for (int i = 0; i < 16; ++i) mx = fmaxf(mx, s[q][i]);
;         mx = fmaxf(mx, __shfl_xor(mx, 32)) * scl;
;         if (!__all(mx - mrun <= THR2)) {
;             const float mnew = fmaxf(mrun, mx), alpha = __builtin_amdgcn_exp2f(mrun - mnew);
;             lrun *= alpha; mrun = mnew;
; #pragma unroll
;             for (int dt = 0; dt < NDT; ++dt)
; #pragma unroll
;                 for (int i = 0; i < 16; ++i) o[dt][i] *= alpha;
;         }
;         float ls = 0.f; const float nm = -mrun;
; #pragma unroll
;         for (int q = 0; q < 2; ++q)
; #pragma unroll
;             for (int i = 0; i < 16; ++i) { s[q][i] = __builtin_amdgcn_exp2f(fmaf(s[q][i], scl, nm)); ls += s[q][i]; }
;         lrun += ls;
; #pragma unroll
;         for (int q = 0; q < 2; ++q)
; #pragma unroll
;             for (int s2 = 0; s2 < 2; ++s2) {
;                 u32x4 pw; pw.x = cvtpk(s[q][8 * s2], s[q][8 * s2 + 1]); pw.y = cvtpk(s[q][8 * s2 + 2], s[q][8 * s2 + 3]); pw.z = cvtpk(s[q][8 * s2 + 4], s[q][8 * s2 + 5]); pw.w = cvtpk(s[q][8 * s2 + 6], s[q][8 * s2 + 7]);
;                 const bf16x8 pb = __builtin_bit_cast(bf16x8, pw);
; #pragma unroll
;                 for (int dt = 0; dt < NDT; ++dt) { const LAS bf16* vp = Vt + (32 * dt + r) * VP + 64 * sub + 32 * q + 16 * s2 + 4 * h;
	ds_read_b128 v[172:175], v0 offset:35328
	ds_read_b128 v[176:179], v0 offset:35360
	ds_read_b128 v[180:183], v0 offset:35392
	ds_read_b128 v[184:187], v0 offset:39968
	ds_read_b128 v[192:195], v0 offset:35424
	ds_read_b128 v[196:199], v0 offset:39936
	s_waitcnt lgkmcnt(5)
	v_mfma_f32_32x32x16_bf16 v[64:79], v[172:175], v[80:83], 0
	ds_read_b128 v[200:203], v0 offset:40000
	s_waitcnt lgkmcnt(5)
	v_mfma_f32_32x32x16_bf16 v[64:79], v[176:179], v[10:13], v[64:79]
	ds_read_b128 v[204:207], v0 offset:40032
	s_waitcnt lgkmcnt(5)
	v_mfma_f32_32x32x16_bf16 v[64:79], v[180:183], v[6:9], v[64:79]
	s_waitcnt lgkmcnt(3)
	v_mfma_f32_32x32x16_bf16 v[64:79], v[192:195], v[2:5], v[64:79]
	s_waitcnt lgkmcnt(2)
	v_mfma_f32_32x32x16_bf16 v[48:63], v[196:199], v[80:83], 0
	s_waitcnt lgkmcnt(4)
	v_mfma_f32_32x32x16_bf16 v[48:63], v[184:187], v[10:13], v[48:63]
	s_waitcnt lgkmcnt(1)
	v_mfma_f32_32x32x16_bf16 v[48:63], v[200:203], v[6:9], v[48:63]
	s_waitcnt lgkmcnt(0)
	v_mfma_f32_32x32x16_bf16 v[48:63], v[204:207], v[2:5], v[48:63]
	s_nop 1
	v_max_f32_e32 v84, v65, v65
	v_max_f32_e32 v85, v64, v64
	v_max_f32_e32 v84, v85, v84
	v_max3_f32 v84, v84, v66, v67
	v_max3_f32 v84, v84, v68, v69
	v_max3_f32 v84, v84, v70, v71
	v_max3_f32 v84, v84, v72, v73
	v_max3_f32 v84, v84, v74, v75
	v_max3_f32 v84, v84, v76, v77
	v_max3_f32 v84, v84, v78, v79
	v_max3_f32 v84, v84, v48, v49
	v_max3_f32 v84, v84, v50, v51
	v_max3_f32 v84, v84, v52, v53
	v_max3_f32 v84, v84, v54, v55
	v_max3_f32 v84, v84, v56, v57
	v_max3_f32 v84, v84, v58, v59
	v_max3_f32 v84, v84, v60, v61
	v_max3_f32 v84, v84, v62, v63
	ds_bpermute_b32 v85, v103, v84
	s_waitcnt lgkmcnt(0)
	v_max_f32_e32 v85, v85, v85
	v_max_f32_e32 v84, v84, v85
	v_fma_f32 v85, v84, s20, -v101
	v_cmp_ge_f32_e32 vcc, s38, v85
	s_cmp_eq_u64 vcc, exec
	s_cbranch_scc1 .LBB0_498
	v_mul_f32_e32 v84, 0x3e38aa3b, v84
	v_max_f32_e32 v84, v84, v84
	v_max_f32_e32 v85, v101, v101
	v_max_f32_e32 v85, v85, v84
	v_sub_f32_e32 v84, v101, v85
	v_exp_f32_e32 v84, v84
	v_mov_b32_e32 v101, v85
	v_pk_mul_f32 v[46:47], v[46:47], v[84:85] op_sel_hi:[1,0]
	v_pk_mul_f32 v[44:45], v[44:45], v[84:85] op_sel_hi:[1,0]
	v_pk_mul_f32 v[42:43], v[42:43], v[84:85] op_sel_hi:[1,0]
	v_pk_mul_f32 v[40:41], v[40:41], v[84:85] op_sel_hi:[1,0]
	v_pk_mul_f32 v[38:39], v[38:39], v[84:85] op_sel_hi:[1,0]
	v_pk_mul_f32 v[36:37], v[36:37], v[84:85] op_sel_hi:[1,0]
	v_pk_mul_f32 v[34:35], v[34:35], v[84:85] op_sel_hi:[1,0]
	v_pk_mul_f32 v[32:33], v[32:33], v[84:85] op_sel_hi:[1,0]
	v_pk_mul_f32 v[30:31], v[30:31], v[84:85] op_sel_hi:[1,0]
	v_pk_mul_f32 v[28:29], v[28:29], v[84:85] op_sel_hi:[1,0]
	v_pk_mul_f32 v[26:27], v[26:27], v[84:85] op_sel_hi:[1,0]
	v_pk_mul_f32 v[24:25], v[24:25], v[84:85] op_sel_hi:[1,0]
	v_pk_mul_f32 v[22:23], v[22:23], v[84:85] op_sel_hi:[1,0]
	v_pk_mul_f32 v[20:21], v[20:21], v[84:85] op_sel_hi:[1,0]
	v_pk_mul_f32 v[18:19], v[18:19], v[84:85] op_sel_hi:[1,0]
	v_pk_mul_f32 v[16:17], v[16:17], v[84:85] op_sel_hi:[1,0]
	v_mul_f32_e32 v100, v100, v84
.LBB0_498:
	v_fma_f32 v64, v64, s20, -v101
	v_exp_f32_e32 v64, v64
	v_fma_f32 v65, v65, s20, -v101
	v_exp_f32_e32 v65, v65
	v_fma_f32 v66, v66, s20, -v101
	v_exp_f32_e32 v66, v66
	v_fma_f32 v67, v67, s20, -v101
	v_exp_f32_e32 v67, v67
	v_fma_f32 v68, v68, s20, -v101
	v_add_f32_e32 v84, 0, v64
	v_exp_f32_e32 v68, v68
	v_fma_f32 v69, v69, s20, -v101
	v_add_f32_e32 v84, v65, v84
	v_exp_f32_e32 v69, v69
	v_fma_f32 v70, v70, s20, -v101
	v_add_f32_e32 v84, v66, v84
	v_exp_f32_e32 v70, v70
	v_fma_f32 v71, v71, s20, -v101
	v_add_f32_e32 v84, v67, v84
	v_exp_f32_e32 v71, v71
	v_fma_f32 v72, v72, s20, -v101
	v_fma_f32 v48, v48, s20, -v101
	v_add_f32_e32 v84, v68, v84
	v_exp_f32_e32 v72, v72
	v_fma_f32 v73, v73, s20, -v101
	v_exp_f32_e32 v87, v48
	v_fma_f32 v48, v49, s20, -v101
	v_add_f32_e32 v84, v69, v84
	v_exp_f32_e32 v73, v73
	v_fma_f32 v74, v74, s20, -v101
	v_exp_f32_e32 v88, v48
	v_fma_f32 v48, v50, s20, -v101
	v_add_f32_e32 v84, v70, v84
	v_exp_f32_e32 v74, v74
	v_fma_f32 v75, v75, s20, -v101
	v_exp_f32_e32 v89, v48
	v_fma_f32 v48, v51, s20, -v101
	v_add_f32_e32 v84, v71, v84
	v_exp_f32_e32 v75, v75
	v_fma_f32 v76, v76, s20, -v101
	v_exp_f32_e32 v90, v48
	v_fma_f32 v48, v52, s20, -v101
	v_add_f32_e32 v84, v72, v84
	v_exp_f32_e32 v76, v76
	v_fma_f32 v77, v77, s20, -v101
	v_exp_f32_e32 v91, v48
	v_fma_f32 v48, v53, s20, -v101
	v_add_f32_e32 v84, v73, v84
	v_exp_f32_e32 v77, v77
	v_fma_f32 v78, v78, s20, -v101
	v_exp_f32_e32 v92, v48
	v_fma_f32 v48, v54, s20, -v101
	v_add_f32_e32 v84, v74, v84
	v_exp_f32_e32 v78, v78
	v_fma_f32 v79, v79, s20, -v101
	v_exp_f32_e32 v93, v48
	v_fma_f32 v48, v55, s20, -v101
	v_add_f32_e32 v84, v75, v84
	v_exp_f32_e32 v79, v79
	v_exp_f32_e32 v94, v48
	v_fma_f32 v48, v56, s20, -v101
	v_add_f32_e32 v84, v76, v84
	v_exp_f32_e32 v95, v48
	v_fma_f32 v48, v57, s20, -v101
	v_add_f32_e32 v84, v77, v84
	v_exp_f32_e32 v96, v48
	v_fma_f32 v48, v58, s20, -v101
	v_add_f32_e32 v84, v78, v84
	v_exp_f32_e32 v97, v48
	v_fma_f32 v48, v59, s20, -v101
	v_add_f32_e32 v86, v79, v84
	v_exp_f32_e32 v98, v48
	v_fma_f32 v48, v60, s20, -v101
	v_add_u32_e32 v84, 0xd000, v15
	v_exp_f32_e32 v60, v48
	v_fma_f32 v48, v61, s20, -v101
	ds_read2_b64 v[172:175], v84 offset0:64 offset1:66
	ds_read2_b64 v[176:179], v84 offset0:68 offset1:70
	v_exp_f32_e32 v61, v48
	v_fma_f32 v48, v62, s20, -v101
	v_exp_f32_e32 v62, v48
	v_fma_f32 v48, v63, s20, -v101
	v_exp_f32_e32 v63, v48
	v_cvt_pk_bf16_f32 v48, v64, v65
	v_cvt_pk_bf16_f32 v49, v66, v67
	v_cvt_pk_bf16_f32 v50, v68, v69
	v_cvt_pk_bf16_f32 v51, v70, v71
	v_add_u32_e32 v85, 0xf000, v15
	ds_read2_b64 v[180:183], v85 offset0:96 offset1:98
	ds_read2_b64 v[184:187], v85 offset0:100 offset1:102
	ds_read2_b64 v[192:195], v84 offset0:72 offset1:74
	ds_read2_b64 v[196:199], v85 offset0:104 offset1:106
	v_add_f32_e32 v15, v87, v86
	s_waitcnt lgkmcnt(5)
; #define LAS __attribute__((address_space(3)))
; template <int D, int MODE, int NSUB>
; DI void attn_item(const bf16* QKV, int pitch, int qcol0, int kcol0, const bf16* VT, bf16* O, int ocol0, const float* sink,
;                   LAS unsigned char* lds, int item, int tid_in, int lane_in, int wave) {
;     ...
;         for (int sub = 0; sub < NSUB; ++sub) {
;         f32x16 s[2];
; #pragma unroll
;         for (int q = 0; q < 2; ++q) { s[q] = zero16(); const LAS bf16* kp = Kt + (64 * sub + 32 * q + r) * KP + 8 * h;
; #pragma unroll
;             for (int ks = 0; ks < NKS; ++ks) s[q] = MFMA32(*(const LAS bf16x8*)(kp + 16 * ks), qf[ks], s[q]); }
;         if (MODE == 1 && KT * t >= CTXL) { const int kp0 = wstart + KT * t + 64 * sub - CTXL - qpos;
; #pragma unroll
;             for (int q = 0; q < 2; ++q)
; #pragma unroll
;                 for (int i = 0; i < 16; ++i) { const int d0 = kp0 + 32 * q + crow(i, h); if (d0 > 128 || d0 < -128) s[q][i] = -INFINITY; } }
;         float mx = s[0][0];
; #pragma unroll
;         for (int q = 0; q < 2; ++q)
; #pragma unroll
;             for (int i = 0; i < 16; ++i) mx = fmaxf(mx, s[q][i]);
;         mx = fmaxf(mx, __shfl_xor(mx, 32)) * scl;
;         if (!__all(mx - mrun <= THR2)) {
;             const float mnew = fmaxf(mrun, mx), alpha = __builtin_amdgcn_exp2f(mrun - mnew);
;             lrun *= alpha; mrun = mnew;
; #pragma unroll
;             for (int dt = 0; dt < NDT; ++dt)
; #pragma unroll
;                 for (int i = 0; i < 16; ++i) o[dt][i] *= alpha;
;         }
;         float ls = 0.f; const float nm = -mrun;
; #pragma unroll
;         for (int q = 0; q < 2; ++q)
; #pragma unroll
;             for (int i = 0; i < 16; ++i) { s[q][i] = __builtin_amdgcn_exp2f(fmaf(s[q][i], scl, nm)); ls += s[q][i]; }
;         lrun += ls;
; #pragma unroll
;         for (int q = 0; q < 2; ++q)
; #pragma unroll
;             for (int s2 = 0; s2 < 2; ++s2) {
;                 u32x4 pw; pw.x = cvtpk(s[q][8 * s2], s[q][8 * s2 + 1]); pw.y = cvtpk(s[q][8 * s2 + 2], s[q][8 * s2 + 3]); pw.z = cvtpk(s[q][8 * s2 + 4], s[q][8 * s2 + 5]); pw.w = cvtpk(s[q][8 * s2 + 6], s[q][8 * s2 + 7]);
;                 const bf16x8 pb = __builtin_bit_cast(bf16x8, pw);
; #pragma unroll
;                 for (int dt = 0; dt < NDT; ++dt) { const LAS bf16* vp = Vt + (32 * dt + r) * VP + 64 * sub + 32 * q + 16 * s2 + 4 * h;
	v_mfma_f32_32x32x16_bf16 v[32:47], v[172:175], v[48:51], v[32:47]
	ds_read2_b64 v[200:203], v84 offset0:76 offset1:78
	v_add_f32_e32 v15, v88, v15
	v_add_f32_e32 v15, v89, v15
	v_add_f32_e32 v15, v90, v15
	v_add_f32_e32 v15, v91, v15
	v_add_f32_e32 v15, v92, v15
	v_add_f32_e32 v15, v93, v15
	s_waitcnt lgkmcnt(4)
	v_mfma_f32_32x32x16_bf16 v[16:31], v[180:183], v[48:51], v[16:31]
	ds_read2_b64 v[204:207], v85 offset0:108 offset1:110
	v_cvt_pk_bf16_f32 v48, v72, v73
	v_cvt_pk_bf16_f32 v49, v74, v75
	v_cvt_pk_bf16_f32 v50, v76, v77
	v_cvt_pk_bf16_f32 v51, v78, v79
	v_add_f32_e32 v15, v94, v15
	v_add_f32_e32 v15, v95, v15
	s_waitcnt lgkmcnt(4)
	v_mfma_f32_32x32x16_bf16 v[16:31], v[184:187], v[48:51], v[16:31]
	v_add_f32_e32 v15, v96, v15
	v_add_f32_e32 v15, v97, v15
	v_add_f32_e32 v15, v98, v15
	v_add_f32_e32 v15, v60, v15
	v_add_f32_e32 v15, v61, v15
	v_add_f32_e32 v15, v62, v15
	s_waitcnt lgkmcnt(6)
	v_mfma_f32_32x32x16_bf16 v[32:47], v[176:179], v[48:51], v[32:47]
	v_cvt_pk_bf16_f32 v48, v87, v88
	v_cvt_pk_bf16_f32 v49, v89, v90
	v_cvt_pk_bf16_f32 v50, v91, v92
	v_cvt_pk_bf16_f32 v51, v93, v94
	v_add_f32_e32 v15, v63, v15
	v_add_f32_e32 v86, v100, v15
	s_waitcnt lgkmcnt(3)
	v_mfma_f32_32x32x16_bf16 v[32:47], v[192:195], v[48:51], v[32:47]
	s_waitcnt lgkmcnt(2)
	v_mfma_f32_32x32x16_bf16 v[16:31], v[196:199], v[48:51], v[16:31]
	v_cvt_pk_bf16_f32 v48, v95, v96
	v_cvt_pk_bf16_f32 v49, v97, v98
	v_cvt_pk_bf16_f32 v50, v60, v61
	v_cvt_pk_bf16_f32 v51, v62, v63
	s_nop 0
	s_waitcnt lgkmcnt(1)
	v_mfma_f32_32x32x16_bf16 v[32:47], v[200:203], v[48:51], v[32:47]
	s_waitcnt lgkmcnt(0)
	v_mfma_f32_32x32x16_bf16 v[16:31], v[204:207], v[48:51], v[16:31]
	ds_read_b128 v[208:211], v0 offset:44544
	ds_read_b128 v[212:215], v0 offset:44576
	s_waitcnt lgkmcnt(1)
	v_mfma_f32_32x32x16_bf16 v[64:79], v[208:211], v[80:83], 0
	ds_read_b128 v[220:223], v0 offset:44608
	s_waitcnt lgkmcnt(1)
	v_mfma_f32_32x32x16_bf16 v[64:79], v[212:215], v[10:13], v[64:79]
	s_waitcnt lgkmcnt(0)
	v_mfma_f32_32x32x16_bf16 v[64:79], v[220:223], v[6:9], v[64:79]
	ds_read_b128 v[224:227], v0 offset:44640
	s_waitcnt lgkmcnt(0)
	v_mfma_f32_32x32x16_bf16 v[64:79], v[224:227], v[2:5], v[64:79]
	ds_read_b128 v[228:231], v0 offset:49152
	s_waitcnt lgkmcnt(0)
	v_mfma_f32_32x32x16_bf16 v[48:63], v[228:231], v[80:83], 0
	ds_read_b128 v[232:235], v0 offset:49184
	s_waitcnt lgkmcnt(0)
	v_mfma_f32_32x32x16_bf16 v[48:63], v[232:235], v[10:13], v[48:63]
	ds_read_b128 v[236:239], v0 offset:49216
	s_waitcnt lgkmcnt(0)
	v_mfma_f32_32x32x16_bf16 v[48:63], v[236:239], v[6:9], v[48:63]
	ds_read_b128 v[240:243], v0 offset:49248
	s_nop 1
	v_max_f32_e32 v0, v65, v65
	s_waitcnt lgkmcnt(0)
	v_mfma_f32_32x32x16_bf16 v[48:63], v[240:243], v[2:5], v[48:63]
	v_max_f32_e32 v2, v64, v64
	v_max_f32_e32 v0, v2, v0
	v_max3_f32 v0, v0, v66, v67
	v_max3_f32 v0, v0, v68, v69
	v_max3_f32 v0, v0, v70, v71
	v_max3_f32 v0, v0, v72, v73
	v_max3_f32 v0, v0, v74, v75
	v_max3_f32 v0, v0, v76, v77
	v_max3_f32 v0, v0, v78, v79
	s_nop 2
	v_max3_f32 v0, v0, v48, v49
	v_max3_f32 v0, v0, v50, v51
	v_max3_f32 v0, v0, v52, v53
	v_max3_f32 v0, v0, v54, v55
	v_max3_f32 v0, v0, v56, v57
	v_max3_f32 v0, v0, v58, v59
	v_max3_f32 v0, v0, v60, v61
	v_max3_f32 v0, v0, v62, v63
	ds_bpermute_b32 v2, v103, v0
	s_waitcnt lgkmcnt(0)
	v_max_f32_e32 v2, v2, v2
	v_max_f32_e32 v0, v0, v2
	v_fma_f32 v2, v0, s20, -v101
	v_cmp_ge_f32_e32 vcc, s38, v2
	s_cmp_eq_u64 vcc, exec
	s_cbranch_scc1 .LBB0_500
	v_mul_f32_e32 v0, 0x3e38aa3b, v0
	v_max_f32_e64 v0, -v0, -v0
	v_max_f32_e64 v2, -v101, -v101
	v_min_f32_e32 v0, v2, v0
	v_add_f32_e32 v2, v101, v0
	v_exp_f32_e32 v2, v2
	s_nop 0
	v_pk_mul_f32 v[46:47], v[46:47], v[2:3] op_sel_hi:[1,0]
	v_pk_mul_f32 v[44:45], v[44:45], v[2:3] op_sel_hi:[1,0]
	v_pk_mul_f32 v[42:43], v[42:43], v[2:3] op_sel_hi:[1,0]
	v_pk_mul_f32 v[40:41], v[40:41], v[2:3] op_sel_hi:[1,0]
	v_pk_mul_f32 v[38:39], v[38:39], v[2:3] op_sel_hi:[1,0]
	v_pk_mul_f32 v[36:37], v[36:37], v[2:3] op_sel_hi:[1,0]
	v_pk_mul_f32 v[34:35], v[34:35], v[2:3] op_sel_hi:[1,0]
	v_pk_mul_f32 v[32:33], v[32:33], v[2:3] op_sel_hi:[1,0]
	v_pk_mul_f32 v[30:31], v[30:31], v[2:3] op_sel_hi:[1,0]
	v_pk_mul_f32 v[28:29], v[28:29], v[2:3] op_sel_hi:[1,0]
	v_pk_mul_f32 v[26:27], v[26:27], v[2:3] op_sel_hi:[1,0]
	v_pk_mul_f32 v[24:25], v[24:25], v[2:3] op_sel_hi:[1,0]
	v_pk_mul_f32 v[22:23], v[22:23], v[2:3] op_sel_hi:[1,0]
	v_pk_mul_f32 v[20:21], v[20:21], v[2:3] op_sel_hi:[1,0]
	v_pk_mul_f32 v[18:19], v[18:19], v[2:3] op_sel_hi:[1,0]
	v_pk_mul_f32 v[16:17], v[16:17], v[2:3] op_sel_hi:[1,0]
	v_mul_f32_e32 v86, v86, v2
	s_branch .LBB0_501

; #define LAS __attribute__((address_space(3)))
; #define MFMA32(a, b, c) __builtin_amdgcn_mfma_f32_32x32x16_bf16((a), (b), (c), 0, 0, 0)
; DI unsigned cvtpk(float lo, float hi) { f32x2 v = {lo, hi}; bf16x2_t b = __builtin_convertvector(v, bf16x2_t); return __builtin_bit_cast(unsigned, b); }
; template <int D, int MODE, int NSUB>
; DI void attn_item(const bf16* QKV, int pitch, int qcol0, int kcol0, const bf16* VT, bf16* O, int ocol0, const float* sink,
;                   LAS unsigned char* lds, int item, int tid_in, int lane_in, int wave) {
;     ...
;         float ls = 0.f; const float nm = -mrun;
; #pragma unroll
;         for (int q = 0; q < 2; ++q)
; #pragma unroll
;             for (int i = 0; i < 16; ++i) { s[q][i] = __builtin_amdgcn_exp2f(fmaf(s[q][i], scl, nm)); ls += s[q][i]; }
;         lrun += ls;
; #pragma unroll
;         for (int q = 0; q < 2; ++q)
; #pragma unroll
;             for (int s2 = 0; s2 < 2; ++s2) {
;                 u32x4 pw; pw.x = cvtpk(s[q][8 * s2], s[q][8 * s2 + 1]); pw.y = cvtpk(s[q][8 * s2 + 2], s[q][8 * s2 + 3]); pw.z = cvtpk(s[q][8 * s2 + 4], s[q][8 * s2 + 5]); pw.w = cvtpk(s[q][8 * s2 + 6], s[q][8 * s2 + 7]);
;                 const bf16x8 pb = __builtin_bit_cast(bf16x8, pw);
; #pragma unroll
;                 for (int dt = 0; dt < NDT; ++dt) { const LAS bf16* vp = Vt + (32 * dt + r) * VP + 64 * sub + 32 * q + 16 * s2 + 4 * h;
;                     const s16x4 lo = *(const LAS s16x4*)vp, hi = *(const LAS s16x4*)(vp + 8);
;                     const bf16x8 a = __builtin_shufflevector(lo, hi, 0, 1, 2, 3, 4, 5, 6, 7);
;                     o[dt] = MFMA32(a, pb, o[dt]); }
;             }
;         }
;         if (t + 1 < nt) ATT_STORE((t + 1) & 1);
;         __syncthreads();
;     }
;     ...
;     const float inv = 1.f / (lrun + __shfl_xor(lrun, 32));
;     bf16* op = O + (size_t)(qrow + r) * DM + ocol0 + head * D + 4 * h;
; #pragma unroll
;     for (int dt = 0; dt < NDT; ++dt)
; #pragma unroll
;         for (int g = 0; g < 4; ++g) { u32x2 w; w.x = cvtpk(o[dt][4 * g] * inv, o[dt][4 * g + 1] * inv); w.y = cvtpk(o[dt][4 * g + 2] * inv, o[dt][4 * g + 3] * inv);
;             *(u32x2*)(op + 32 * dt + 8 * g) = w; }
.LBB0_501:
	v_fmamk_f32 v2, v64, 0x3e38aa3b, v0
	v_exp_f32_e32 v64, v2
	v_fmamk_f32 v2, v65, 0x3e38aa3b, v0
	v_exp_f32_e32 v65, v2
	v_fmamk_f32 v2, v66, 0x3e38aa3b, v0
	v_exp_f32_e32 v66, v2
	v_fmamk_f32 v2, v67, 0x3e38aa3b, v0
	v_exp_f32_e32 v67, v2
	v_fmamk_f32 v2, v68, 0x3e38aa3b, v0
	v_exp_f32_e32 v68, v2
	v_fmamk_f32 v2, v69, 0x3e38aa3b, v0
	v_exp_f32_e32 v69, v2
	v_fmamk_f32 v2, v70, 0x3e38aa3b, v0
	v_exp_f32_e32 v70, v2
	v_fmamk_f32 v2, v71, 0x3e38aa3b, v0
	v_exp_f32_e32 v71, v2
	v_fmamk_f32 v2, v72, 0x3e38aa3b, v0
	v_exp_f32_e32 v72, v2
	v_fmamk_f32 v2, v73, 0x3e38aa3b, v0
	v_exp_f32_e32 v73, v2
	v_fmamk_f32 v2, v74, 0x3e38aa3b, v0
	v_exp_f32_e32 v74, v2
	v_fmamk_f32 v2, v75, 0x3e38aa3b, v0
	v_exp_f32_e32 v75, v2
	v_fmamk_f32 v2, v76, 0x3e38aa3b, v0
	v_exp_f32_e32 v76, v2
	v_fmamk_f32 v2, v77, 0x3e38aa3b, v0
	v_exp_f32_e32 v77, v2
	v_fmamk_f32 v2, v78, 0x3e38aa3b, v0
	v_exp_f32_e32 v78, v2
	v_fmamk_f32 v2, v79, 0x3e38aa3b, v0
	v_exp_f32_e32 v79, v2
	v_fmamk_f32 v2, v48, 0x3e38aa3b, v0
	v_exp_f32_e32 v48, v2
	v_fmamk_f32 v2, v49, 0x3e38aa3b, v0
	v_exp_f32_e32 v49, v2
	v_fmamk_f32 v2, v50, 0x3e38aa3b, v0
	v_exp_f32_e32 v50, v2
	v_fmamk_f32 v2, v51, 0x3e38aa3b, v0
	v_exp_f32_e32 v51, v2
	v_fmamk_f32 v2, v52, 0x3e38aa3b, v0
	v_exp_f32_e32 v52, v2
	v_fmamk_f32 v2, v53, 0x3e38aa3b, v0
	v_exp_f32_e32 v53, v2
	v_fmamk_f32 v2, v54, 0x3e38aa3b, v0
	v_exp_f32_e32 v54, v2
	v_fmamk_f32 v2, v55, 0x3e38aa3b, v0
	v_exp_f32_e32 v55, v2
	v_fmamk_f32 v2, v56, 0x3e38aa3b, v0
	v_exp_f32_e32 v56, v2
	v_fmamk_f32 v2, v57, 0x3e38aa3b, v0
	v_exp_f32_e32 v57, v2
	v_fmamk_f32 v2, v58, 0x3e38aa3b, v0
	v_exp_f32_e32 v58, v2
	v_fmamk_f32 v2, v59, 0x3e38aa3b, v0
	v_exp_f32_e32 v59, v2
	v_fmamk_f32 v2, v60, 0x3e38aa3b, v0
	ds_read2_b64 v[172:175], v84 offset0:80 offset1:82
	ds_read2_b64 v[176:179], v84 offset0:84 offset1:86
	ds_read2_b64 v[180:183], v85 offset0:112 offset1:114
	ds_read2_b64 v[184:187], v85 offset0:116 offset1:118
	ds_read2_b64 v[192:195], v84 offset0:88 offset1:90
	ds_read2_b64 v[196:199], v85 offset0:120 offset1:122
	v_exp_f32_e32 v60, v2
	v_fmamk_f32 v2, v61, 0x3e38aa3b, v0
	v_exp_f32_e32 v61, v2
	v_fmamk_f32 v2, v62, 0x3e38aa3b, v0
	v_exp_f32_e32 v62, v2
	v_cvt_pk_bf16_f32 v2, v64, v65
	v_cvt_pk_bf16_f32 v3, v66, v67
	v_cvt_pk_bf16_f32 v4, v68, v69
	v_cvt_pk_bf16_f32 v5, v70, v71
	v_fmac_f32_e32 v0, 0x3e38aa3b, v63
	v_exp_f32_e32 v0, v0
	s_waitcnt lgkmcnt(5)
	v_mfma_f32_32x32x16_bf16 v[32:47], v[172:175], v[2:5], v[32:47]
	ds_read2_b64 v[200:203], v84 offset0:92 offset1:94
	v_mov_b32_e32 v15, v1
	v_readlane_b32 s4, v254, 31
	s_lshl_b32 s0, s6, 6
	v_readlane_b32 s5, v254, 32
	s_lshl_b32 s0, s0, 1
	s_waitcnt lgkmcnt(4)
	v_mfma_f32_32x32x16_bf16 v[16:31], v[180:183], v[2:5], v[16:31]
	v_cvt_pk_bf16_f32 v2, v72, v73
	v_cvt_pk_bf16_f32 v3, v74, v75
	v_cvt_pk_bf16_f32 v4, v76, v77
	v_cvt_pk_bf16_f32 v5, v78, v79
	s_nop 0
	s_waitcnt lgkmcnt(3)
	v_mfma_f32_32x32x16_bf16 v[16:31], v[184:187], v[2:5], v[16:31]
	s_waitcnt lgkmcnt(5)
	v_mfma_f32_32x32x16_bf16 v[32:47], v[176:179], v[2:5], v[32:47]
	v_cvt_pk_bf16_f32 v2, v48, v49
	v_cvt_pk_bf16_f32 v3, v50, v51
	v_cvt_pk_bf16_f32 v4, v52, v53
	v_cvt_pk_bf16_f32 v5, v54, v55
	s_nop 0
	s_waitcnt lgkmcnt(2)
	v_mfma_f32_32x32x16_bf16 v[32:47], v[192:195], v[2:5], v[32:47]
	s_waitcnt lgkmcnt(1)
	v_mfma_f32_32x32x16_bf16 v[16:31], v[196:199], v[2:5], v[16:31]
	v_cvt_pk_bf16_f32 v2, v56, v57
	v_cvt_pk_bf16_f32 v3, v58, v59
	v_cvt_pk_bf16_f32 v4, v60, v61
	v_cvt_pk_bf16_f32 v5, v62, v0
	s_nop 0
	s_waitcnt lgkmcnt(0)
	v_mfma_f32_32x32x16_bf16 v[32:47], v[200:203], v[2:5], v[32:47]
	ds_read2_b64 v[6:9], v85 offset0:124 offset1:126
	s_waitcnt lgkmcnt(0)
	s_barrier
	v_mfma_f32_32x32x16_bf16 v[16:31], v[6:9], v[2:5], v[16:31]
	v_add_f32_e32 v2, 0, v64
	v_add_f32_e32 v2, v65, v2
	v_add_f32_e32 v2, v66, v2
	v_add_f32_e32 v2, v67, v2
	v_add_f32_e32 v2, v68, v2
	v_add_f32_e32 v2, v69, v2
	v_add_f32_e32 v2, v70, v2
	v_add_f32_e32 v2, v71, v2
	v_add_f32_e32 v2, v72, v2
	v_add_f32_e32 v2, v73, v2
	v_add_f32_e32 v2, v74, v2
	v_add_f32_e32 v2, v75, v2
	v_add_f32_e32 v2, v76, v2
	v_add_f32_e32 v2, v77, v2
	v_add_f32_e32 v2, v78, v2
	v_add_f32_e32 v2, v79, v2
	v_add_f32_e32 v2, v48, v2
	v_add_f32_e32 v2, v49, v2
	v_add_f32_e32 v2, v50, v2
	v_add_f32_e32 v2, v51, v2
	v_add_f32_e32 v2, v52, v2
	v_add_f32_e32 v2, v53, v2
	v_add_f32_e32 v2, v54, v2
	v_add_f32_e32 v2, v55, v2
	v_add_f32_e32 v2, v56, v2
	v_add_f32_e32 v2, v57, v2
	v_add_f32_e32 v2, v58, v2
	v_add_f32_e32 v2, v59, v2
	v_add_f32_e32 v2, v60, v2
	v_add_f32_e32 v2, v61, v2
	v_add_f32_e32 v2, v62, v2
	v_add_f32_e32 v0, v0, v2
	v_add_f32_e32 v0, v86, v0
	ds_bpermute_b32 v2, v103, v0
	s_waitcnt lgkmcnt(0)
	v_add_f32_e32 v4, v0, v2
	v_lshlrev_b64 v[2:3], 11, v[14:15]
	v_lshl_add_u64 v[2:3], s[4:5], 0, v[2:3]
	v_lshl_add_u64 v[2:3], v[2:3], 0, s[0:1]
	v_lshl_add_u64 v[2:3], v[2:3], 0, s[42:43]
	v_lshlrev_b32_e32 v0, 2, v102
	s_mov_b64 s[4:5], 0

; #define LAS __attribute__((address_space(3)))
; #define MFMA32(a, b, c) __builtin_amdgcn_mfma_f32_32x32x16_bf16((a), (b), (c), 0, 0, 0)
; DI int crow(int i, int h) { return (i & 3) + 8 * (i >> 2) + 4 * h; }
; DI f32x16 zero16() { f32x16 z; for (int i = 0; i < 16; ++i) z[i] = 0.f; return z; }
; #define ATT_LOAD(t) do { int krow0, vkey0; ATT_TILE(t, krow0, vkey0); _Pragma("unroll") for (int i = 0; i < NPT; ++i) { const int id = tid + 512 * i; \
;         kr[i] = *(const u32x4*)(QKV + (size_t)(krow0 + id / CPR) * pitch + kcol + (id % CPR) * 8); \
;         vr[i] = *(const u32x4*)(VTb + (size_t)(id / VCR) * KVLEN + vkey0 + (id % VCR) * 8); } } while (0)
; template <int D, int MODE, int NSUB>
; DI void attn_item(const bf16* QKV, int pitch, int qcol0, int kcol0, const bf16* VT, bf16* O, int ocol0, const float* sink,
;                   LAS unsigned char* lds, int item, int tid_in, int lane_in, int wave) {
;     ...
;     for (int t = 0; t < nt; ++t) {
;         if (t + 1 < nt) ATT_LOAD(t + 1);
;         const LAS bf16* Kt = (const LAS bf16*)(lds + (t & 1) * BUF); const LAS bf16* Vt = (const LAS bf16*)(lds + (t & 1) * BUF + KBYTES);
; #pragma unroll
;         for (int sub = 0; sub < NSUB; ++sub) {
;         f32x16 s[2];
; #pragma unroll
;         for (int q = 0; q < 2; ++q) { s[q] = zero16(); const LAS bf16* kp = Kt + (64 * sub + 32 * q + r) * KP + 8 * h;
; #pragma unroll
;             for (int ks = 0; ks < NKS; ++ks) s[q] = MFMA32(*(const LAS bf16x8*)(kp + 16 * ks), qf[ks], s[q]); }
;         if (MODE == 1 && KT * t >= CTXL) { const int kp0 = wstart + KT * t + 64 * sub - CTXL - qpos;
; #pragma unroll
;             for (int q = 0; q < 2; ++q)
; #pragma unroll
;                 for (int i = 0; i < 16; ++i) { const int d0 = kp0 + 32 * q + crow(i, h); if (d0 > 128 || d0 < -128) s[q][i] = -INFINITY; } }
.LBB0_509:
	s_bitcmp1_b32 s4, 0
	s_cselect_b32 s4, 0x8a00, 0
	s_add_i32 s31, s4, 0
	v_lshl_add_u32 v0, v140, 1, s31
	v_add_u32_e32 v4, v0, v142
	ds_read_b128 v[172:175], v4
	ds_read_b128 v[176:179], v4 offset:32
	ds_read_b128 v[180:183], v4 offset:64
	ds_read_b128 v[184:187], v4 offset:96
	ds_read_b128 v[192:195], v4 offset:4608
	ds_read_b128 v[196:199], v4 offset:4640
	s_cmpk_gt_u32 s6, 0xff
	s_cselect_b64 s[4:5], -1, 0
	s_cmpk_lt_u32 s6, 0x100
	s_waitcnt lgkmcnt(5)
	v_mfma_f32_32x32x16_bf16 v[64:79], v[172:175], v[96:99], 0
	ds_read_b128 v[200:203], v4 offset:4672
	v_add_u32_e32 v3, s6, v144
	s_waitcnt lgkmcnt(5)
	v_mfma_f32_32x32x16_bf16 v[64:79], v[176:179], v[88:91], v[64:79]
	ds_read_b128 v[204:207], v4 offset:4704
	s_waitcnt lgkmcnt(5)
	v_mfma_f32_32x32x16_bf16 v[64:79], v[180:183], v[92:95], v[64:79]
	s_waitcnt lgkmcnt(4)
	v_mfma_f32_32x32x16_bf16 v[64:79], v[184:187], v[100:103], v[64:79]
	s_waitcnt lgkmcnt(3)
	v_mfma_f32_32x32x16_bf16 v[48:63], v[192:195], v[96:99], 0
	s_waitcnt lgkmcnt(2)
	v_mfma_f32_32x32x16_bf16 v[48:63], v[196:199], v[88:91], v[48:63]
	s_waitcnt lgkmcnt(1)
	v_mfma_f32_32x32x16_bf16 v[48:63], v[200:203], v[92:95], v[48:63]
	s_waitcnt lgkmcnt(0)
	v_mfma_f32_32x32x16_bf16 v[48:63], v[204:207], v[100:103], v[48:63]
	s_cbranch_scc1 .LBB0_511
	v_add_u32_e32 v0, 0xfffffe7f, v3
	v_cmp_gt_u32_e32 vcc, s44, v0
	v_add_u32_e32 v0, 0xfffffe80, v3
	s_nop 0
	v_cndmask_b32_e32 v64, v64, v129, vcc
	v_cmp_lt_u32_e32 vcc, s45, v0
	v_add_u32_e32 v0, 0xfffffe81, v3
	s_nop 0
	v_cndmask_b32_e32 v65, v129, v65, vcc
	v_cmp_lt_u32_e32 vcc, s45, v0
	v_add_u32_e32 v0, 0xfffffe82, v3
	s_nop 0
	v_cndmask_b32_e32 v66, v129, v66, vcc
	v_cmp_lt_u32_e32 vcc, s45, v0
	v_add_u32_e32 v0, 0xfffffe87, v3
	s_nop 0
	v_cndmask_b32_e32 v67, v129, v67, vcc
	v_cmp_lt_u32_e32 vcc, s45, v0
	v_add_u32_e32 v0, 0xfffffe88, v3
	s_nop 0
	v_cndmask_b32_e32 v68, v129, v68, vcc
	v_cmp_lt_u32_e32 vcc, s45, v0
	v_add_u32_e32 v0, 0xfffffe89, v3
	s_nop 0
	v_cndmask_b32_e32 v69, v129, v69, vcc
	v_cmp_lt_u32_e32 vcc, s45, v0
	v_add_u32_e32 v0, 0xfffffe8a, v3
	s_nop 0
	v_cndmask_b32_e32 v70, v129, v70, vcc
	v_cmp_lt_u32_e32 vcc, s45, v0
	v_add_u32_e32 v0, 0xfffffe8f, v3
	s_nop 0
	v_cndmask_b32_e32 v71, v129, v71, vcc
	v_cmp_lt_u32_e32 vcc, s45, v0
	v_add_u32_e32 v0, 0xfffffe90, v3
	s_nop 0
	v_cndmask_b32_e32 v72, v129, v72, vcc
	v_cmp_lt_u32_e32 vcc, s45, v0
	v_add_u32_e32 v0, 0xfffffe91, v3
	s_nop 0
	v_cndmask_b32_e32 v73, v129, v73, vcc
	v_cmp_lt_u32_e32 vcc, s45, v0
	v_add_u32_e32 v0, 0xfffffe92, v3
	s_nop 0
	v_cndmask_b32_e32 v74, v129, v74, vcc
	v_cmp_lt_u32_e32 vcc, s45, v0
	v_add_u32_e32 v0, 0xfffffe97, v3
	s_nop 0
	v_cndmask_b32_e32 v75, v129, v75, vcc
	v_cmp_lt_u32_e32 vcc, s45, v0
	v_add_u32_e32 v0, 0xfffffe98, v3
	s_nop 0
	v_cndmask_b32_e32 v76, v129, v76, vcc
	v_cmp_lt_u32_e32 vcc, s45, v0
	v_add_u32_e32 v0, 0xfffffe99, v3
	s_nop 0
	v_cndmask_b32_e32 v77, v129, v77, vcc
	v_cmp_lt_u32_e32 vcc, s45, v0
	v_add_u32_e32 v0, 0xfffffe9a, v3
	s_nop 0
	v_cndmask_b32_e32 v78, v129, v78, vcc
	v_cmp_lt_u32_e32 vcc, s45, v0
	v_add_u32_e32 v0, 0xfffffe9f, v3
	s_nop 0
	v_cndmask_b32_e32 v79, v129, v79, vcc
	v_cmp_lt_u32_e32 vcc, s45, v0
	v_add_u32_e32 v0, 0xfffffea0, v3
	s_nop 0
	v_cndmask_b32_e32 v48, v129, v48, vcc
	v_cmp_lt_u32_e32 vcc, s45, v0
	v_add_u32_e32 v0, 0xfffffea1, v3
	s_nop 0
	v_cndmask_b32_e32 v49, v129, v49, vcc
	v_cmp_lt_u32_e32 vcc, s45, v0
	v_add_u32_e32 v0, 0xfffffea2, v3
	s_nop 0
	v_cndmask_b32_e32 v50, v129, v50, vcc
	v_cmp_lt_u32_e32 vcc, s45, v0
	v_add_u32_e32 v0, 0xfffffea7, v3
	s_nop 0
	v_cndmask_b32_e32 v51, v129, v51, vcc
	v_cmp_lt_u32_e32 vcc, s45, v0
	v_add_u32_e32 v0, 0xfffffea8, v3
	s_nop 0
	v_cndmask_b32_e32 v52, v129, v52, vcc
	v_cmp_lt_u32_e32 vcc, s45, v0
	v_add_u32_e32 v0, 0xfffffea9, v3
	s_nop 0
	v_cndmask_b32_e32 v53, v129, v53, vcc
	v_cmp_lt_u32_e32 vcc, s45, v0
	v_add_u32_e32 v0, 0xfffffeaa, v3
	s_nop 0
	v_cndmask_b32_e32 v54, v129, v54, vcc
	v_cmp_lt_u32_e32 vcc, s45, v0
	v_add_u32_e32 v0, 0xfffffeaf, v3
	s_nop 0
	v_cndmask_b32_e32 v55, v129, v55, vcc
	v_cmp_lt_u32_e32 vcc, s45, v0
	v_add_u32_e32 v0, 0xfffffeb0, v3
	s_nop 0
	v_cndmask_b32_e32 v56, v129, v56, vcc
	v_cmp_lt_u32_e32 vcc, s45, v0
	v_add_u32_e32 v0, 0xfffffeb1, v3
	s_nop 0
	v_cndmask_b32_e32 v57, v129, v57, vcc
	v_cmp_lt_u32_e32 vcc, s45, v0
	v_add_u32_e32 v0, 0xfffffeb2, v3
	s_nop 0
	v_cndmask_b32_e32 v58, v129, v58, vcc
	v_cmp_lt_u32_e32 vcc, s45, v0
	v_add_u32_e32 v0, 0xfffffeb7, v3
	s_nop 0
	v_cndmask_b32_e32 v59, v129, v59, vcc
	v_cmp_lt_u32_e32 vcc, s45, v0
	v_add_u32_e32 v0, 0xfffffeb8, v3
	s_nop 0
	v_cndmask_b32_e32 v60, v129, v60, vcc
	v_cmp_lt_u32_e32 vcc, s45, v0
	v_add_u32_e32 v0, 0xfffffeb9, v3
	s_nop 0
	v_cndmask_b32_e32 v61, v129, v61, vcc
	v_cmp_lt_u32_e32 vcc, s45, v0
	v_add_u32_e32 v0, 0xfffffeba, v3
	s_nop 0
	v_cndmask_b32_e32 v62, v129, v62, vcc
	v_cmp_lt_u32_e32 vcc, s45, v0
	s_nop 1
	v_cndmask_b32_e32 v63, v129, v63, vcc

; #define LAS __attribute__((address_space(3)))
; #define MFMA32(a, b, c) __builtin_amdgcn_mfma_f32_32x32x16_bf16((a), (b), (c), 0, 0, 0)
; DI unsigned cvtpk(float lo, float hi) { f32x2 v = {lo, hi}; bf16x2_t b = __builtin_convertvector(v, bf16x2_t); return __builtin_bit_cast(unsigned, b); }
; DI f32x16 zero16() { f32x16 z; for (int i = 0; i < 16; ++i) z[i] = 0.f; return z; }
; template <int D, int MODE, int NSUB>
; DI void attn_item(const bf16* QKV, int pitch, int qcol0, int kcol0, const bf16* VT, bf16* O, int ocol0, const float* sink,
;                   LAS unsigned char* lds, int item, int tid_in, int lane_in, int wave) {
;     ...
;         for (int q = 0; q < 2; ++q) { s[q] = zero16(); const LAS bf16* kp = Kt + (64 * sub + 32 * q + r) * KP + 8 * h;
; #pragma unroll
;             for (int ks = 0; ks < NKS; ++ks) s[q] = MFMA32(*(const LAS bf16x8*)(kp + 16 * ks), qf[ks], s[q]); }
;     ...
;         float ls = 0.f; const float nm = -mrun;
; #pragma unroll
;         for (int q = 0; q < 2; ++q)
; #pragma unroll
;             for (int i = 0; i < 16; ++i) { s[q][i] = __builtin_amdgcn_exp2f(fmaf(s[q][i], scl, nm)); ls += s[q][i]; }
;         lrun += ls;
; #pragma unroll
;         for (int q = 0; q < 2; ++q)
; #pragma unroll
;             for (int s2 = 0; s2 < 2; ++s2) {
;                 u32x4 pw; pw.x = cvtpk(s[q][8 * s2], s[q][8 * s2 + 1]); pw.y = cvtpk(s[q][8 * s2 + 2], s[q][8 * s2 + 3]); pw.z = cvtpk(s[q][8 * s2 + 4], s[q][8 * s2 + 5]); pw.w = cvtpk(s[q][8 * s2 + 6], s[q][8 * s2 + 7]);
;                 const bf16x8 pb = __builtin_bit_cast(bf16x8, pw);
; #pragma unroll
;                 for (int dt = 0; dt < NDT; ++dt) { const LAS bf16* vp = Vt + (32 * dt + r) * VP + 64 * sub + 32 * q + 16 * s2 + 4 * h;
;                     const s16x4 lo = *(const LAS s16x4*)vp, hi = *(const LAS s16x4*)(vp + 8);
;                     const bf16x8 a = __builtin_shufflevector(lo, hi, 0, 1, 2, 3, 4, 5, 6, 7);
;                     o[dt] = MFMA32(a, pb, o[dt]); }
;             }
.LBB0_513:
	v_fma_f32 v2, v64, s20, -v145
	v_exp_f32_e32 v5, v2
	v_fma_f32 v2, v65, s20, -v145
	v_exp_f32_e32 v6, v2
	v_fma_f32 v2, v66, s20, -v145
	v_exp_f32_e32 v7, v2
	v_fma_f32 v2, v67, s20, -v145
	v_exp_f32_e32 v8, v2
	v_fma_f32 v2, v68, s20, -v145
	v_exp_f32_e32 v10, v2
	v_fma_f32 v2, v69, s20, -v145
	v_exp_f32_e32 v12, v2
	v_fma_f32 v2, v70, s20, -v145
	v_exp_f32_e32 v14, v2
	v_fma_f32 v2, v71, s20, -v145
	v_exp_f32_e32 v147, v2
	v_fma_f32 v2, v72, s20, -v145
	v_exp_f32_e32 v148, v2
	v_fma_f32 v2, v73, s20, -v145
	v_exp_f32_e32 v149, v2
	v_fma_f32 v2, v74, s20, -v145
	v_exp_f32_e32 v150, v2
	v_fma_f32 v2, v75, s20, -v145
	v_exp_f32_e32 v151, v2
	v_fma_f32 v2, v76, s20, -v145
	v_exp_f32_e32 v152, v2
	v_fma_f32 v2, v77, s20, -v145
	v_exp_f32_e32 v153, v2
	v_fma_f32 v2, v78, s20, -v145
	v_exp_f32_e32 v154, v2
	v_fma_f32 v2, v79, s20, -v145
	v_exp_f32_e32 v155, v2
	v_fma_f32 v2, v48, s20, -v145
	v_exp_f32_e32 v156, v2
	v_fma_f32 v2, v49, s20, -v145
	v_exp_f32_e32 v157, v2
	v_fma_f32 v2, v50, s20, -v145
	v_exp_f32_e32 v158, v2
	v_fma_f32 v2, v51, s20, -v145
	v_exp_f32_e32 v159, v2
	v_fma_f32 v2, v52, s20, -v145
	v_exp_f32_e32 v160, v2
	v_fma_f32 v2, v53, s20, -v145
	v_exp_f32_e32 v161, v2
	v_fma_f32 v2, v54, s20, -v145
	v_exp_f32_e32 v162, v2
	v_fma_f32 v2, v55, s20, -v145
	v_exp_f32_e32 v163, v2
	v_fma_f32 v2, v56, s20, -v145
	v_exp_f32_e32 v164, v2
	v_fma_f32 v2, v57, s20, -v145
	v_exp_f32_e32 v165, v2
	v_fma_f32 v2, v58, s20, -v145
	v_exp_f32_e32 v166, v2
	v_fma_f32 v2, v59, s20, -v145
	v_exp_f32_e32 v167, v2
	v_fma_f32 v2, v60, s20, -v145
	v_exp_f32_e32 v9, v2
	v_fma_f32 v2, v61, s20, -v145
	v_exp_f32_e32 v11, v2
	v_fma_f32 v2, v62, s20, -v145
	v_add_u32_e32 v0, s31, v140
	v_exp_f32_e32 v13, v2
	v_fma_f32 v2, v63, s20, -v145
	v_exp_f32_e32 v15, v2
	v_add_u32_e32 v2, v0, v143
	v_add_u32_e32 v0, 0x4800, v2
	ds_read2_b64 v[172:175], v0 offset1:2
	ds_read2_b64 v[176:179], v0 offset0:4 offset1:6
	v_cvt_pk_bf16_f32 v48, v5, v6
	v_cvt_pk_bf16_f32 v49, v7, v8
	v_cvt_pk_bf16_f32 v50, v10, v12
	v_cvt_pk_bf16_f32 v51, v14, v147
	v_add_u32_e32 v2, 0x6800, v2
	ds_read2_b64 v[180:183], v2 offset0:32 offset1:34
	ds_read2_b64 v[184:187], v2 offset0:36 offset1:38
	ds_read2_b64 v[192:195], v0 offset0:8 offset1:10
	ds_read2_b64 v[196:199], v2 offset0:40 offset1:42
	s_andn2_b64 vcc, exec, s[4:5]
	s_waitcnt lgkmcnt(5)
	v_mfma_f32_32x32x16_bf16 v[32:47], v[172:175], v[48:51], v[32:47]
	ds_read2_b64 v[200:203], v0 offset0:12 offset1:14
	s_waitcnt lgkmcnt(4)
	v_mfma_f32_32x32x16_bf16 v[16:31], v[180:183], v[48:51], v[16:31]
	ds_read2_b64 v[204:207], v2 offset0:44 offset1:46
	ds_read_b128 v[208:211], v4 offset:9216
	v_cvt_pk_bf16_f32 v48, v148, v149
	v_cvt_pk_bf16_f32 v49, v150, v151
	v_cvt_pk_bf16_f32 v50, v152, v153
	v_cvt_pk_bf16_f32 v51, v154, v155
	s_nop 0
	s_waitcnt lgkmcnt(5)
	v_mfma_f32_32x32x16_bf16 v[16:31], v[184:187], v[48:51], v[16:31]
	ds_read_b128 v[212:215], v4 offset:9248
	s_waitcnt lgkmcnt(8)
	v_mfma_f32_32x32x16_bf16 v[32:47], v[176:179], v[48:51], v[32:47]
	v_cvt_pk_bf16_f32 v48, v156, v157
	v_cvt_pk_bf16_f32 v49, v158, v159
	v_cvt_pk_bf16_f32 v50, v160, v161
	v_cvt_pk_bf16_f32 v51, v162, v163
	s_nop 0
	s_waitcnt lgkmcnt(5)
	v_mfma_f32_32x32x16_bf16 v[32:47], v[192:195], v[48:51], v[32:47]
	ds_read_b128 v[220:223], v4 offset:13856
	s_waitcnt lgkmcnt(5)
	v_mfma_f32_32x32x16_bf16 v[16:31], v[196:199], v[48:51], v[16:31]
	ds_read_b128 v[224:227], v4 offset:9280
	v_cvt_pk_bf16_f32 v48, v164, v165
	v_cvt_pk_bf16_f32 v49, v166, v167
	v_cvt_pk_bf16_f32 v50, v9, v11
	v_cvt_pk_bf16_f32 v51, v13, v15
	s_nop 0
	s_waitcnt lgkmcnt(5)
	v_mfma_f32_32x32x16_bf16 v[32:47], v[200:203], v[48:51], v[32:47]
	ds_read_b128 v[228:231], v4 offset:9312
	s_waitcnt lgkmcnt(5)
	v_mfma_f32_32x32x16_bf16 v[16:31], v[204:207], v[48:51], v[16:31]
	ds_read_b128 v[232:235], v4 offset:13824
	s_waitcnt lgkmcnt(5)
	v_mfma_f32_32x32x16_bf16 v[64:79], v[208:211], v[96:99], 0
	ds_read_b128 v[236:239], v4 offset:13888
	s_waitcnt lgkmcnt(5)
	v_mfma_f32_32x32x16_bf16 v[64:79], v[212:215], v[88:91], v[64:79]
	ds_read_b128 v[240:243], v4 offset:13920
	s_waitcnt lgkmcnt(4)
	v_mfma_f32_32x32x16_bf16 v[64:79], v[224:227], v[92:95], v[64:79]
	s_waitcnt lgkmcnt(3)
	v_mfma_f32_32x32x16_bf16 v[64:79], v[228:231], v[100:103], v[64:79]
	s_waitcnt lgkmcnt(2)
	v_mfma_f32_32x32x16_bf16 v[48:63], v[232:235], v[96:99], 0
	s_waitcnt lgkmcnt(5)
	v_mfma_f32_32x32x16_bf16 v[48:63], v[220:223], v[88:91], v[48:63]
	s_waitcnt lgkmcnt(1)
	v_mfma_f32_32x32x16_bf16 v[48:63], v[236:239], v[92:95], v[48:63]
	s_waitcnt lgkmcnt(0)
	v_mfma_f32_32x32x16_bf16 v[48:63], v[240:243], v[100:103], v[48:63]
	s_cbranch_vccnz .LBB0_515
; DI int crow(int i, int h) { return (i & 3) + 8 * (i >> 2) + 4 * h; }
; template <int D, int MODE, int NSUB>
; DI void attn_item(const bf16* QKV, int pitch, int qcol0, int kcol0, const bf16* VT, bf16* O, int ocol0, const float* sink,
;                   LAS unsigned char* lds, int item, int tid_in, int lane_in, int wave) {
;     ...
;         if (MODE == 1 && KT * t >= CTXL) { const int kp0 = wstart + KT * t + 64 * sub - CTXL - qpos;
; #pragma unroll
;             for (int q = 0; q < 2; ++q)
; #pragma unroll
;                 for (int i = 0; i < 16; ++i) { const int d0 = kp0 + 32 * q + crow(i, h); if (d0 > 128 || d0 < -128) s[q][i] = -INFINITY; } }
	v_add_u32_e32 v4, 0xfffffebf, v3
	v_cmp_gt_u32_e32 vcc, s44, v4
	v_add_u32_e32 v4, 0xfffffec0, v3
	s_nop 0
	v_cndmask_b32_e32 v64, v64, v129, vcc
	v_cmp_lt_u32_e32 vcc, s45, v4
	v_add_u32_e32 v4, 0xfffffec1, v3
	s_nop 0
	v_cndmask_b32_e32 v65, v129, v65, vcc
	v_cmp_lt_u32_e32 vcc, s45, v4
	v_add_u32_e32 v4, 0xfffffec2, v3
	s_nop 0
	v_cndmask_b32_e32 v66, v129, v66, vcc
	v_cmp_lt_u32_e32 vcc, s45, v4
	v_add_u32_e32 v4, 0xfffffec7, v3
	s_nop 0
	v_cndmask_b32_e32 v67, v129, v67, vcc
	v_cmp_lt_u32_e32 vcc, s45, v4
	v_add_u32_e32 v4, 0xfffffec8, v3
	s_nop 0
	v_cndmask_b32_e32 v68, v129, v68, vcc
	v_cmp_lt_u32_e32 vcc, s45, v4
	v_add_u32_e32 v4, 0xfffffec9, v3
	s_nop 0
	v_cndmask_b32_e32 v69, v129, v69, vcc
	v_cmp_lt_u32_e32 vcc, s45, v4
	v_add_u32_e32 v4, 0xfffffeca, v3
	s_nop 0
	v_cndmask_b32_e32 v70, v129, v70, vcc
	v_cmp_lt_u32_e32 vcc, s45, v4
	v_add_u32_e32 v4, 0xfffffecf, v3
	s_nop 0
	v_cndmask_b32_e32 v71, v129, v71, vcc
	v_cmp_lt_u32_e32 vcc, s45, v4
	v_add_u32_e32 v4, 0xfffffed0, v3
	s_nop 0
	v_cndmask_b32_e32 v72, v129, v72, vcc
	v_cmp_lt_u32_e32 vcc, s45, v4
	v_add_u32_e32 v4, 0xfffffed1, v3
	s_nop 0
	v_cndmask_b32_e32 v73, v129, v73, vcc
	v_cmp_lt_u32_e32 vcc, s45, v4
	v_add_u32_e32 v4, 0xfffffed2, v3
	s_nop 0
	v_cndmask_b32_e32 v74, v129, v74, vcc
	v_cmp_lt_u32_e32 vcc, s45, v4
	v_add_u32_e32 v4, 0xfffffed7, v3
	s_nop 0
	v_cndmask_b32_e32 v75, v129, v75, vcc
	v_cmp_lt_u32_e32 vcc, s45, v4
	v_add_u32_e32 v4, 0xfffffed8, v3
	s_nop 0
	v_cndmask_b32_e32 v76, v129, v76, vcc
	v_cmp_lt_u32_e32 vcc, s45, v4
	v_add_u32_e32 v4, 0xfffffed9, v3
	s_nop 0
	v_cndmask_b32_e32 v77, v129, v77, vcc
	v_cmp_lt_u32_e32 vcc, s45, v4
	v_add_u32_e32 v4, 0xfffffeda, v3
	s_nop 0
	v_cndmask_b32_e32 v78, v129, v78, vcc
	v_cmp_lt_u32_e32 vcc, s45, v4
	v_add_u32_e32 v4, 0xfffffedf, v3
	s_nop 0
	v_cndmask_b32_e32 v79, v129, v79, vcc
	v_cmp_lt_u32_e32 vcc, s45, v4
	v_add_u32_e32 v4, 0xfffffee0, v3
	s_nop 0
	v_cndmask_b32_e32 v48, v129, v48, vcc
	v_cmp_lt_u32_e32 vcc, s45, v4
	v_add_u32_e32 v4, 0xfffffee1, v3
	s_nop 0
	v_cndmask_b32_e32 v49, v129, v49, vcc
	v_cmp_lt_u32_e32 vcc, s45, v4
	v_add_u32_e32 v4, 0xfffffee2, v3
	s_nop 0
	v_cndmask_b32_e32 v50, v129, v50, vcc
	v_cmp_lt_u32_e32 vcc, s45, v4
	v_add_u32_e32 v4, 0xfffffee7, v3
	s_nop 0
	v_cndmask_b32_e32 v51, v129, v51, vcc
	v_cmp_lt_u32_e32 vcc, s45, v4
	v_add_u32_e32 v4, 0xfffffee8, v3
	s_nop 0
	v_cndmask_b32_e32 v52, v129, v52, vcc
	v_cmp_lt_u32_e32 vcc, s45, v4
	v_add_u32_e32 v4, 0xfffffee9, v3
	s_nop 0
	v_cndmask_b32_e32 v53, v129, v53, vcc
	v_cmp_lt_u32_e32 vcc, s45, v4
	v_add_u32_e32 v4, 0xfffffeea, v3
	s_nop 0
	v_cndmask_b32_e32 v54, v129, v54, vcc
	v_cmp_lt_u32_e32 vcc, s45, v4
	v_add_u32_e32 v4, 0xfffffeef, v3
	s_nop 0
	v_cndmask_b32_e32 v55, v129, v55, vcc
	v_cmp_lt_u32_e32 vcc, s45, v4
	v_add_u32_e32 v4, 0xfffffef0, v3
	s_nop 0
	v_cndmask_b32_e32 v56, v129, v56, vcc
	v_cmp_lt_u32_e32 vcc, s45, v4
	v_add_u32_e32 v4, 0xfffffef1, v3
	s_nop 0
	v_cndmask_b32_e32 v57, v129, v57, vcc
	v_cmp_lt_u32_e32 vcc, s45, v4
	v_add_u32_e32 v4, 0xfffffef2, v3
	s_nop 0
	v_cndmask_b32_e32 v58, v129, v58, vcc
	v_cmp_lt_u32_e32 vcc, s45, v4
	v_add_u32_e32 v4, 0xfffffef7, v3
	s_nop 0
	v_cndmask_b32_e32 v59, v129, v59, vcc
	v_cmp_lt_u32_e32 vcc, s45, v4
	v_add_u32_e32 v4, 0xfffffef8, v3
	s_nop 0
	v_cndmask_b32_e32 v60, v129, v60, vcc
	v_cmp_lt_u32_e32 vcc, s45, v4
	v_add_u32_e32 v4, 0xfffffef9, v3
	v_add_u32_e32 v3, 0xfffffefa, v3
	v_cndmask_b32_e32 v61, v129, v61, vcc
	v_cmp_lt_u32_e32 vcc, s45, v4
	s_nop 1
	v_cndmask_b32_e32 v62, v129, v62, vcc
	v_cmp_lt_u32_e32 vcc, s45, v3
	s_nop 1
	v_cndmask_b32_e32 v63, v129, v63, vcc

; #define LAS __attribute__((address_space(3)))
; #define MFMA32(a, b, c) __builtin_amdgcn_mfma_f32_32x32x16_bf16((a), (b), (c), 0, 0, 0)
; DI unsigned cvtpk(float lo, float hi) { f32x2 v = {lo, hi}; bf16x2_t b = __builtin_convertvector(v, bf16x2_t); return __builtin_bit_cast(unsigned, b); }
; template <int D, int MODE, int NSUB>
; DI void attn_item(const bf16* QKV, int pitch, int qcol0, int kcol0, const bf16* VT, bf16* O, int ocol0, const float* sink,
;                   LAS unsigned char* lds, int item, int tid_in, int lane_in, int wave) {
;     ...
;         float ls = 0.f; const float nm = -mrun;
; #pragma unroll
;         for (int q = 0; q < 2; ++q)
; #pragma unroll
;             for (int i = 0; i < 16; ++i) { s[q][i] = __builtin_amdgcn_exp2f(fmaf(s[q][i], scl, nm)); ls += s[q][i]; }
;         lrun += ls;
; #pragma unroll
;         for (int q = 0; q < 2; ++q)
; #pragma unroll
;             for (int s2 = 0; s2 < 2; ++s2) {
;                 u32x4 pw; pw.x = cvtpk(s[q][8 * s2], s[q][8 * s2 + 1]); pw.y = cvtpk(s[q][8 * s2 + 2], s[q][8 * s2 + 3]); pw.z = cvtpk(s[q][8 * s2 + 4], s[q][8 * s2 + 5]); pw.w = cvtpk(s[q][8 * s2 + 6], s[q][8 * s2 + 7]);
;                 const bf16x8 pb = __builtin_bit_cast(bf16x8, pw);
; #pragma unroll
;                 for (int dt = 0; dt < NDT; ++dt) { const LAS bf16* vp = Vt + (32 * dt + r) * VP + 64 * sub + 32 * q + 16 * s2 + 4 * h;
;                     const s16x4 lo = *(const LAS s16x4*)vp, hi = *(const LAS s16x4*)(vp + 8);
;                     const bf16x8 a = __builtin_shufflevector(lo, hi, 0, 1, 2, 3, 4, 5, 6, 7);
;                     o[dt] = MFMA32(a, pb, o[dt]); }
;             }
;         }
;         if (t + 1 < nt) ATT_STORE((t + 1) & 1);
;         __syncthreads();
.LBB0_518:
	v_fmamk_f32 v4, v64, 0x3e38aa3b, v146
	v_fmamk_f32 v5, v65, 0x3e38aa3b, v146
	v_fmamk_f32 v6, v66, 0x3e38aa3b, v146
	v_fmamk_f32 v7, v67, 0x3e38aa3b, v146
	v_fmamk_f32 v8, v68, 0x3e38aa3b, v146
	v_fmamk_f32 v9, v69, 0x3e38aa3b, v146
	v_fmamk_f32 v10, v70, 0x3e38aa3b, v146
	v_fmamk_f32 v11, v71, 0x3e38aa3b, v146
	v_exp_f32_e32 v4, v4
	v_exp_f32_e32 v5, v5
	v_exp_f32_e32 v6, v6
	v_exp_f32_e32 v7, v7
	v_exp_f32_e32 v8, v8
	v_exp_f32_e32 v9, v9
	v_exp_f32_e32 v10, v10
	v_exp_f32_e32 v11, v11
	v_fmamk_f32 v12, v72, 0x3e38aa3b, v146
	v_fmamk_f32 v13, v73, 0x3e38aa3b, v146
	v_fmamk_f32 v14, v74, 0x3e38aa3b, v146
	v_fmamk_f32 v15, v75, 0x3e38aa3b, v146
	v_fmamk_f32 v64, v76, 0x3e38aa3b, v146
	v_fmamk_f32 v65, v77, 0x3e38aa3b, v146
	v_fmamk_f32 v66, v78, 0x3e38aa3b, v146
	v_fmamk_f32 v67, v79, 0x3e38aa3b, v146
	ds_read2_b64 v[172:175], v0 offset0:16 offset1:18
	ds_read2_b64 v[176:179], v0 offset0:20 offset1:22
	ds_read2_b64 v[180:183], v2 offset0:48 offset1:50
	ds_read2_b64 v[184:187], v2 offset0:52 offset1:54
	ds_read2_b64 v[192:195], v0 offset0:24 offset1:26
	ds_read2_b64 v[196:199], v2 offset0:56 offset1:58
	v_cvt_pk_bf16_f32 v68, v4, v5
	v_cvt_pk_bf16_f32 v69, v6, v7
	v_cvt_pk_bf16_f32 v70, v8, v9
	v_cvt_pk_bf16_f32 v71, v10, v11
	v_exp_f32_e32 v12, v12
	v_exp_f32_e32 v13, v13
	s_waitcnt lgkmcnt(5)
	v_mfma_f32_32x32x16_bf16 v[32:47], v[172:175], v[68:71], v[32:47]
	ds_read2_b64 v[200:203], v0 offset0:28 offset1:30
	v_exp_f32_e32 v14, v14
	v_exp_f32_e32 v15, v15
	v_exp_f32_e32 v64, v64
	v_exp_f32_e32 v65, v65
	v_exp_f32_e32 v66, v66
	v_exp_f32_e32 v67, v67
	s_waitcnt lgkmcnt(4)
	v_mfma_f32_32x32x16_bf16 v[16:31], v[180:183], v[68:71], v[16:31]
	ds_read2_b64 v[204:207], v2 offset0:60 offset1:62
	v_cvt_pk_bf16_f32 v68, v12, v13
	v_cvt_pk_bf16_f32 v69, v14, v15
	v_cvt_pk_bf16_f32 v70, v64, v65
	v_cvt_pk_bf16_f32 v71, v66, v67
	v_fmamk_f32 v48, v48, 0x3e38aa3b, v146
	v_fmamk_f32 v49, v49, 0x3e38aa3b, v146
	s_waitcnt lgkmcnt(4)
	v_mfma_f32_32x32x16_bf16 v[16:31], v[184:187], v[68:71], v[16:31]
	v_fmamk_f32 v50, v50, 0x3e38aa3b, v146
	v_fmamk_f32 v51, v51, 0x3e38aa3b, v146
	v_fmamk_f32 v52, v52, 0x3e38aa3b, v146
	v_fmamk_f32 v53, v53, 0x3e38aa3b, v146
	v_fmamk_f32 v54, v54, 0x3e38aa3b, v146
	v_fmamk_f32 v55, v55, 0x3e38aa3b, v146
	s_waitcnt lgkmcnt(6)
	v_mfma_f32_32x32x16_bf16 v[32:47], v[176:179], v[68:71], v[32:47]
	v_exp_f32_e32 v48, v48
	v_exp_f32_e32 v49, v49
	v_exp_f32_e32 v50, v50
	v_exp_f32_e32 v51, v51
	v_exp_f32_e32 v52, v52
	v_exp_f32_e32 v53, v53
	v_exp_f32_e32 v54, v54
	v_exp_f32_e32 v55, v55
	v_cvt_pk_bf16_f32 v68, v48, v49
	v_cvt_pk_bf16_f32 v69, v50, v51
	v_cvt_pk_bf16_f32 v70, v52, v53
	v_cvt_pk_bf16_f32 v71, v54, v55
	v_fmamk_f32 v56, v56, 0x3e38aa3b, v146
	v_fmamk_f32 v57, v57, 0x3e38aa3b, v146
	s_waitcnt lgkmcnt(3)
	v_mfma_f32_32x32x16_bf16 v[32:47], v[192:195], v[68:71], v[32:47]
	v_fmamk_f32 v58, v58, 0x3e38aa3b, v146
	v_fmamk_f32 v59, v59, 0x3e38aa3b, v146
	v_fmamk_f32 v60, v60, 0x3e38aa3b, v146
	v_fmamk_f32 v61, v61, 0x3e38aa3b, v146
	v_fmamk_f32 v62, v62, 0x3e38aa3b, v146
	v_fmac_f32_e32 v146, 0x3e38aa3b, v63
	s_waitcnt lgkmcnt(2)
	v_mfma_f32_32x32x16_bf16 v[16:31], v[196:199], v[68:71], v[16:31]
	v_exp_f32_e32 v56, v56
	v_exp_f32_e32 v57, v57
	v_exp_f32_e32 v58, v58
	v_exp_f32_e32 v59, v59
	v_exp_f32_e32 v60, v60
	v_exp_f32_e32 v61, v61
	v_exp_f32_e32 v62, v62
	v_exp_f32_e32 v63, v146
	v_cvt_pk_bf16_f32 v68, v56, v57
	v_cvt_pk_bf16_f32 v69, v58, v59
	v_cvt_pk_bf16_f32 v70, v60, v61
	v_cvt_pk_bf16_f32 v71, v62, v63
	s_andn2_b64 vcc, exec, s[12:13]
	s_waitcnt lgkmcnt(1)
	v_mfma_f32_32x32x16_bf16 v[32:47], v[200:203], v[68:71], v[32:47]
	s_waitcnt lgkmcnt(0)
	v_mfma_f32_32x32x16_bf16 v[16:31], v[204:207], v[68:71], v[16:31]
	s_cbranch_vccnz .LBB0_520
	s_bitcmp1_b32 s41, 0
	s_cselect_b32 s4, 0x8a00, 0
	s_add_i32 s4, s4, 0
	v_add3_u32 v0, s4, v131, v132
	s_waitcnt vmcnt(3)
	ds_write_b128 v0, v[80:83]
	v_add_u32_e32 v0, s4, v133
	v_add3_u32 v0, v0, v134, s17
	s_waitcnt vmcnt(2)
	ds_write2_b64 v0, v[84:85], v[86:87] offset1:1
	v_add3_u32 v0, s4, v135, v136
	s_waitcnt vmcnt(1)
	ds_write_b128 v0, v[104:107]
	v_add_u32_e32 v0, s4, v137
	v_add3_u32 v0, v0, v138, s17
	s_waitcnt vmcnt(0)
	ds_write2_b64 v0, v[108:109], v[110:111] offset1:1

; __global__ void __launch_bounds__(512, 2) fwd_kernel(Params p) {
;     ...
;         for (int rep_s = 0; rep_s < REP_SWA; ++rep_s)
;         for (int item = (int)blockIdx.x; item < SWA_A; item += G_) {
;             if (item < 1024) attn_item<64, 1, 2>(BIG, NIN0, 2048, 2560, VT, OC, 512, p.in[13], lds, item, tid, lane, wave);
;             else attn_item<64, 2, 2>(BIG, NIN0, 2048, 2560, VT, OC, 512, p.in[13], lds, item - 1024, tid, lane, wave);
;         }
.LBB0_522:
	v_mov_b32_e32 v10, v126
	v_mov_b32_e32 v11, v127
	v_mov_b32_e32 v13, v128
	v_mov_b32_e32 v0, v139
	s_branch .LBB0_488
	s_nop 0
	s_nop 0
	s_nop 0
	s_nop 0
	s_nop 0
	s_nop 0
	s_nop 0

; #define LAS __attribute__((address_space(3)))
; DI int crow(int i, int h) { return (i & 3) + 8 * (i >> 2) + 4 * h; }
; DI void mlstm_x3(const Params& p, LAS unsigned char* lds, int item, int tid_in, int lane_in, int wave) {
;     ...
;     __syncthreads();
;     LAS float* Hs = (LAS float*)(lds + Y_C);
; #pragma unroll
;     for (int i = 0; i < 16; ++i) { const int trow = 32 * ti + crow(i, h);
;         const float rs = rsqrtf((s_ssq[trow * 2] + s_ssq[trow * 2 + 1]) * (1.f / 128.f) + EPS);
;         Hs[trow * 132 + 32 * (2 * eh) + r_] = hs[0][i] * rs; Hs[trow * 132 + 32 * (2 * eh + 1) + r_] = hs[1][i] * rs; }
;     __syncthreads();
;     const float* gn = p.in[10] + head * 128;
;     const int c8o = (tid & 15) * 8;
;     const f32x4 g0 = *(const f32x4*)(gn + c8o), g1 = *(const f32x4*)(gn + c8o + 4);
;     u32x4 oav[4];
; #pragma unroll
;     for (int it = 0; it < 4; ++it) { const int row = (tid + 512 * it) >> 4; oav[it] = *(const u32x4*)(QKV + (size_t)(base + row) * NIN0 + 1536 + head * 128 + c8o); }
.LBB0_686:
	s_or_b64 exec, exec, s[4:5]
	v_readlane_b32 s100, v253, 33
	v_readlane_b32 s101, v253, 34
	v_lshlrev_b32_e32 v100, 2, v172
	v_add_u32_e32 v102, s7, v172
	s_lshl_b32 s98, s7, 2
	s_add_u32 s100, s100, s98
	s_addc_u32 s101, s101, 0
	v_lshlrev_b32_e32 v102, 1, v102
	v_mov_b32_e32 v103, 0
	v_mov_b64_e32 v[98:99], s[10:11]
	global_load_dwordx4 v[104:107], v100, s[100:101] offset:16
	global_load_dwordx4 v[108:111], v100, s[100:101]
	v_add_u32_e32 v101, s79, v171
	v_mad_i64_i32 v[96:97], s[98:99], v101, s16, v[98:99]
	v_lshl_add_u64 v[96:97], v[96:97], 0, v[102:103]
	global_load_dwordx4 v[112:115], v[96:97], off offset:3072
	v_add_u32_e32 v101, s79, v170
	v_mad_i64_i32 v[96:97], s[98:99], v101, s16, v[98:99]
	v_lshl_add_u64 v[96:97], v[96:97], 0, v[102:103]
	global_load_dwordx4 v[116:119], v[96:97], off offset:3072
	v_add_u32_e32 v101, s79, v169
	v_mad_i64_i32 v[96:97], s[98:99], v101, s16, v[98:99]
	v_lshl_add_u64 v[96:97], v[96:97], 0, v[102:103]
	global_load_dwordx4 v[120:123], v[96:97], off offset:3072
	v_add_u32_e32 v101, s79, v168
	v_mad_i64_i32 v[96:97], s[98:99], v101, s16, v[98:99]
	v_lshl_add_u64 v[96:97], v[96:97], 0, v[102:103]
	global_load_dwordx4 v[124:127], v[96:97], off offset:3072
	v_readlane_b32 s4, v254, 31
	v_readlane_b32 s5, v254, 32
	s_add_u32 s4, s4, s12
	s_addc_u32 s5, s5, s13
	s_add_i32 s8, 0, 0x23b30
	s_waitcnt lgkmcnt(0)
	s_barrier
	v_lshl_add_u32 v46, v188, 3, s8
	ds_read_b64 v[64:65], v46
	v_lshl_add_u32 v47, v187, 3, s8
	ds_read_b64 v[66:67], v47
	v_lshl_add_u32 v50, v186, 3, s8
	ds_read_b64 v[68:69], v50
	v_lshl_add_u32 v51, v185, 3, s8
	ds_read_b64 v[70:71], v51
	v_lshl_add_u32 v52, v184, 3, s8
	ds_read_b64 v[72:73], v52
	v_lshl_add_u32 v53, v183, 3, s8
	ds_read_b64 v[74:75], v53
	v_lshl_add_u32 v54, v182, 3, s8
	ds_read_b64 v[76:77], v54
	v_lshl_add_u32 v55, v181, 3, s8
	ds_read_b64 v[78:79], v55
	v_lshlrev_b32_e32 v4, 2, v173
	v_readlane_b32 s36, v253, 29
	v_readlane_b32 s40, v253, 33
	s_waitcnt lgkmcnt(7)
	v_add_f32_e32 v1, v64, v65
	v_fmamk_f32 v1, v1, 0x3c000000, v165
	v_cmp_gt_f32_e32 vcc, s62, v1
	v_mul_f32_e32 v2, 0x4b800000, v1
	v_readlane_b32 s41, v253, 34
	v_cndmask_b32_e32 v1, v1, v2, vcc
	v_rsq_f32_e32 v1, v1
	v_lshlrev_b32_e32 v20, 2, v172
	v_add_u32_e32 v36, s79, v171
	v_mov_b64_e32 v[8:9], s[10:11]
	v_mul_f32_e32 v2, 0x45800000, v1
	v_cndmask_b32_e32 v2, v1, v2, vcc
	v_mul_lo_u32 v1, v188, s63
	v_mul_f32_e32 v3, v158, v2
	v_add3_u32 v1, s76, v1, v4
	v_mul_f32_e32 v2, v160, v2
	ds_write2_b32 v1, v3, v2 offset1:32
	v_add_u32_e32 v4, 0x400, v1
	v_lshlrev_b32_e32 v132, 1, v172
	v_add_u32_e32 v34, s79, v170
	v_add_u32_e32 v30, s79, v169
	s_waitcnt lgkmcnt(7)
	v_add_f32_e32 v2, v66, v67
	v_fmamk_f32 v2, v2, 0x3c000000, v165
	v_cmp_gt_f32_e32 vcc, s62, v2
	v_mul_f32_e32 v3, 0x4b800000, v2
	v_add_u32_e32 v26, s79, v168
	v_cndmask_b32_e32 v2, v2, v3, vcc
	v_rsq_f32_e32 v2, v2
	v_add_u32_e32 v32, s6, v20
	v_ashrrev_i32_e32 v37, 31, v36
	v_ashrrev_i32_e32 v35, 31, v34
	v_mul_f32_e32 v3, 0x45800000, v2
	v_cndmask_b32_e32 v2, v2, v3, vcc
	v_mul_f32_e32 v3, v159, v2
	v_mul_f32_e32 v2, v161, v2
	ds_write2_b32 v1, v3, v2 offset0:132 offset1:164
	v_ashrrev_i32_e32 v31, 31, v30
	v_ashrrev_i32_e32 v27, 31, v26
	v_readlane_b32 s37, v253, 30
	v_readlane_b32 s38, v253, 31
	s_waitcnt lgkmcnt(7)
	v_add_f32_e32 v2, v68, v69
	v_fmamk_f32 v2, v2, 0x3c000000, v165
	v_cmp_gt_f32_e32 vcc, s62, v2
	v_mul_f32_e32 v3, 0x4b800000, v2
	v_readlane_b32 s39, v253, 32
	v_cndmask_b32_e32 v2, v2, v3, vcc
	v_rsq_f32_e32 v2, v2
	v_readlane_b32 s42, v253, 35
	v_readlane_b32 s43, v253, 36
	v_readlane_b32 s44, v253, 37
	v_mul_f32_e32 v3, 0x45800000, v2
	v_cndmask_b32_e32 v2, v2, v3, vcc
	v_mul_f32_e32 v3, v154, v2
	v_mul_f32_e32 v2, v156, v2
	ds_write2_b32 v4, v3, v2 offset0:8 offset1:40
	v_readlane_b32 s45, v253, 38
	v_readlane_b32 s46, v253, 39
	v_readlane_b32 s47, v253, 40
	v_readlane_b32 s48, v253, 41
	s_waitcnt lgkmcnt(7)
	v_add_f32_e32 v2, v70, v71
	v_fmamk_f32 v2, v2, 0x3c000000, v165
	v_cmp_gt_f32_e32 vcc, s62, v2
	v_mul_f32_e32 v3, 0x4b800000, v2
	v_readlane_b32 s49, v253, 42
	v_cndmask_b32_e32 v2, v2, v3, vcc
	v_rsq_f32_e32 v2, v2
	v_readlane_b32 s50, v253, 43
	v_readlane_b32 s51, v253, 44
	v_mul_f32_e32 v3, 0x45800000, v2
	v_cndmask_b32_e32 v2, v2, v3, vcc
	v_mul_f32_e32 v3, v155, v2
	v_mul_f32_e32 v2, v157, v2
	ds_write2_b32 v4, v3, v2 offset0:140 offset1:172
	v_add_u32_e32 v4, 0x1000, v1
	s_waitcnt lgkmcnt(7)
	v_add_f32_e32 v2, v72, v73
	v_fmamk_f32 v2, v2, 0x3c000000, v165
	v_cmp_gt_f32_e32 vcc, s62, v2
	v_mul_f32_e32 v3, 0x4b800000, v2
	s_nop 0
	v_cndmask_b32_e32 v2, v2, v3, vcc
	v_rsq_f32_e32 v2, v2
	s_nop 0
	v_mul_f32_e32 v3, 0x45800000, v2
	v_cndmask_b32_e32 v2, v2, v3, vcc
	v_mul_f32_e32 v3, v150, v2
	v_mul_f32_e32 v2, v152, v2
	ds_write2_b32 v4, v3, v2 offset0:32 offset1:64
	s_waitcnt lgkmcnt(7)
	v_add_f32_e32 v2, v74, v75
	v_fmamk_f32 v2, v2, 0x3c000000, v165
	v_cmp_gt_f32_e32 vcc, s62, v2
	v_mul_f32_e32 v3, 0x4b800000, v2
	s_nop 0
	v_cndmask_b32_e32 v2, v2, v3, vcc
	v_rsq_f32_e32 v2, v2
	s_nop 0
	v_mul_f32_e32 v3, 0x45800000, v2
	v_cndmask_b32_e32 v2, v2, v3, vcc
	v_mul_f32_e32 v3, v151, v2
	v_mul_f32_e32 v2, v153, v2
	ds_write2_b32 v4, v3, v2 offset0:164 offset1:196
	v_add_u32_e32 v4, 0x1400, v1
	s_waitcnt lgkmcnt(7)
	v_add_f32_e32 v2, v76, v77
	v_fmamk_f32 v2, v2, 0x3c000000, v165
	v_cmp_gt_f32_e32 vcc, s62, v2
	v_mul_f32_e32 v3, 0x4b800000, v2
	s_nop 0
	v_cndmask_b32_e32 v2, v2, v3, vcc
	v_rsq_f32_e32 v2, v2
	s_nop 0
	v_mul_f32_e32 v3, 0x45800000, v2
	v_cndmask_b32_e32 v2, v2, v3, vcc
	v_mul_f32_e32 v3, v146, v2
	v_mul_f32_e32 v2, v148, v2
	ds_write2_b32 v4, v3, v2 offset0:40 offset1:72
	s_waitcnt lgkmcnt(7)
; DI int crow(int i, int h) { return (i & 3) + 8 * (i >> 2) + 4 * h; }
; DI void mlstm_x3(const Params& p, LAS unsigned char* lds, int item, int tid_in, int lane_in, int wave) {
;     ...
; #pragma unroll
;     for (int i = 0; i < 16; ++i) { const int trow = 32 * ti + crow(i, h);
;         const float rs = rsqrtf((s_ssq[trow * 2] + s_ssq[trow * 2 + 1]) * (1.f / 128.f) + EPS);
;         Hs[trow * 132 + 32 * (2 * eh) + r_] = hs[0][i] * rs; Hs[trow * 132 + 32 * (2 * eh + 1) + r_] = hs[1][i] * rs; }
;     __syncthreads();
	v_add_f32_e32 v2, v78, v79
	v_fmamk_f32 v2, v2, 0x3c000000, v165
	v_cmp_gt_f32_e32 vcc, s62, v2
	v_mul_f32_e32 v3, 0x4b800000, v2
	s_nop 0
	v_cndmask_b32_e32 v2, v2, v3, vcc
	v_rsq_f32_e32 v2, v2
	s_nop 0
	v_mul_f32_e32 v3, 0x45800000, v2
	v_cndmask_b32_e32 v2, v2, v3, vcc
	v_mul_f32_e32 v3, v147, v2
	v_mul_f32_e32 v2, v149, v2
	ds_write2_b32 v4, v3, v2 offset0:172 offset1:204
	v_lshl_add_u32 v46, v180, 3, s8
	ds_read_b64 v[80:81], v46
	v_lshl_add_u32 v47, v179, 3, s8
	ds_read_b64 v[82:83], v47
	v_lshl_add_u32 v50, v178, 3, s8
	ds_read_b64 v[84:85], v50
	v_lshl_add_u32 v51, v177, 3, s8
	ds_read_b64 v[86:87], v51
	v_lshl_add_u32 v52, v176, 3, s8
	ds_read_b64 v[88:89], v52
	v_lshl_add_u32 v53, v175, 3, s8
	ds_read_b64 v[90:91], v53
	v_lshl_add_u32 v54, v174, 3, s8
	ds_read_b64 v[92:93], v54
	v_lshl_add_u32 v55, v189, 3, s8
	ds_read_b64 v[94:95], v55
	v_add_u32_e32 v4, 0x2000, v1
	s_waitcnt lgkmcnt(7)
	v_add_f32_e32 v2, v80, v81
	v_fmamk_f32 v2, v2, 0x3c000000, v165
	v_cmp_gt_f32_e32 vcc, s62, v2
	v_mul_f32_e32 v3, 0x4b800000, v2
	s_nop 0
	v_cndmask_b32_e32 v2, v2, v3, vcc
	v_rsq_f32_e32 v2, v2
	s_nop 0
	v_mul_f32_e32 v3, 0x45800000, v2
	v_cndmask_b32_e32 v2, v2, v3, vcc
	v_mul_f32_e32 v3, v142, v2
	v_mul_f32_e32 v2, v144, v2
	ds_write2_b32 v4, v3, v2 offset0:64 offset1:96
	s_waitcnt lgkmcnt(7)
	v_add_f32_e32 v2, v82, v83
	v_fmamk_f32 v2, v2, 0x3c000000, v165
	v_cmp_gt_f32_e32 vcc, s62, v2
	v_mul_f32_e32 v3, 0x4b800000, v2
	s_nop 0
	v_cndmask_b32_e32 v2, v2, v3, vcc
	v_rsq_f32_e32 v2, v2
	s_nop 0
	v_mul_f32_e32 v3, 0x45800000, v2
	v_cndmask_b32_e32 v2, v2, v3, vcc
	v_mul_f32_e32 v3, v143, v2
	v_mul_f32_e32 v2, v145, v2
	ds_write2_b32 v4, v3, v2 offset0:196 offset1:228
	v_add_u32_e32 v4, 0x2400, v1
	s_waitcnt lgkmcnt(7)
	v_add_f32_e32 v2, v84, v85
	v_fmamk_f32 v2, v2, 0x3c000000, v165
	v_cmp_gt_f32_e32 vcc, s62, v2
	v_mul_f32_e32 v3, 0x4b800000, v2
	s_nop 0
	v_cndmask_b32_e32 v2, v2, v3, vcc
	v_rsq_f32_e32 v2, v2
	s_nop 0
	v_mul_f32_e32 v3, 0x45800000, v2
	v_cndmask_b32_e32 v2, v2, v3, vcc
	v_mul_f32_e32 v3, v138, v2
	v_mul_f32_e32 v2, v140, v2
	ds_write2_b32 v4, v3, v2 offset0:72 offset1:104
	s_waitcnt lgkmcnt(7)
	v_add_f32_e32 v2, v86, v87
	v_fmamk_f32 v2, v2, 0x3c000000, v165
	v_cmp_gt_f32_e32 vcc, s62, v2
	v_mul_f32_e32 v3, 0x4b800000, v2
	s_nop 0
	v_cndmask_b32_e32 v2, v2, v3, vcc
	v_rsq_f32_e32 v2, v2
	s_nop 0
	v_mul_f32_e32 v3, 0x45800000, v2
	v_cndmask_b32_e32 v2, v2, v3, vcc
	v_mul_f32_e32 v3, v139, v2
	v_mul_f32_e32 v2, v141, v2
	ds_write2_b32 v4, v3, v2 offset0:204 offset1:236
	v_add_u32_e32 v4, 0x3000, v1
	s_waitcnt lgkmcnt(7)
	v_add_f32_e32 v2, v88, v89
	v_fmamk_f32 v2, v2, 0x3c000000, v165
	v_cmp_gt_f32_e32 vcc, s62, v2
	v_mul_f32_e32 v3, 0x4b800000, v2
	s_nop 0
	v_cndmask_b32_e32 v2, v2, v3, vcc
	v_rsq_f32_e32 v2, v2
	s_nop 0
	v_mul_f32_e32 v3, 0x45800000, v2
	v_cndmask_b32_e32 v2, v2, v3, vcc
	v_mul_f32_e32 v3, v134, v2
	v_mul_f32_e32 v2, v136, v2
	ds_write2_b32 v4, v3, v2 offset0:96 offset1:128
	v_add_u32_e32 v4, 0x3200, v1
	s_waitcnt lgkmcnt(7)
	v_add_f32_e32 v2, v90, v91
	v_fmamk_f32 v2, v2, 0x3c000000, v165
	v_cmp_gt_f32_e32 vcc, s62, v2
	v_mul_f32_e32 v3, 0x4b800000, v2
	s_nop 0
	v_cndmask_b32_e32 v2, v2, v3, vcc
	v_rsq_f32_e32 v2, v2
	s_nop 0
	v_mul_f32_e32 v3, 0x45800000, v2
	v_cndmask_b32_e32 v2, v2, v3, vcc
	v_mul_f32_e32 v3, v135, v2
	v_mul_f32_e32 v2, v137, v2
	ds_write2_b32 v4, v3, v2 offset0:100 offset1:132
	v_add_u32_e32 v4, 0x3400, v1
	s_lshl_b32 s8, s7, 2
	s_add_u32 s8, s40, s8
	v_add_u32_e32 v1, 0x3600, v1
	s_waitcnt lgkmcnt(7)
	v_add_f32_e32 v2, v92, v93
	v_fmamk_f32 v2, v2, 0x3c000000, v165
	v_cmp_gt_f32_e32 vcc, s62, v2
	v_mul_f32_e32 v3, 0x4b800000, v2
	s_addc_u32 s9, s41, 0
	v_cndmask_b32_e32 v2, v2, v3, vcc
	v_rsq_f32_e32 v2, v2
	s_lshl_b32 s18, s7, 1
	s_add_u32 s4, s4, s18
	s_addc_u32 s5, s5, 0
	v_mul_f32_e32 v3, 0x45800000, v2
	v_cndmask_b32_e32 v2, v2, v3, vcc
	v_mul_f32_e32 v3, v130, v2
	v_mul_f32_e32 v2, v128, v2
	ds_write2_b32 v4, v3, v2 offset0:104 offset1:136
	v_lshl_add_u64 v[28:29], s[4:5], 0, v[132:133]
	s_add_i32 s2, s2, s30
	s_cmpk_gt_i32 s2, 0x43f
	s_waitcnt lgkmcnt(7)
	v_add_f32_e32 v0, v94, v95
	v_fmamk_f32 v0, v0, 0x3c000000, v165
	v_cmp_gt_f32_e32 vcc, s62, v0
	v_mul_f32_e32 v2, 0x4b800000, v0
	s_nop 0
	v_cndmask_b32_e32 v0, v0, v2, vcc
	v_rsq_f32_e32 v0, v0
	s_nop 0
	v_mul_f32_e32 v2, 0x45800000, v0
	v_cndmask_b32_e32 v0, v0, v2, vcc
	v_mul_f32_e32 v2, v131, v0
	v_mul_f32_e32 v0, v129, v0
	ds_write2_b32 v1, v2, v0 offset0:108 offset1:140
	s_waitcnt lgkmcnt(0)
	s_barrier
; #define LAS __attribute__((address_space(3)))
; DI unsigned cvtpk(float lo, float hi) { f32x2 v = {lo, hi}; bf16x2_t b = __builtin_convertvector(v, bf16x2_t); return __builtin_bit_cast(unsigned, b); }
; DI void mlstm_x3(const Params& p, LAS unsigned char* lds, int item, int tid_in, int lane_in, int wave) {
;     ...
;     const float* gn = p.in[10] + head * 128;
;     const int c8o = (tid & 15) * 8;
;     const f32x4 g0 = *(const f32x4*)(gn + c8o), g1 = *(const f32x4*)(gn + c8o + 4);
;     u32x4 oav[4];
; #pragma unroll
;     for (int it = 0; it < 4; ++it) { const int row = (tid + 512 * it) >> 4; oav[it] = *(const u32x4*)(QKV + (size_t)(base + row) * NIN0 + 1536 + head * 128 + c8o); }
;     asm volatile("" ::: "memory");
; #pragma unroll
;     for (int it = 0; it < 4; ++it) { const int row = (tid + 512 * it) >> 4; const size_t grow = base + row; const u32x4 oa = oav[it];
;         const f32x4 v0 = *(const LAS f32x4*)(Hs + row * 132 + c8o), v1 = *(const LAS f32x4*)(Hs + row * 132 + c8o + 4);
;         float o[8]; o[0] = __uint_as_float(oa.x << 16); o[1] = __uint_as_float(oa.x & 0xffff0000u); o[2] = __uint_as_float(oa.y << 16); o[3] = __uint_as_float(oa.y & 0xffff0000u);
;         o[4] = __uint_as_float(oa.z << 16); o[5] = __uint_as_float(oa.z & 0xffff0000u); o[6] = __uint_as_float(oa.w << 16); o[7] = __uint_as_float(oa.w & 0xffff0000u);
;         u32x4 w;
;         w.x = cvtpk(v0[0] * g0[0] / (1.f + __expf(-o[0])), v0[1] * g0[1] / (1.f + __expf(-o[1]))); w.y = cvtpk(v0[2] * g0[2] / (1.f + __expf(-o[2])), v0[3] * g0[3] / (1.f + __expf(-o[3])));
;         w.z = cvtpk(v1[0] * g1[0] / (1.f + __expf(-o[4])), v1[1] * g1[1] / (1.f + __expf(-o[5]))); w.w = cvtpk(v1[2] * g1[2] / (1.f + __expf(-o[6])), v1[3] * g1[3] / (1.f + __expf(-o[7])));
;         *(u32x4*)(OC + grow * DM + head * 128 + c8o) = w; }
	v_mad_u64_u32 v[20:21], s[4:5], v171, s63, v[32:33]
	s_waitcnt vmcnt(0)
	v_mov_b32_e32 v0, v104
	v_mov_b32_e32 v1, v105
	v_mov_b32_e32 v2, v106
	v_mov_b32_e32 v3, v107
	v_mov_b32_e32 v4, v108
	v_mov_b32_e32 v5, v109
	v_mov_b32_e32 v6, v110
	v_mov_b32_e32 v7, v111
	v_mov_b32_e32 v38, v112
	v_mov_b32_e32 v39, v113
	v_mov_b32_e32 v40, v114
	v_mov_b32_e32 v41, v115
	v_mov_b32_e32 v16, v116
	v_mov_b32_e32 v17, v117
	v_mov_b32_e32 v18, v118
	v_mov_b32_e32 v19, v119
	v_mov_b32_e32 v12, v120
	v_mov_b32_e32 v13, v121
	v_mov_b32_e32 v14, v122
	v_mov_b32_e32 v15, v123
	v_mov_b32_e32 v8, v124
	v_mov_b32_e32 v9, v125
	v_mov_b32_e32 v10, v126
	v_mov_b32_e32 v11, v127
	ds_read_b128 v[42:45], v20
	ds_read_b128 v[22:25], v20 offset:16
	s_waitcnt vmcnt(5) lgkmcnt(0)
	v_pk_mul_f32 v[22:23], v[0:1], v[22:23]
	s_waitcnt vmcnt(4)
	v_pk_mul_f32 v[42:43], v[4:5], v[42:43]
	v_pk_mul_f32 v[24:25], v[2:3], v[24:25]
	s_waitcnt vmcnt(3)
	v_lshlrev_b32_e32 v20, 16, v38
	v_and_b32_e32 v21, 0xffff0000, v38
	v_mul_f32_e32 v20, 0xbfb8aa3b, v20
	v_mul_f32_e32 v21, 0xbfb8aa3b, v21
	v_exp_f32_e32 v20, v20
	v_exp_f32_e32 v21, v21
	v_lshlrev_b32_e32 v48, 16, v40
	v_and_b32_e32 v49, 0xffff0000, v40
	v_lshlrev_b32_e32 v40, 16, v41
	v_pk_add_f32 v[20:21], v[20:21], 1.0 op_sel_hi:[1,0]
	v_and_b32_e32 v33, 0xffff0000, v41
	v_div_scale_f32 v41, s[4:5], v21, v21, v43
	v_lshlrev_b32_e32 v46, 16, v39
	v_and_b32_e32 v47, 0xffff0000, v39
	v_pk_mul_f32 v[38:39], v[6:7], v[44:45]
	v_rcp_f32_e32 v44, v41
	s_nop 0
	v_fma_f32 v45, -v41, v44, 1.0
	v_fmac_f32_e32 v44, v45, v44
	v_div_scale_f32 v45, vcc, v43, v21, v43
	v_mul_f32_e32 v50, v45, v44
	v_fma_f32 v51, -v41, v50, v45
	v_fmac_f32_e32 v50, v51, v44
	v_fma_f32 v41, -v41, v50, v45
	v_div_fmas_f32 v41, v41, v44, v50
	v_div_fixup_f32 v21, v41, v21, v43
	v_div_scale_f32 v41, s[4:5], v20, v20, v42
	v_rcp_f32_e32 v43, v41
	s_nop 0
	v_fma_f32 v44, -v41, v43, 1.0
	v_fmac_f32_e32 v43, v44, v43
	v_div_scale_f32 v44, vcc, v42, v20, v42
	v_mul_f32_e32 v45, v44, v43
	v_fma_f32 v50, -v41, v45, v44
	v_fmac_f32_e32 v45, v50, v43
	v_fma_f32 v41, -v41, v45, v44
	v_div_fmas_f32 v41, v41, v43, v45
	v_div_fixup_f32 v20, v41, v20, v42
	v_cvt_pk_bf16_f32 v20, v20, v21
	v_mul_f32_e32 v21, 0xbfb8aa3b, v46
	v_exp_f32_e32 v42, v21
	v_mul_f32_e32 v21, 0xbfb8aa3b, v47
	v_exp_f32_e32 v43, v21
	s_nop 0
	v_pk_add_f32 v[42:43], v[42:43], 1.0 op_sel_hi:[1,0]
	s_nop 0
	v_div_scale_f32 v21, s[4:5], v43, v43, v39
	v_rcp_f32_e32 v41, v21
	s_nop 0
	v_fma_f32 v44, -v21, v41, 1.0
	v_fmac_f32_e32 v41, v44, v41
	v_div_scale_f32 v44, vcc, v39, v43, v39
	v_mul_f32_e32 v45, v44, v41
	v_fma_f32 v46, -v21, v45, v44
	v_fmac_f32_e32 v45, v46, v41
	v_fma_f32 v21, -v21, v45, v44
	v_div_fmas_f32 v21, v21, v41, v45
	v_div_fixup_f32 v21, v21, v43, v39
	v_div_scale_f32 v39, s[4:5], v42, v42, v38
	v_rcp_f32_e32 v41, v39
	s_nop 0
	v_fma_f32 v43, -v39, v41, 1.0
	v_fmac_f32_e32 v41, v43, v41
	v_div_scale_f32 v43, vcc, v38, v42, v38
	v_mul_f32_e32 v44, v43, v41
	v_fma_f32 v45, -v39, v44, v43
	v_fmac_f32_e32 v44, v45, v41
	v_fma_f32 v39, -v39, v44, v43
	v_div_fmas_f32 v39, v39, v41, v44
	v_div_fixup_f32 v38, v39, v42, v38
	v_cvt_pk_bf16_f32 v21, v38, v21
	v_mul_f32_e32 v38, 0xbfb8aa3b, v48
	v_mul_f32_e32 v39, 0xbfb8aa3b, v49
	v_exp_f32_e32 v38, v38
	v_exp_f32_e32 v39, v39
	s_nop 0
	v_pk_add_f32 v[38:39], v[38:39], 1.0 op_sel_hi:[1,0]
	s_nop 0
	v_div_scale_f32 v41, s[4:5], v39, v39, v23
	v_rcp_f32_e32 v42, v41
	s_nop 0
	v_fma_f32 v43, -v41, v42, 1.0
	v_fmac_f32_e32 v42, v43, v42
	v_div_scale_f32 v43, vcc, v23, v39, v23
	v_mul_f32_e32 v44, v43, v42
	v_fma_f32 v45, -v41, v44, v43
	v_fmac_f32_e32 v44, v45, v42
	v_fma_f32 v41, -v41, v44, v43
	v_div_fmas_f32 v41, v41, v42, v44
	v_div_fixup_f32 v23, v41, v39, v23
	v_div_scale_f32 v39, s[4:5], v38, v38, v22
	v_rcp_f32_e32 v41, v39
	s_nop 0
	v_fma_f32 v42, -v39, v41, 1.0
	v_fmac_f32_e32 v41, v42, v41
	v_div_scale_f32 v42, vcc, v22, v38, v22
	v_mul_f32_e32 v43, v42, v41
	v_fma_f32 v44, -v39, v43, v42
	v_fmac_f32_e32 v43, v44, v41
	v_fma_f32 v39, -v39, v43, v42
	v_div_fmas_f32 v39, v39, v41, v43
	v_div_fixup_f32 v22, v39, v38, v22
	v_cvt_pk_bf16_f32 v22, v22, v23
	v_mul_f32_e32 v23, 0xbfb8aa3b, v40
	v_exp_f32_e32 v38, v23
	v_mul_f32_e32 v23, 0xbfb8aa3b, v33
	v_exp_f32_e32 v39, v23
	s_waitcnt vmcnt(2)
	v_lshlrev_b32_e32 v43, 16, v19
	v_and_b32_e32 v44, 0xffff0000, v19
	v_pk_add_f32 v[38:39], v[38:39], 1.0 op_sel_hi:[1,0]
	s_nop 0
	v_div_scale_f32 v23, s[4:5], v39, v39, v25
	v_rcp_f32_e32 v33, v23
	s_nop 0
	v_fma_f32 v40, -v23, v33, 1.0
	v_fmac_f32_e32 v33, v40, v33
	v_div_scale_f32 v40, vcc, v25, v39, v25
	v_mul_f32_e32 v41, v40, v33
	v_fma_f32 v42, -v23, v41, v40
	v_fmac_f32_e32 v41, v42, v33
	v_fma_f32 v23, -v23, v41, v40
	v_div_fmas_f32 v23, v23, v33, v41
	v_div_fixup_f32 v23, v23, v39, v25
	v_div_scale_f32 v25, s[4:5], v38, v38, v24
	v_rcp_f32_e32 v33, v25
	v_and_b32_e32 v42, 0xffff0000, v18
	v_fma_f32 v39, -v25, v33, 1.0
	v_fmac_f32_e32 v33, v39, v33
	v_div_scale_f32 v39, vcc, v24, v38, v24
	v_mul_f32_e32 v40, v39, v33
	v_fma_f32 v41, -v25, v40, v39
	v_fmac_f32_e32 v40, v41, v33
	v_fma_f32 v25, -v25, v40, v39
	v_div_fmas_f32 v25, v25, v33, v40
	v_div_fixup_f32 v24, v25, v38, v24
	v_cvt_pk_bf16_f32 v23, v24, v23
	v_lshlrev_b64 v[24:25], 11, v[36:37]
	v_lshl_add_u64 v[24:25], v[28:29], 0, v[24:25]
	global_store_dwordx4 v[24:25], v[20:23], off
	v_lshlrev_b32_e32 v24, 16, v16
	v_and_b32_e32 v25, 0xffff0000, v16
	v_mad_u64_u32 v[20:21], s[4:5], v170, s63, v[32:33]
	v_lshlrev_b32_e32 v33, 16, v17
	v_and_b32_e32 v40, 0xffff0000, v17
	v_mul_f32_e32 v16, 0xbfb8aa3b, v24
	v_mul_f32_e32 v17, 0xbfb8aa3b, v25
	ds_read_b128 v[36:39], v20
	ds_read_b128 v[20:23], v20 offset:16
	v_exp_f32_e32 v16, v16
	v_exp_f32_e32 v17, v17
	v_lshlrev_b32_e32 v41, 16, v18
	s_waitcnt lgkmcnt(1)
; #define LAS __attribute__((address_space(3)))
; DI unsigned cvtpk(float lo, float hi) { f32x2 v = {lo, hi}; bf16x2_t b = __builtin_convertvector(v, bf16x2_t); return __builtin_bit_cast(unsigned, b); }
; DI void mlstm_x3(const Params& p, LAS unsigned char* lds, int item, int tid_in, int lane_in, int wave) {
;     ...
;     for (int it = 0; it < 4; ++it) { const int row = (tid + 512 * it) >> 4; const size_t grow = base + row; const u32x4 oa = oav[it];
;         const f32x4 v0 = *(const LAS f32x4*)(Hs + row * 132 + c8o), v1 = *(const LAS f32x4*)(Hs + row * 132 + c8o + 4);
;         float o[8]; o[0] = __uint_as_float(oa.x << 16); o[1] = __uint_as_float(oa.x & 0xffff0000u); o[2] = __uint_as_float(oa.y << 16); o[3] = __uint_as_float(oa.y & 0xffff0000u);
;         o[4] = __uint_as_float(oa.z << 16); o[5] = __uint_as_float(oa.z & 0xffff0000u); o[6] = __uint_as_float(oa.w << 16); o[7] = __uint_as_float(oa.w & 0xffff0000u);
;         u32x4 w;
;         w.x = cvtpk(v0[0] * g0[0] / (1.f + __expf(-o[0])), v0[1] * g0[1] / (1.f + __expf(-o[1]))); w.y = cvtpk(v0[2] * g0[2] / (1.f + __expf(-o[2])), v0[3] * g0[3] / (1.f + __expf(-o[3])));
;         w.z = cvtpk(v1[0] * g1[0] / (1.f + __expf(-o[4])), v1[1] * g1[1] / (1.f + __expf(-o[5]))); w.w = cvtpk(v1[2] * g1[2] / (1.f + __expf(-o[6])), v1[3] * g1[3] / (1.f + __expf(-o[7])));
;         *(u32x4*)(OC + grow * DM + head * 128 + c8o) = w; }
	v_pk_mul_f32 v[24:25], v[4:5], v[36:37]
	v_pk_mul_f32 v[18:19], v[6:7], v[38:39]
	v_pk_add_f32 v[16:17], v[16:17], 1.0 op_sel_hi:[1,0]
	s_waitcnt lgkmcnt(0)
	v_pk_mul_f32 v[20:21], v[0:1], v[20:21]
	v_div_scale_f32 v36, s[4:5], v17, v17, v25
	v_rcp_f32_e32 v37, v36
	v_pk_mul_f32 v[22:23], v[2:3], v[22:23]
	v_fma_f32 v38, -v36, v37, 1.0
	v_fmac_f32_e32 v37, v38, v37
	v_div_scale_f32 v38, vcc, v25, v17, v25
	v_mul_f32_e32 v39, v38, v37
	v_fma_f32 v45, -v36, v39, v38
	v_fmac_f32_e32 v39, v45, v37
	v_fma_f32 v36, -v36, v39, v38
	v_div_fmas_f32 v36, v36, v37, v39
	v_div_fixup_f32 v17, v36, v17, v25
	v_div_scale_f32 v25, s[4:5], v16, v16, v24
	v_rcp_f32_e32 v36, v25
	s_nop 0
	v_fma_f32 v37, -v25, v36, 1.0
	v_fmac_f32_e32 v36, v37, v36
	v_div_scale_f32 v37, vcc, v24, v16, v24
	v_mul_f32_e32 v38, v37, v36
	v_fma_f32 v39, -v25, v38, v37
	v_fmac_f32_e32 v38, v39, v36
	v_fma_f32 v25, -v25, v38, v37
	v_div_fmas_f32 v25, v25, v36, v38
	v_div_fixup_f32 v16, v25, v16, v24
	v_cvt_pk_bf16_f32 v16, v16, v17
	v_mul_f32_e32 v17, 0xbfb8aa3b, v33
	v_exp_f32_e32 v24, v17
	v_mul_f32_e32 v17, 0xbfb8aa3b, v40
	v_exp_f32_e32 v25, v17
	s_nop 0
	v_pk_add_f32 v[24:25], v[24:25], 1.0 op_sel_hi:[1,0]
	s_nop 0
	v_div_scale_f32 v17, s[4:5], v25, v25, v19
	v_rcp_f32_e32 v33, v17
	s_nop 0
	v_fma_f32 v36, -v17, v33, 1.0
	v_fmac_f32_e32 v33, v36, v33
	v_div_scale_f32 v36, vcc, v19, v25, v19
	v_mul_f32_e32 v37, v36, v33
	v_fma_f32 v38, -v17, v37, v36
	v_fmac_f32_e32 v37, v38, v33
	v_fma_f32 v17, -v17, v37, v36
	v_div_fmas_f32 v17, v17, v33, v37
	v_div_fixup_f32 v17, v17, v25, v19
	v_div_scale_f32 v19, s[4:5], v24, v24, v18
	v_rcp_f32_e32 v25, v19
	s_waitcnt vmcnt(2)
	v_and_b32_e32 v38, 0xffff0000, v15
	v_fma_f32 v33, -v19, v25, 1.0
	v_fmac_f32_e32 v25, v33, v25
	v_div_scale_f32 v33, vcc, v18, v24, v18
	v_mul_f32_e32 v36, v33, v25
	v_fma_f32 v37, -v19, v36, v33
	v_fmac_f32_e32 v36, v37, v25
	v_fma_f32 v19, -v19, v36, v33
	v_div_fmas_f32 v19, v19, v25, v36
	v_div_fixup_f32 v18, v19, v24, v18
	v_cvt_pk_bf16_f32 v17, v18, v17
	v_mul_f32_e32 v18, 0xbfb8aa3b, v41
	v_mul_f32_e32 v19, 0xbfb8aa3b, v42
	v_exp_f32_e32 v18, v18
	v_exp_f32_e32 v19, v19
	s_nop 0
	v_pk_add_f32 v[18:19], v[18:19], 1.0 op_sel_hi:[1,0]
	s_nop 0
	v_div_scale_f32 v24, s[4:5], v19, v19, v21
	v_rcp_f32_e32 v25, v24
	s_nop 0
	v_fma_f32 v33, -v24, v25, 1.0
	v_fmac_f32_e32 v25, v33, v25
	v_div_scale_f32 v33, vcc, v21, v19, v21
	v_mul_f32_e32 v36, v33, v25
	v_fma_f32 v37, -v24, v36, v33
	v_fmac_f32_e32 v36, v37, v25
	v_fma_f32 v24, -v24, v36, v33
	v_div_fmas_f32 v24, v24, v25, v36
	v_div_fixup_f32 v19, v24, v19, v21
	v_div_scale_f32 v21, s[4:5], v18, v18, v20
	v_rcp_f32_e32 v24, v21
	v_lshlrev_b32_e32 v37, 16, v15
	v_fma_f32 v25, -v21, v24, 1.0
	v_fmac_f32_e32 v24, v25, v24
	v_div_scale_f32 v25, vcc, v20, v18, v20
	v_mul_f32_e32 v33, v25, v24
	v_fma_f32 v36, -v21, v33, v25
	v_fmac_f32_e32 v33, v36, v24
	v_fma_f32 v21, -v21, v33, v25
	v_div_fmas_f32 v21, v21, v24, v33
	v_div_fixup_f32 v18, v21, v18, v20
	v_cvt_pk_bf16_f32 v18, v18, v19
	v_mul_f32_e32 v19, 0xbfb8aa3b, v43
	v_exp_f32_e32 v20, v19
	v_mul_f32_e32 v19, 0xbfb8aa3b, v44
	v_exp_f32_e32 v21, v19
	s_nop 0
	v_pk_add_f32 v[20:21], v[20:21], 1.0 op_sel_hi:[1,0]
	s_nop 0
	v_div_scale_f32 v19, s[4:5], v21, v21, v23
	v_rcp_f32_e32 v24, v19
	s_nop 0
	v_fma_f32 v25, -v19, v24, 1.0
	v_fmac_f32_e32 v24, v25, v24
	v_div_scale_f32 v25, vcc, v23, v21, v23
	v_mul_f32_e32 v33, v25, v24
	v_fma_f32 v36, -v19, v33, v25
	v_fmac_f32_e32 v33, v36, v24
	v_fma_f32 v19, -v19, v33, v25
	v_div_fmas_f32 v19, v19, v24, v33
	v_div_fixup_f32 v19, v19, v21, v23
	v_div_scale_f32 v21, s[4:5], v20, v20, v22
	v_rcp_f32_e32 v23, v21
	v_and_b32_e32 v36, 0xffff0000, v14
	v_fma_f32 v24, -v21, v23, 1.0
	v_fmac_f32_e32 v23, v24, v23
	v_div_scale_f32 v24, vcc, v22, v20, v22
	v_mul_f32_e32 v25, v24, v23
	v_fma_f32 v33, -v21, v25, v24
	v_fmac_f32_e32 v25, v33, v23
	v_fma_f32 v21, -v21, v25, v24
	v_div_fmas_f32 v21, v21, v23, v25
	v_div_fixup_f32 v20, v21, v20, v22
	v_cvt_pk_bf16_f32 v19, v20, v19
	v_lshlrev_b64 v[20:21], 11, v[34:35]
	v_lshl_add_u64 v[20:21], v[28:29], 0, v[20:21]
	v_lshlrev_b32_e32 v24, 16, v12
	v_and_b32_e32 v25, 0xffff0000, v12
	global_store_dwordx4 v[20:21], v[16:19], off
	v_and_b32_e32 v34, 0xffff0000, v13
	v_mul_f32_e32 v12, 0xbfb8aa3b, v24
	v_mad_u64_u32 v[16:17], s[4:5], v169, s63, v[32:33]
	v_lshlrev_b32_e32 v33, 16, v13
	v_mul_f32_e32 v13, 0xbfb8aa3b, v25
	ds_read_b128 v[20:23], v16
	ds_read_b128 v[16:19], v16 offset:16
	v_exp_f32_e32 v12, v12
	v_exp_f32_e32 v13, v13
	v_lshlrev_b32_e32 v35, 16, v14
	s_waitcnt lgkmcnt(1)
	v_pk_mul_f32 v[20:21], v[4:5], v[20:21]
	v_pk_mul_f32 v[14:15], v[6:7], v[22:23]
	v_pk_add_f32 v[12:13], v[12:13], 1.0 op_sel_hi:[1,0]
	s_waitcnt lgkmcnt(0)
	v_pk_mul_f32 v[16:17], v[0:1], v[16:17]
	v_div_scale_f32 v22, s[4:5], v13, v13, v21
	v_rcp_f32_e32 v23, v22
	v_pk_mul_f32 v[18:19], v[2:3], v[18:19]
	v_fma_f32 v24, -v22, v23, 1.0
	v_fmac_f32_e32 v23, v24, v23
	v_div_scale_f32 v24, vcc, v21, v13, v21
	v_mul_f32_e32 v25, v24, v23
	v_fma_f32 v39, -v22, v25, v24
	v_fmac_f32_e32 v25, v39, v23
	v_fma_f32 v22, -v22, v25, v24
	v_div_fmas_f32 v22, v22, v23, v25
	v_div_fixup_f32 v13, v22, v13, v21
	v_div_scale_f32 v21, s[4:5], v12, v12, v20
	v_rcp_f32_e32 v22, v21
	s_nop 0
	v_fma_f32 v23, -v21, v22, 1.0
	v_fmac_f32_e32 v22, v23, v22
	v_div_scale_f32 v23, vcc, v20, v12, v20
	v_mul_f32_e32 v24, v23, v22
	v_fma_f32 v25, -v21, v24, v23
	v_fmac_f32_e32 v24, v25, v22
	v_fma_f32 v21, -v21, v24, v23
	v_div_fmas_f32 v21, v21, v22, v24
	v_div_fixup_f32 v12, v21, v12, v20
	v_cvt_pk_bf16_f32 v12, v12, v13
	v_mul_f32_e32 v13, 0xbfb8aa3b, v33
	v_exp_f32_e32 v20, v13
	v_mul_f32_e32 v13, 0xbfb8aa3b, v34
	v_exp_f32_e32 v21, v13
	s_nop 0
	v_pk_add_f32 v[20:21], v[20:21], 1.0 op_sel_hi:[1,0]
	s_nop 0
	v_div_scale_f32 v13, s[4:5], v21, v21, v15
	v_rcp_f32_e32 v22, v13
	s_nop 0
	v_fma_f32 v23, -v13, v22, 1.0
	v_fmac_f32_e32 v22, v23, v22
	v_div_scale_f32 v23, vcc, v15, v21, v15
	v_mul_f32_e32 v24, v23, v22
	v_fma_f32 v25, -v13, v24, v23
	v_fmac_f32_e32 v24, v25, v22
	v_fma_f32 v13, -v13, v24, v23
	v_div_fmas_f32 v13, v13, v22, v24
	v_div_fixup_f32 v13, v13, v21, v15
	v_div_scale_f32 v15, s[4:5], v20, v20, v14
	v_rcp_f32_e32 v21, v15
	s_waitcnt vmcnt(2)
; #define LAS __attribute__((address_space(3)))
; DI unsigned cvtpk(float lo, float hi) { f32x2 v = {lo, hi}; bf16x2_t b = __builtin_convertvector(v, bf16x2_t); return __builtin_bit_cast(unsigned, b); }
; DI void mlstm_x3(const Params& p, LAS unsigned char* lds, int item, int tid_in, int lane_in, int wave) {
;     ...
;     for (int it = 0; it < 4; ++it) { const int row = (tid + 512 * it) >> 4; const size_t grow = base + row; const u32x4 oa = oav[it];
;         const f32x4 v0 = *(const LAS f32x4*)(Hs + row * 132 + c8o), v1 = *(const LAS f32x4*)(Hs + row * 132 + c8o + 4);
;         float o[8]; o[0] = __uint_as_float(oa.x << 16); o[1] = __uint_as_float(oa.x & 0xffff0000u); o[2] = __uint_as_float(oa.y << 16); o[3] = __uint_as_float(oa.y & 0xffff0000u);
;         o[4] = __uint_as_float(oa.z << 16); o[5] = __uint_as_float(oa.z & 0xffff0000u); o[6] = __uint_as_float(oa.w << 16); o[7] = __uint_as_float(oa.w & 0xffff0000u);
;         u32x4 w;
;         w.x = cvtpk(v0[0] * g0[0] / (1.f + __expf(-o[0])), v0[1] * g0[1] / (1.f + __expf(-o[1]))); w.y = cvtpk(v0[2] * g0[2] / (1.f + __expf(-o[2])), v0[3] * g0[3] / (1.f + __expf(-o[3])));
;         w.z = cvtpk(v1[0] * g1[0] / (1.f + __expf(-o[4])), v1[1] * g1[1] / (1.f + __expf(-o[5]))); w.w = cvtpk(v1[2] * g1[2] / (1.f + __expf(-o[6])), v1[3] * g1[3] / (1.f + __expf(-o[7])));
;         *(u32x4*)(OC + grow * DM + head * 128 + c8o) = w; }
	v_lshlrev_b32_e32 v25, 16, v11
	v_and_b32_e32 v11, 0xffff0000, v11
	v_fma_f32 v22, -v15, v21, 1.0
	v_fmac_f32_e32 v21, v22, v21
	v_div_scale_f32 v22, vcc, v14, v20, v14
	v_mul_f32_e32 v23, v22, v21
	v_fma_f32 v24, -v15, v23, v22
	v_fmac_f32_e32 v23, v24, v21
	v_fma_f32 v15, -v15, v23, v22
	v_div_fmas_f32 v15, v15, v21, v23
	v_div_fixup_f32 v14, v15, v20, v14
	v_cvt_pk_bf16_f32 v13, v14, v13
	v_mul_f32_e32 v14, 0xbfb8aa3b, v35
	v_mul_f32_e32 v15, 0xbfb8aa3b, v36
	v_exp_f32_e32 v14, v14
	v_exp_f32_e32 v15, v15
	s_nop 0
	v_pk_add_f32 v[14:15], v[14:15], 1.0 op_sel_hi:[1,0]
	s_nop 0
	v_div_scale_f32 v20, s[4:5], v15, v15, v17
	v_rcp_f32_e32 v21, v20
	s_nop 0
	v_fma_f32 v22, -v20, v21, 1.0
	v_fmac_f32_e32 v21, v22, v21
	v_div_scale_f32 v22, vcc, v17, v15, v17
	v_mul_f32_e32 v23, v22, v21
	v_fma_f32 v24, -v20, v23, v22
	v_fmac_f32_e32 v23, v24, v21
	v_fma_f32 v20, -v20, v23, v22
	v_div_fmas_f32 v20, v20, v21, v23
	v_div_fixup_f32 v15, v20, v15, v17
	v_div_scale_f32 v17, s[4:5], v14, v14, v16
	v_rcp_f32_e32 v20, v17
	v_lshlrev_b32_e32 v24, 16, v10
	v_and_b32_e32 v10, 0xffff0000, v10
	v_fma_f32 v21, -v17, v20, 1.0
	v_fmac_f32_e32 v20, v21, v20
	v_div_scale_f32 v21, vcc, v16, v14, v16
	v_mul_f32_e32 v22, v21, v20
	v_fma_f32 v23, -v17, v22, v21
	v_fmac_f32_e32 v22, v23, v20
	v_fma_f32 v17, -v17, v22, v21
	v_div_fmas_f32 v17, v17, v20, v22
	v_div_fixup_f32 v14, v17, v14, v16
	v_cvt_pk_bf16_f32 v14, v14, v15
	v_mul_f32_e32 v15, 0xbfb8aa3b, v37
	v_exp_f32_e32 v16, v15
	v_mul_f32_e32 v15, 0xbfb8aa3b, v38
	v_exp_f32_e32 v17, v15
	s_nop 0
	v_pk_add_f32 v[16:17], v[16:17], 1.0 op_sel_hi:[1,0]
	s_nop 0
	v_div_scale_f32 v15, s[4:5], v17, v17, v19
	v_rcp_f32_e32 v20, v15
	s_nop 0
	v_fma_f32 v21, -v15, v20, 1.0
	v_fmac_f32_e32 v20, v21, v20
	v_div_scale_f32 v21, vcc, v19, v17, v19
	v_mul_f32_e32 v22, v21, v20
	v_fma_f32 v23, -v15, v22, v21
	v_fmac_f32_e32 v22, v23, v20
	v_fma_f32 v15, -v15, v22, v21
	v_div_fmas_f32 v15, v15, v20, v22
	v_div_fixup_f32 v15, v15, v17, v19
	v_div_scale_f32 v17, s[4:5], v16, v16, v18
	v_rcp_f32_e32 v19, v17
	v_and_b32_e32 v23, 0xffff0000, v9
	v_fma_f32 v20, -v17, v19, 1.0
	v_fmac_f32_e32 v19, v20, v19
	v_div_scale_f32 v20, vcc, v18, v16, v18
	v_mul_f32_e32 v21, v20, v19
	v_fma_f32 v22, -v17, v21, v20
	v_fmac_f32_e32 v21, v22, v19
	v_fma_f32 v17, -v17, v21, v20
	v_div_fmas_f32 v17, v17, v19, v21
	v_div_fixup_f32 v16, v17, v16, v18
	v_cvt_pk_bf16_f32 v15, v16, v15
	v_lshlrev_b64 v[16:17], 11, v[30:31]
	v_lshl_add_u64 v[16:17], v[28:29], 0, v[16:17]
	v_lshlrev_b32_e32 v20, 16, v8
	v_and_b32_e32 v21, 0xffff0000, v8
	global_store_dwordx4 v[16:17], v[12:15], off
	v_lshlrev_b32_e32 v22, 16, v9
	v_mul_f32_e32 v8, 0xbfb8aa3b, v20
	v_mad_u64_u32 v[12:13], s[4:5], v168, s63, v[32:33]
	v_mul_f32_e32 v9, 0xbfb8aa3b, v21
	ds_read_b128 v[16:19], v12
	ds_read_b128 v[12:15], v12 offset:16
	v_exp_f32_e32 v8, v8
	v_exp_f32_e32 v9, v9
	s_waitcnt lgkmcnt(1)
	v_pk_mul_f32 v[4:5], v[4:5], v[16:17]
	v_pk_mul_f32 v[6:7], v[6:7], v[18:19]
	v_pk_add_f32 v[8:9], v[8:9], 1.0 op_sel_hi:[1,0]
	s_waitcnt lgkmcnt(0)
	v_pk_mul_f32 v[0:1], v[0:1], v[12:13]
	v_div_scale_f32 v16, s[4:5], v9, v9, v5
	v_rcp_f32_e32 v17, v16
	v_pk_mul_f32 v[2:3], v[2:3], v[14:15]
	v_fma_f32 v18, -v16, v17, 1.0
	v_fmac_f32_e32 v17, v18, v17
	v_div_scale_f32 v18, vcc, v5, v9, v5
	v_mul_f32_e32 v19, v18, v17
	v_fma_f32 v20, -v16, v19, v18
	v_fmac_f32_e32 v19, v20, v17
	v_fma_f32 v16, -v16, v19, v18
	v_div_fmas_f32 v16, v16, v17, v19
	v_div_fixup_f32 v5, v16, v9, v5
	v_div_scale_f32 v9, s[4:5], v8, v8, v4
	v_rcp_f32_e32 v16, v9
	s_nop 0
	v_fma_f32 v17, -v9, v16, 1.0
	v_fmac_f32_e32 v16, v17, v16
	v_div_scale_f32 v17, vcc, v4, v8, v4
	v_mul_f32_e32 v18, v17, v16
	v_fma_f32 v19, -v9, v18, v17
	v_fmac_f32_e32 v18, v19, v16
	v_fma_f32 v9, -v9, v18, v17
	v_div_fmas_f32 v9, v9, v16, v18
	v_div_fixup_f32 v4, v9, v8, v4
	v_cvt_pk_bf16_f32 v4, v4, v5
	v_mul_f32_e32 v5, 0xbfb8aa3b, v22
	v_exp_f32_e32 v8, v5
	v_mul_f32_e32 v5, 0xbfb8aa3b, v23
	v_exp_f32_e32 v9, v5
	s_nop 0
	v_pk_add_f32 v[8:9], v[8:9], 1.0 op_sel_hi:[1,0]
	s_nop 0
	v_div_scale_f32 v5, s[4:5], v9, v9, v7
	v_rcp_f32_e32 v16, v5
	s_nop 0
	v_fma_f32 v17, -v5, v16, 1.0
	v_fmac_f32_e32 v16, v17, v16
	v_div_scale_f32 v17, vcc, v7, v9, v7
	v_mul_f32_e32 v18, v17, v16
	v_fma_f32 v19, -v5, v18, v17
	v_fmac_f32_e32 v18, v19, v16
	v_fma_f32 v5, -v5, v18, v17
	v_div_fmas_f32 v5, v5, v16, v18
	v_div_fixup_f32 v5, v5, v9, v7
	v_div_scale_f32 v7, s[4:5], v8, v8, v6
	v_rcp_f32_e32 v9, v7
	s_nop 0
	v_fma_f32 v16, -v7, v9, 1.0
	v_fmac_f32_e32 v9, v16, v9
	v_div_scale_f32 v16, vcc, v6, v8, v6
	v_mul_f32_e32 v17, v16, v9
	v_fma_f32 v18, -v7, v17, v16
	v_fmac_f32_e32 v17, v18, v9
	v_fma_f32 v7, -v7, v17, v16
	v_div_fmas_f32 v7, v7, v9, v17
	v_div_fixup_f32 v6, v7, v8, v6
	v_cvt_pk_bf16_f32 v5, v6, v5
	v_mul_f32_e32 v6, 0xbfb8aa3b, v24
	v_mul_f32_e32 v7, 0xbfb8aa3b, v10
	v_exp_f32_e32 v6, v6
	v_exp_f32_e32 v7, v7
	s_nop 0
	v_pk_add_f32 v[6:7], v[6:7], 1.0 op_sel_hi:[1,0]
	s_nop 0
	v_div_scale_f32 v8, s[4:5], v7, v7, v1
	v_rcp_f32_e32 v9, v8
	s_nop 0
	v_fma_f32 v10, -v8, v9, 1.0
	v_fmac_f32_e32 v9, v10, v9
	v_div_scale_f32 v10, vcc, v1, v7, v1
	v_mul_f32_e32 v12, v10, v9
	v_fma_f32 v13, -v8, v12, v10
	v_fmac_f32_e32 v12, v13, v9
	v_fma_f32 v8, -v8, v12, v10
	v_div_fmas_f32 v8, v8, v9, v12
	v_div_fixup_f32 v1, v8, v7, v1
	v_div_scale_f32 v7, s[4:5], v6, v6, v0
	v_rcp_f32_e32 v8, v7
	s_nop 0
	v_fma_f32 v9, -v7, v8, 1.0
	v_fmac_f32_e32 v8, v9, v8
	v_div_scale_f32 v9, vcc, v0, v6, v0
	v_mul_f32_e32 v10, v9, v8
	v_fma_f32 v12, -v7, v10, v9
	v_fmac_f32_e32 v10, v12, v8
	v_fma_f32 v7, -v7, v10, v9
	v_div_fmas_f32 v7, v7, v8, v10
	v_div_fixup_f32 v0, v7, v6, v0
	v_cvt_pk_bf16_f32 v6, v0, v1
	v_mul_f32_e32 v0, 0xbfb8aa3b, v25
	v_mul_f32_e32 v1, 0xbfb8aa3b, v11
	v_exp_f32_e32 v0, v0
	v_exp_f32_e32 v1, v1
	s_nop 0
	v_pk_add_f32 v[0:1], v[0:1], 1.0 op_sel_hi:[1,0]
	s_nop 0
	v_div_scale_f32 v7, s[4:5], v1, v1, v3
	v_rcp_f32_e32 v8, v7
	s_nop 0
	v_fma_f32 v9, -v7, v8, 1.0
	v_fmac_f32_e32 v8, v9, v8
	v_div_scale_f32 v9, vcc, v3, v1, v3
	v_mul_f32_e32 v10, v9, v8
	v_fma_f32 v11, -v7, v10, v9
	v_fmac_f32_e32 v10, v11, v8
	v_fma_f32 v7, -v7, v10, v9
	v_div_fmas_f32 v7, v7, v8, v10
	v_div_fixup_f32 v1, v7, v1, v3
	v_div_scale_f32 v3, s[4:5], v0, v0, v2
	v_rcp_f32_e32 v7, v3
	s_nop 0
	v_fma_f32 v8, -v3, v7, 1.0
	v_fmac_f32_e32 v7, v8, v7
	v_div_scale_f32 v8, vcc, v2, v0, v2
	v_mul_f32_e32 v9, v8, v7
	v_fma_f32 v10, -v3, v9, v8
	v_fmac_f32_e32 v9, v10, v7
	v_fma_f32 v3, -v3, v9, v8
	v_div_fmas_f32 v3, v3, v7, v9
	v_div_fixup_f32 v0, v3, v0, v2
	v_cvt_pk_bf16_f32 v7, v0, v1
	v_lshlrev_b64 v[0:1], 11, v[26:27]
	v_lshl_add_u64 v[0:1], v[28:29], 0, v[0:1]
	global_store_dwordx4 v[0:1], v[4:7], off
	s_cbranch_scc1 .LBB0_828

; #define LAS __attribute__((address_space(3)))
; #define MFMA32(a, b, c) __builtin_amdgcn_mfma_f32_32x32x16_bf16((a), (b), (c), 0, 0, 0)
; DI int crow(int i, int h) { return (i & 3) + 8 * (i >> 2) + 4 * h; }
; DI f32x16 zero16() { f32x16 z; for (int i = 0; i < 16; ++i) z[i] = 0.f; return z; }
; DI void mlstm_x3(const Params& p, LAS unsigned char* lds, int item, int tid_in, int lane_in, int wave) {
;     ...
;         asm volatile("" ::: "memory");
;         const LAS bf16* Cb = Cs + dir * UROWS * MP;
;         const int klo = dir ? 32 * ti : 0, khi = dir ? 128 : 32 * (ti + 1);
;         const LAS bf16* sp = Ss + (32 * ti + r) * MP + 8 * h;
;         {
;             f32x16 a1 = zero16(), a2 = zero16();
;             const LAS bf16* cpp = Cb + 128 * MP + 8 * h;
; #pragma unroll
;             for (int ks = 0; ks < 8; ++ks) a1 = MFMA32(qf[ks], *(const LAS bf16x8*)(cpp + 16 * ks), a1);
;             const LAS bf16* vp = VTs + 128 * MP + 8 * h;
; #pragma unroll 1
;             for (int k0 = klo; k0 < khi; k0 += 16) a2 = MFMA32(*(const LAS bf16x8*)(sp + k0), *(const LAS bf16x8*)(vp + k0), a2);
;             if (r == 0) {
; #pragma unroll
;             for (int i = 0; i < 16; ++i) { const int trow = 32 * ti + crow(i, h); sc[trow] = 1.f / fmaxf(fabsf(d[256 + trow] * a1[i] + a2[i]), d[384 + trow]); } }
;         }
.LBB0_775:
	s_mul_i32 s9, s9, 0x8910
	s_waitcnt lgkmcnt(0)
	s_barrier
	v_add_u32_e32 v36, s9, v229
	ds_read_b128 v[0:3], v36 offset:34816
	ds_read_b128 v[96:99], v36 offset:34848
	ds_read_b128 v[100:103], v36 offset:34880
	ds_read_b128 v[104:107], v36 offset:34912
	ds_read_b128 v[108:111], v36 offset:34944
	ds_read_b128 v[112:115], v36 offset:34976
	ds_read_b128 v[116:119], v36 offset:35008
	ds_read_b128 v[120:123], v36 offset:35040
	s_waitcnt lgkmcnt(7)
	v_mfma_f32_32x32x16_bf16 v[0:15], v[64:67], v[0:3], 0
	s_and_b64 s[4:5], s[38:39], exec
	s_cselect_b32 s4, 0, s3
	s_cselect_b32 s5, s17, 0x80
	v_mov_b32_e32 v31, 0
	s_cmp_lt_u32 s4, s5
	s_cselect_b64 s[42:43], -1, 0
	s_cmp_ge_u32 s4, s5
	s_waitcnt lgkmcnt(6)
	v_mfma_f32_32x32x16_bf16 v[0:15], v[68:71], v[96:99], v[0:15]
	v_mov_b32_e32 v30, v31
	v_mov_b32_e32 v29, v31
	v_mov_b32_e32 v28, v31
	v_mov_b32_e32 v27, v31
	v_mov_b32_e32 v26, v31
	v_mov_b32_e32 v25, v31
	s_waitcnt lgkmcnt(5)
	v_mfma_f32_32x32x16_bf16 v[0:15], v[72:75], v[100:103], v[0:15]
	v_mov_b32_e32 v24, v31
	v_mov_b32_e32 v23, v31
	v_mov_b32_e32 v22, v31
	v_mov_b32_e32 v21, v31
	v_mov_b32_e32 v20, v31
	s_waitcnt lgkmcnt(4)
	v_mfma_f32_32x32x16_bf16 v[0:15], v[76:79], v[104:107], v[0:15]
	s_waitcnt lgkmcnt(3)
	v_mfma_f32_32x32x16_bf16 v[0:15], v[80:83], v[108:111], v[0:15]
	s_waitcnt lgkmcnt(2)
	v_mfma_f32_32x32x16_bf16 v[0:15], v[84:87], v[112:115], v[0:15]
	s_waitcnt lgkmcnt(1)
	v_mfma_f32_32x32x16_bf16 v[0:15], v[88:91], v[116:119], v[0:15]
	s_waitcnt lgkmcnt(0)
	v_mfma_f32_32x32x16_bf16 v[0:15], v[92:95], v[120:123], v[0:15]
	v_mov_b32_e32 v19, v31
	v_mov_b32_e32 v18, v31
	v_mov_b32_e32 v17, v31
	v_mov_b32_e32 v16, v31
	s_cbranch_scc1 .LBB0_778
	v_add_u32_e32 v16, s3, v37
	v_mul_lo_u32 v32, v16, s93
	v_mov_b32_e32 v16, 0
	v_lshl_add_u32 v33, s4, 1, v230
	s_mov_b32 s9, s4
	v_mov_b32_e32 v17, v16
	v_mov_b32_e32 v18, v16
	v_mov_b32_e32 v19, v16
	v_mov_b32_e32 v20, v16
	v_mov_b32_e32 v21, v16
	v_mov_b32_e32 v22, v16
	v_mov_b32_e32 v23, v16
	v_mov_b32_e32 v24, v16
	v_mov_b32_e32 v25, v16
	v_mov_b32_e32 v26, v16
	v_mov_b32_e32 v27, v16
	v_mov_b32_e32 v28, v16
	v_mov_b32_e32 v29, v16
	v_mov_b32_e32 v30, v16
	v_mov_b32_e32 v31, v16
	v_add_u32_e32 v34, v33, v32
	ds_read_b128 v[40:43], v34 offset:272
	ds_read_b128 v[44:47], v33
.LBB0_777:
	s_add_i32 s9, s9, 16
	s_cmp_ge_u32 s9, s5
	s_cbranch_scc1 .Lx3p_t0_777
	ds_read_b128 v[48:51], v34 offset:304
	ds_read_b128 v[52:55], v33 offset:32
	s_waitcnt lgkmcnt(2)
	v_mfma_f32_32x32x16_bf16 v[16:31], v[40:43], v[44:47], v[16:31]
	s_add_i32 s9, s9, 16
	s_cmp_ge_u32 s9, s5
	s_cbranch_scc1 .Lx3p_t1_777
	v_add_u32_e32 v34, 64, v34
	v_add_u32_e32 v33, 64, v33
	ds_read_b128 v[40:43], v34 offset:272
	ds_read_b128 v[44:47], v33
	s_waitcnt lgkmcnt(2)
	v_mfma_f32_32x32x16_bf16 v[16:31], v[48:51], v[52:55], v[16:31]
	s_branch .LBB0_777
.Lx3p_t0_777:
	s_waitcnt lgkmcnt(0)
	v_mfma_f32_32x32x16_bf16 v[16:31], v[40:43], v[44:47], v[16:31]
	s_branch .Lx3p_d_777
.Lx3p_t1_777:
	s_waitcnt lgkmcnt(0)
	v_mfma_f32_32x32x16_bf16 v[16:31], v[48:51], v[52:55], v[16:31]
.Lx3p_d_777:
.LBB0_778:
	s_xor_b64 s[40:41], s[38:39], -1
	v_cmp_eq_u32_e32 vcc, 0, v37
	v_lshl_add_u32 v233, v188, 2, s8
	s_and_saveexec_b64 s[38:39], vcc
	s_cbranch_execz .LBB0_780
	ds_read_b128 v[40:43], v233 offset:1024
	ds_read_b128 v[32:35], v233 offset:1056
	ds_read_b128 v[44:47], v233 offset:1536
	s_waitcnt lgkmcnt(2)
	s_nop 1
	v_fmac_f32_e32 v17, v1, v41
	v_fmac_f32_e32 v16, v0, v40
	s_waitcnt lgkmcnt(0)
	v_max_f32_e32 v1, v45, v45
	v_max_f32_e32 v0, v44, v44
	v_max_f32_e64 v1, |v17|, v1
	v_max_f32_e64 v0, |v16|, v0
	v_div_scale_f32 v16, s[8:9], v1, v1, 1.0
	v_rcp_f32_e32 v17, v16
	v_fmac_f32_e32 v19, v3, v43
	v_max_f32_e32 v3, v47, v47
	v_max_f32_e64 v3, |v19|, v3
	v_fma_f32 v39, -v16, v17, 1.0
	v_fmac_f32_e32 v17, v39, v17
	v_div_scale_f32 v39, vcc, 1.0, v1, 1.0
	v_mul_f32_e32 v40, v39, v17
	v_fma_f32 v41, -v16, v40, v39
	v_fmac_f32_e32 v40, v41, v17
	v_fma_f32 v16, -v16, v40, v39
	v_div_fmas_f32 v16, v16, v17, v40
	v_div_fixup_f32 v1, v16, v1, 1.0
	v_div_scale_f32 v16, s[8:9], v0, v0, 1.0
	v_rcp_f32_e32 v17, v16
	v_fmac_f32_e32 v18, v2, v42
	v_max_f32_e32 v2, v46, v46
	v_max_f32_e64 v2, |v18|, v2
	v_fma_f32 v39, -v16, v17, 1.0
	v_fmac_f32_e32 v17, v39, v17
	v_div_scale_f32 v39, vcc, 1.0, v0, 1.0
	v_mul_f32_e32 v40, v39, v17
	v_fma_f32 v41, -v16, v40, v39
	v_fmac_f32_e32 v40, v41, v17
	v_fma_f32 v16, -v16, v40, v39
	v_div_fmas_f32 v16, v16, v17, v40
	v_div_fixup_f32 v0, v16, v0, 1.0
	v_div_scale_f32 v16, s[8:9], v3, v3, 1.0
	v_rcp_f32_e32 v17, v16
	v_fmac_f32_e32 v21, v5, v33
	v_fmac_f32_e32 v20, v4, v32
	v_fmac_f32_e32 v23, v7, v35
	v_fma_f32 v18, -v16, v17, 1.0
	v_fmac_f32_e32 v17, v18, v17
	v_div_scale_f32 v18, vcc, 1.0, v3, 1.0
	v_mul_f32_e32 v19, v18, v17
	v_fma_f32 v39, -v16, v19, v18
	v_fmac_f32_e32 v19, v39, v17
	v_fma_f32 v16, -v16, v19, v18
	v_div_fmas_f32 v16, v16, v17, v19
	v_div_fixup_f32 v3, v16, v3, 1.0
	v_div_scale_f32 v16, s[8:9], v2, v2, 1.0
	v_rcp_f32_e32 v17, v16
	v_fmac_f32_e32 v22, v6, v34
	v_fma_f32 v18, -v16, v17, 1.0
	v_fmac_f32_e32 v17, v18, v17
	v_div_scale_f32 v18, vcc, 1.0, v2, 1.0
	v_mul_f32_e32 v19, v18, v17
	v_fma_f32 v39, -v16, v19, v18
	v_fmac_f32_e32 v19, v39, v17
	v_fma_f32 v16, -v16, v19, v18
	v_div_fmas_f32 v16, v16, v17, v19
	v_div_fixup_f32 v2, v16, v2, 1.0
	ds_write_b128 v225, v[0:3]
	ds_read_b128 v[0:3], v233 offset:1568
	s_waitcnt lgkmcnt(0)
; DI int crow(int i, int h) { return (i & 3) + 8 * (i >> 2) + 4 * h; }
; DI void mlstm_x3(const Params& p, LAS unsigned char* lds, int item, int tid_in, int lane_in, int wave) {
;     ...
;             if (r == 0) {
; #pragma unroll
;             for (int i = 0; i < 16; ++i) { const int trow = 32 * ti + crow(i, h); sc[trow] = 1.f / fmaxf(fabsf(d[256 + trow] * a1[i] + a2[i]), d[384 + trow]); } }
	v_max_f32_e32 v1, v1, v1
	v_max_f32_e64 v1, |v21|, v1
	v_div_scale_f32 v4, s[8:9], v1, v1, 1.0
	v_rcp_f32_e32 v5, v4
	v_max_f32_e32 v0, v0, v0
	v_max_f32_e64 v0, |v20|, v0
	v_max_f32_e32 v3, v3, v3
	v_fma_f32 v16, -v4, v5, 1.0
	v_fmac_f32_e32 v5, v16, v5
	v_div_scale_f32 v16, vcc, 1.0, v1, 1.0
	v_mul_f32_e32 v17, v16, v5
	v_fma_f32 v18, -v4, v17, v16
	v_fmac_f32_e32 v17, v18, v5
	v_fma_f32 v4, -v4, v17, v16
	v_div_fmas_f32 v4, v4, v5, v17
	v_div_fixup_f32 v1, v4, v1, 1.0
	v_div_scale_f32 v4, s[8:9], v0, v0, 1.0
	v_rcp_f32_e32 v5, v4
	v_max_f32_e64 v3, |v23|, v3
	v_max_f32_e32 v2, v2, v2
	v_max_f32_e64 v2, |v22|, v2
	v_fma_f32 v16, -v4, v5, 1.0
	v_fmac_f32_e32 v5, v16, v5
	v_div_scale_f32 v16, vcc, 1.0, v0, 1.0
	v_mul_f32_e32 v17, v16, v5
	v_fma_f32 v18, -v4, v17, v16
	v_fmac_f32_e32 v17, v18, v5
	v_fma_f32 v4, -v4, v17, v16
	v_div_fmas_f32 v4, v4, v5, v17
	v_div_fixup_f32 v0, v4, v0, 1.0
	v_div_scale_f32 v4, s[8:9], v3, v3, 1.0
	v_rcp_f32_e32 v5, v4
	s_nop 0
	v_fma_f32 v6, -v4, v5, 1.0
	v_fmac_f32_e32 v5, v6, v5
	v_div_scale_f32 v6, vcc, 1.0, v3, 1.0
	v_mul_f32_e32 v7, v6, v5
	v_fma_f32 v16, -v4, v7, v6
	v_fmac_f32_e32 v7, v16, v5
	v_fma_f32 v4, -v4, v7, v6
	v_div_fmas_f32 v4, v4, v5, v7
	v_div_fixup_f32 v3, v4, v3, 1.0
	v_div_scale_f32 v4, s[8:9], v2, v2, 1.0
	v_rcp_f32_e32 v5, v4
	s_nop 0
	v_fma_f32 v6, -v4, v5, 1.0
	v_fmac_f32_e32 v5, v6, v5
	v_div_scale_f32 v6, vcc, 1.0, v2, 1.0
	v_mul_f32_e32 v7, v6, v5
	v_fma_f32 v16, -v4, v7, v6
	v_fmac_f32_e32 v7, v16, v5
	v_fma_f32 v4, -v4, v7, v6
	v_div_fmas_f32 v4, v4, v5, v7
	v_div_fixup_f32 v2, v4, v2, 1.0
	ds_write_b128 v226, v[0:3]
	ds_read_b128 v[0:3], v233 offset:1088
	ds_read_b128 v[4:7], v233 offset:1600
	s_waitcnt lgkmcnt(1)
	v_fmac_f32_e32 v25, v9, v1
	s_waitcnt lgkmcnt(0)
	v_max_f32_e32 v1, v5, v5
	v_max_f32_e64 v1, |v25|, v1
	v_fmac_f32_e32 v24, v8, v0
	v_max_f32_e32 v0, v4, v4
	v_div_scale_f32 v4, s[8:9], v1, v1, 1.0
	v_rcp_f32_e32 v5, v4
	v_max_f32_e64 v0, |v24|, v0
	v_fmac_f32_e32 v27, v11, v3
	v_max_f32_e32 v3, v7, v7
	v_fma_f32 v8, -v4, v5, 1.0
	v_fmac_f32_e32 v5, v8, v5
	v_div_scale_f32 v8, vcc, 1.0, v1, 1.0
	v_mul_f32_e32 v9, v8, v5
	v_fma_f32 v16, -v4, v9, v8
	v_fmac_f32_e32 v9, v16, v5
	v_fma_f32 v4, -v4, v9, v8
	v_div_fmas_f32 v4, v4, v5, v9
	v_div_fixup_f32 v1, v4, v1, 1.0
	v_div_scale_f32 v4, s[8:9], v0, v0, 1.0
	v_rcp_f32_e32 v5, v4
	v_max_f32_e64 v3, |v27|, v3
	v_fmac_f32_e32 v26, v10, v2
	v_max_f32_e32 v2, v6, v6
	v_fma_f32 v8, -v4, v5, 1.0
	v_fmac_f32_e32 v5, v8, v5
	v_div_scale_f32 v8, vcc, 1.0, v0, 1.0
	v_mul_f32_e32 v9, v8, v5
	v_fma_f32 v16, -v4, v9, v8
	v_fmac_f32_e32 v9, v16, v5
	v_fma_f32 v4, -v4, v9, v8
	v_div_fmas_f32 v4, v4, v5, v9
	v_div_fixup_f32 v0, v4, v0, 1.0
	v_div_scale_f32 v4, s[8:9], v3, v3, 1.0
	v_rcp_f32_e32 v5, v4
	v_max_f32_e64 v2, |v26|, v2
	v_fma_f32 v6, -v4, v5, 1.0
	v_fmac_f32_e32 v5, v6, v5
	v_div_scale_f32 v6, vcc, 1.0, v3, 1.0
	v_mul_f32_e32 v7, v6, v5
	v_fma_f32 v8, -v4, v7, v6
	v_fmac_f32_e32 v7, v8, v5
	v_fma_f32 v4, -v4, v7, v6
	v_div_fmas_f32 v4, v4, v5, v7
	v_div_fixup_f32 v3, v4, v3, 1.0
	v_div_scale_f32 v4, s[8:9], v2, v2, 1.0
	v_rcp_f32_e32 v5, v4
	s_nop 0
	v_fma_f32 v6, -v4, v5, 1.0
	v_fmac_f32_e32 v5, v6, v5
	v_div_scale_f32 v6, vcc, 1.0, v2, 1.0
	v_mul_f32_e32 v7, v6, v5
	v_fma_f32 v8, -v4, v7, v6
	v_fmac_f32_e32 v7, v8, v5
	v_fma_f32 v4, -v4, v7, v6
	v_div_fmas_f32 v4, v4, v5, v7
	v_div_fixup_f32 v2, v4, v2, 1.0
	ds_write_b128 v227, v[0:3]
	ds_read_b128 v[0:3], v233 offset:1120
	ds_read_b128 v[4:7], v233 offset:1632
	s_waitcnt lgkmcnt(1)
	v_fmac_f32_e32 v29, v13, v1
	s_waitcnt lgkmcnt(0)
	v_max_f32_e32 v1, v5, v5
	v_max_f32_e64 v1, |v29|, v1
	v_fmac_f32_e32 v28, v12, v0
	v_max_f32_e32 v0, v4, v4
	v_div_scale_f32 v4, s[8:9], v1, v1, 1.0
	v_rcp_f32_e32 v5, v4
	v_max_f32_e64 v0, |v28|, v0
	v_fmac_f32_e32 v31, v15, v3
	v_max_f32_e32 v3, v7, v7
	v_fma_f32 v8, -v4, v5, 1.0
	v_fmac_f32_e32 v5, v8, v5
	v_div_scale_f32 v8, vcc, 1.0, v1, 1.0
	v_mul_f32_e32 v9, v8, v5
	v_fma_f32 v10, -v4, v9, v8
	v_fmac_f32_e32 v9, v10, v5
	v_fma_f32 v4, -v4, v9, v8
	v_div_fmas_f32 v4, v4, v5, v9
	v_div_fixup_f32 v1, v4, v1, 1.0
	v_div_scale_f32 v4, s[8:9], v0, v0, 1.0
	v_rcp_f32_e32 v5, v4
	v_max_f32_e64 v3, |v31|, v3
	v_fmac_f32_e32 v30, v14, v2
	v_max_f32_e32 v2, v6, v6
	v_fma_f32 v8, -v4, v5, 1.0
	v_fmac_f32_e32 v5, v8, v5
	v_div_scale_f32 v8, vcc, 1.0, v0, 1.0
	v_mul_f32_e32 v9, v8, v5
	v_fma_f32 v10, -v4, v9, v8
	v_fmac_f32_e32 v9, v10, v5
	v_fma_f32 v4, -v4, v9, v8
	v_div_fmas_f32 v4, v4, v5, v9
	v_div_fixup_f32 v0, v4, v0, 1.0
	v_div_scale_f32 v4, s[8:9], v3, v3, 1.0
	v_rcp_f32_e32 v5, v4
	v_max_f32_e64 v2, |v30|, v2
	v_fma_f32 v6, -v4, v5, 1.0
	v_fmac_f32_e32 v5, v6, v5
	v_div_scale_f32 v6, vcc, 1.0, v3, 1.0
	v_mul_f32_e32 v7, v6, v5
	v_fma_f32 v8, -v4, v7, v6
	v_fmac_f32_e32 v7, v8, v5
	v_fma_f32 v4, -v4, v7, v6
	v_div_fmas_f32 v4, v4, v5, v7
	v_div_fixup_f32 v3, v4, v3, 1.0
	v_div_scale_f32 v4, s[8:9], v2, v2, 1.0
	v_rcp_f32_e32 v5, v4
	s_nop 0
	v_fma_f32 v6, -v4, v5, 1.0
	v_fmac_f32_e32 v5, v6, v5
	v_div_scale_f32 v6, vcc, 1.0, v2, 1.0
	v_mul_f32_e32 v7, v6, v5
	v_fma_f32 v8, -v4, v7, v6
	v_fmac_f32_e32 v7, v8, v5
	v_fma_f32 v4, -v4, v7, v6
	v_div_fmas_f32 v4, v4, v5, v7
	v_div_fixup_f32 v2, v4, v2, 1.0
	ds_write_b128 v228, v[0:3]
; #define LAS __attribute__((address_space(3)))
; #define MFMA32(a, b, c) __builtin_amdgcn_mfma_f32_32x32x16_bf16((a), (b), (c), 0, 0, 0)
; DI int crow(int i, int h) { return (i & 3) + 8 * (i >> 2) + 4 * h; }
; DI f32x16 zero16() { f32x16 z; for (int i = 0; i < 16; ++i) z[i] = 0.f; return z; }
; DI void mlstm_x3(const Params& p, LAS unsigned char* lds, int item, int tid_in, int lane_in, int wave) {
;     ...
; #pragma unroll
;         for (int tt = 0; tt < 2; ++tt) { const int te = 2 * eh + tt;
;             f32x16 a1 = zero16(), a2 = zero16();
;             const LAS bf16* cpp = Cb + (32 * te + r) * MP + 8 * h;
; #pragma unroll
;             for (int ks = 0; ks < 8; ++ks) a1 = MFMA32(qf[ks], *(const LAS bf16x8*)(cpp + 16 * ks), a1);
;             const LAS bf16* vp = VTs + (32 * te + r) * MP + 8 * h;
; #pragma unroll 1
;             for (int k0 = klo; k0 < khi; k0 += 16) a2 = MFMA32(*(const LAS bf16x8*)(sp + k0), *(const LAS bf16x8*)(vp + k0), a2);
; #pragma unroll
;             for (int i = 0; i < 16; ++i) { const int trow = 32 * ti + crow(i, h); hs[tt][i] += (d[256 + trow] * a1[i] + a2[i]) * sc[trow]; }
;             asm volatile("" ::: "memory"); }
.LBB0_780:
	s_or_b64 exec, exec, s[38:39]
	v_mad_u64_u32 v[48:49], s[8:9], v38, s93, v[36:37]
	ds_read_b128 v[0:3], v48
	ds_read_b128 v[96:99], v48 offset:32
	ds_read_b128 v[100:103], v48 offset:64
	ds_read_b128 v[104:107], v48 offset:96
	ds_read_b128 v[108:111], v48 offset:128
	ds_read_b128 v[112:115], v48 offset:160
	ds_read_b128 v[116:119], v48 offset:192
	ds_read_b128 v[120:123], v48 offset:224
	v_mov_b32_e32 v31, 0
	s_waitcnt lgkmcnt(7)
	v_mfma_f32_32x32x16_bf16 v[0:15], v[64:67], v[0:3], 0
	s_andn2_b64 vcc, exec, s[42:43]
	v_mov_b32_e32 v30, v31
	v_mov_b32_e32 v29, v31
	v_mov_b32_e32 v28, v31
	v_mov_b32_e32 v27, v31
	v_mov_b32_e32 v26, v31
	v_mov_b32_e32 v25, v31
	s_waitcnt lgkmcnt(6)
	v_mfma_f32_32x32x16_bf16 v[0:15], v[68:71], v[96:99], v[0:15]
	v_mov_b32_e32 v24, v31
	v_mov_b32_e32 v23, v31
	v_mov_b32_e32 v22, v31
	v_mov_b32_e32 v21, v31
	v_mov_b32_e32 v20, v31
	s_waitcnt lgkmcnt(5)
	v_mfma_f32_32x32x16_bf16 v[0:15], v[72:75], v[100:103], v[0:15]
	s_waitcnt lgkmcnt(4)
	v_mfma_f32_32x32x16_bf16 v[0:15], v[76:79], v[104:107], v[0:15]
	s_waitcnt lgkmcnt(3)
	v_mfma_f32_32x32x16_bf16 v[0:15], v[80:83], v[108:111], v[0:15]
	s_waitcnt lgkmcnt(2)
	v_mfma_f32_32x32x16_bf16 v[0:15], v[84:87], v[112:115], v[0:15]
	s_waitcnt lgkmcnt(1)
	v_mfma_f32_32x32x16_bf16 v[0:15], v[88:91], v[116:119], v[0:15]
	s_waitcnt lgkmcnt(0)
	v_mfma_f32_32x32x16_bf16 v[0:15], v[92:95], v[120:123], v[0:15]
	v_cndmask_b32_e64 v16, 0, 1, s[42:43]
	v_cmp_ne_u32_e64 s[38:39], 1, v16
	v_mul_lo_u32 v16, v37, s93
	v_lshl_add_u32 v234, s4, 1, v16
	v_mov_b32_e32 v19, v31
	v_mov_b32_e32 v18, v31
	v_mov_b32_e32 v17, v31
	v_mov_b32_e32 v16, v31
	s_cbranch_vccnz .LBB0_783
	v_mov_b32_e32 v16, 0
	v_add_u32_e32 v32, v231, v234
	v_add_u32_e32 v33, v232, v234
	s_mov_b32 s8, s4
	v_mov_b32_e32 v17, v16
	v_mov_b32_e32 v18, v16
	v_mov_b32_e32 v19, v16
	v_mov_b32_e32 v20, v16
	v_mov_b32_e32 v21, v16
	v_mov_b32_e32 v22, v16
	v_mov_b32_e32 v23, v16
	v_mov_b32_e32 v24, v16
	v_mov_b32_e32 v25, v16
	v_mov_b32_e32 v26, v16
	v_mov_b32_e32 v27, v16
	v_mov_b32_e32 v28, v16
	v_mov_b32_e32 v29, v16
	v_mov_b32_e32 v30, v16
	v_mov_b32_e32 v31, v16
	ds_read_b128 v[34:37], v32
	ds_read_b128 v[38:41], v33
.LBB0_782:
	s_add_i32 s8, s8, 16
	s_cmp_ge_u32 s8, s5
	s_cbranch_scc1 .Lx3p_t0_782
	ds_read_b128 v[42:45], v32 offset:32
	ds_read_b128 v[50:53], v33 offset:32
	s_waitcnt lgkmcnt(2)
	v_mfma_f32_32x32x16_bf16 v[16:31], v[34:37], v[38:41], v[16:31]
	s_add_i32 s8, s8, 16
	s_cmp_ge_u32 s8, s5
	s_cbranch_scc1 .Lx3p_t1_782
	v_add_u32_e32 v32, 64, v32
	v_add_u32_e32 v33, 64, v33
	ds_read_b128 v[34:37], v32
	ds_read_b128 v[38:41], v33
	s_waitcnt lgkmcnt(2)
	v_mfma_f32_32x32x16_bf16 v[16:31], v[42:45], v[50:53], v[16:31]
	s_branch .LBB0_782
.Lx3p_t0_782:
	s_waitcnt lgkmcnt(0)
	v_mfma_f32_32x32x16_bf16 v[16:31], v[34:37], v[38:41], v[16:31]
	s_branch .Lx3p_d_782
.Lx3p_t1_782:
	s_waitcnt lgkmcnt(0)
	v_mfma_f32_32x32x16_bf16 v[16:31], v[42:45], v[50:53], v[16:31]
.Lx3p_d_782:
.LBB0_783:
	ds_read_b128 v[124:127], v233 offset:1024
	ds_read_b128 v[116:119], v233 offset:1056
	ds_read_b128 v[120:123], v225
	ds_read_b128 v[112:115], v226
	ds_read_b128 v[108:111], v233 offset:1088
	ds_read_b128 v[104:107], v227
	ds_read_b128 v[100:103], v233 offset:1120
	ds_read_b128 v[96:99], v228
	ds_read_b128 v[32:35], v48 offset:8704
	ds_read_b128 v[236:239], v48 offset:8736
	ds_read_b128 v[240:243], v48 offset:8768
	ds_read_b128 v[244:247], v48 offset:8800
	ds_read_b128 v[248:251], v48 offset:8832
	v_mov_b32_e32 v63, 0
	s_and_b64 vcc, exec, s[38:39]
	s_waitcnt lgkmcnt(4)
	v_mfma_f32_32x32x16_bf16 v[32:47], v[64:67], v[32:35], 0
	v_mov_b32_e32 v62, v63
	v_mov_b32_e32 v61, v63
	v_mov_b32_e32 v60, v63
	v_mov_b32_e32 v59, v63
	v_mov_b32_e32 v58, v63
	v_mov_b32_e32 v57, v63
	v_mov_b32_e32 v56, v63
	s_waitcnt lgkmcnt(3)
	v_mfma_f32_32x32x16_bf16 v[32:47], v[68:71], v[236:239], v[32:47]
	ds_read_b128 v[236:239], v48 offset:8864
	v_mov_b32_e32 v55, v63
	v_mov_b32_e32 v54, v63
	s_waitcnt lgkmcnt(3)
	v_mfma_f32_32x32x16_bf16 v[32:47], v[72:75], v[240:243], v[32:47]
	ds_read_b128 v[240:243], v48 offset:8896
	s_waitcnt lgkmcnt(3)
	v_mfma_f32_32x32x16_bf16 v[32:47], v[76:79], v[244:247], v[32:47]
	ds_read_b128 v[244:247], v48 offset:8928
	s_waitcnt lgkmcnt(3)
	v_mfma_f32_32x32x16_bf16 v[32:47], v[80:83], v[248:251], v[32:47]
	s_waitcnt lgkmcnt(2)
	v_mfma_f32_32x32x16_bf16 v[32:47], v[84:87], v[236:239], v[32:47]
	s_waitcnt lgkmcnt(1)
	v_mfma_f32_32x32x16_bf16 v[32:47], v[88:91], v[240:243], v[32:47]
	v_mov_b32_e32 v53, v63
	v_mov_b32_e32 v52, v63
	s_waitcnt lgkmcnt(0)
	v_mfma_f32_32x32x16_bf16 v[32:47], v[92:95], v[244:247], v[32:47]
	v_mov_b32_e32 v51, v63
	v_mov_b32_e32 v50, v63
	v_mov_b32_e32 v49, v63
	v_mov_b32_e32 v48, v63
	s_cbranch_vccnz .LBB0_706
	v_mov_b32_e32 v48, 0
	v_add_u32_e32 v235, v132, v234
	v_add_u32_e32 v234, v231, v234
	v_mov_b32_e32 v49, v48
	v_mov_b32_e32 v50, v48
	v_mov_b32_e32 v51, v48
	v_mov_b32_e32 v52, v48
	v_mov_b32_e32 v53, v48
	v_mov_b32_e32 v54, v48
	v_mov_b32_e32 v55, v48
	v_mov_b32_e32 v56, v48
	v_mov_b32_e32 v57, v48
	v_mov_b32_e32 v58, v48
	v_mov_b32_e32 v59, v48
	v_mov_b32_e32 v60, v48
	v_mov_b32_e32 v61, v48
	v_mov_b32_e32 v62, v48
	v_mov_b32_e32 v63, v48
	ds_read_b128 v[236:239], v234
	ds_read_b128 v[240:243], v235
.LBB0_785:
	s_add_i32 s4, s4, 16
	s_cmp_lt_u32 s4, s5
	s_cbranch_scc0 .Lx3p_t0_785
	ds_read_b128 v[244:247], v234 offset:32
	ds_read_b128 v[248:251], v235 offset:32
	s_waitcnt lgkmcnt(2)
	v_mfma_f32_32x32x16_bf16 v[48:63], v[236:239], v[240:243], v[48:63]
	s_add_i32 s4, s4, 16
	s_cmp_lt_u32 s4, s5
	s_cbranch_scc0 .Lx3p_t1_785
	v_add_u32_e32 v234, 64, v234
	v_add_u32_e32 v235, 64, v235
	ds_read_b128 v[236:239], v234
	ds_read_b128 v[240:243], v235
	s_waitcnt lgkmcnt(2)
	v_mfma_f32_32x32x16_bf16 v[48:63], v[244:247], v[248:251], v[48:63]
	s_branch .LBB0_785
.Lx3p_t0_785:
	s_waitcnt lgkmcnt(0)
	v_mfma_f32_32x32x16_bf16 v[48:63], v[236:239], v[240:243], v[48:63]
	s_branch .Lx3p_d_785
.Lx3p_t1_785:
	s_waitcnt lgkmcnt(0)
	v_mfma_f32_32x32x16_bf16 v[48:63], v[244:247], v[248:251], v[48:63]
.Lx3p_d_785:
	s_branch .LBB0_706

; DI int crow(int i, int h) { return (i & 3) + 8 * (i >> 2) + 4 * h; }
; DI void mlstm_x3(const Params& p, LAS unsigned char* lds, int item, int tid_in, int lane_in, int wave) {
;     ...
; #pragma unroll
;     for (int i = 0; i < 16; ++i) { float q = hs[0][i] * hs[0][i] + hs[1][i] * hs[1][i];
; #pragma unroll
;         for (int o = 1; o < 32; o <<= 1) q += __int_as_float(__builtin_amdgcn_ds_bpermute((lane ^ o) << 2, __float_as_int(q)));
;         if (r_ == 0) s_ssq[(32 * ti + crow(i, h)) * 2 + eh] = q; }
.LBB0_794:
	v_cmp_ne_u32_e32 vcc, 0, v173
	v_cmp_eq_u32_e64 s[38:39], 0, v173
	v_xor_b32_e32 v6, 64, v190
	v_pk_mul_f32 v[64:65], v[160:161], v[160:161]
	v_pk_mul_f32 v[66:67], v[156:157], v[156:157]
	v_pk_mul_f32 v[68:69], v[152:153], v[152:153]
	v_pk_mul_f32 v[70:71], v[148:149], v[148:149]
	v_pk_mul_f32 v[72:73], v[144:145], v[144:145]
	v_pk_mul_f32 v[74:75], v[140:141], v[140:141]
	v_pk_mul_f32 v[76:77], v[136:137], v[136:137]
	v_pk_mul_f32 v[78:79], v[128:129], v[128:129]
	v_pk_fma_f32 v[64:65], v[158:159], v[158:159], v[64:65]
	v_pk_fma_f32 v[66:67], v[154:155], v[154:155], v[66:67]
	v_pk_fma_f32 v[68:69], v[150:151], v[150:151], v[68:69]
	v_pk_fma_f32 v[70:71], v[146:147], v[146:147], v[70:71]
	v_pk_fma_f32 v[72:73], v[142:143], v[142:143], v[72:73]
	v_pk_fma_f32 v[74:75], v[138:139], v[138:139], v[74:75]
	v_pk_fma_f32 v[76:77], v[134:135], v[134:135], v[76:77]
	v_pk_fma_f32 v[78:79], v[130:131], v[130:131], v[78:79]
	s_nop 1
	v_add_f32_dpp v64, v64, v64 quad_perm:[1,0,3,2] row_mask:0xf bank_mask:0xf
	v_add_f32_dpp v65, v65, v65 quad_perm:[1,0,3,2] row_mask:0xf bank_mask:0xf
	v_add_f32_dpp v66, v66, v66 quad_perm:[1,0,3,2] row_mask:0xf bank_mask:0xf
	v_add_f32_dpp v67, v67, v67 quad_perm:[1,0,3,2] row_mask:0xf bank_mask:0xf
	v_add_f32_dpp v68, v68, v68 quad_perm:[1,0,3,2] row_mask:0xf bank_mask:0xf
	v_add_f32_dpp v69, v69, v69 quad_perm:[1,0,3,2] row_mask:0xf bank_mask:0xf
	v_add_f32_dpp v70, v70, v70 quad_perm:[1,0,3,2] row_mask:0xf bank_mask:0xf
	v_add_f32_dpp v71, v71, v71 quad_perm:[1,0,3,2] row_mask:0xf bank_mask:0xf
	v_add_f32_dpp v72, v72, v72 quad_perm:[1,0,3,2] row_mask:0xf bank_mask:0xf
	v_add_f32_dpp v73, v73, v73 quad_perm:[1,0,3,2] row_mask:0xf bank_mask:0xf
	v_add_f32_dpp v74, v74, v74 quad_perm:[1,0,3,2] row_mask:0xf bank_mask:0xf
	v_add_f32_dpp v75, v75, v75 quad_perm:[1,0,3,2] row_mask:0xf bank_mask:0xf
	v_add_f32_dpp v76, v76, v76 quad_perm:[1,0,3,2] row_mask:0xf bank_mask:0xf
	v_add_f32_dpp v77, v77, v77 quad_perm:[1,0,3,2] row_mask:0xf bank_mask:0xf
	v_add_f32_dpp v78, v78, v78 quad_perm:[1,0,3,2] row_mask:0xf bank_mask:0xf
	v_add_f32_dpp v79, v79, v79 quad_perm:[1,0,3,2] row_mask:0xf bank_mask:0xf
	v_add_f32_dpp v64, v64, v64 quad_perm:[2,3,0,1] row_mask:0xf bank_mask:0xf
	v_add_f32_dpp v65, v65, v65 quad_perm:[2,3,0,1] row_mask:0xf bank_mask:0xf
	v_add_f32_dpp v66, v66, v66 quad_perm:[2,3,0,1] row_mask:0xf bank_mask:0xf
	v_add_f32_dpp v67, v67, v67 quad_perm:[2,3,0,1] row_mask:0xf bank_mask:0xf
	v_add_f32_dpp v68, v68, v68 quad_perm:[2,3,0,1] row_mask:0xf bank_mask:0xf
	v_add_f32_dpp v69, v69, v69 quad_perm:[2,3,0,1] row_mask:0xf bank_mask:0xf
	v_add_f32_dpp v70, v70, v70 quad_perm:[2,3,0,1] row_mask:0xf bank_mask:0xf
	v_add_f32_dpp v71, v71, v71 quad_perm:[2,3,0,1] row_mask:0xf bank_mask:0xf
	v_add_f32_dpp v72, v72, v72 quad_perm:[2,3,0,1] row_mask:0xf bank_mask:0xf
	v_add_f32_dpp v73, v73, v73 quad_perm:[2,3,0,1] row_mask:0xf bank_mask:0xf
	v_add_f32_dpp v74, v74, v74 quad_perm:[2,3,0,1] row_mask:0xf bank_mask:0xf
	v_add_f32_dpp v75, v75, v75 quad_perm:[2,3,0,1] row_mask:0xf bank_mask:0xf
	v_add_f32_dpp v76, v76, v76 quad_perm:[2,3,0,1] row_mask:0xf bank_mask:0xf
	v_add_f32_dpp v77, v77, v77 quad_perm:[2,3,0,1] row_mask:0xf bank_mask:0xf
	v_add_f32_dpp v78, v78, v78 quad_perm:[2,3,0,1] row_mask:0xf bank_mask:0xf
	v_add_f32_dpp v79, v79, v79 quad_perm:[2,3,0,1] row_mask:0xf bank_mask:0xf
	v_add_f32_dpp v64, v64, v64 row_half_mirror row_mask:0xf bank_mask:0xf
	v_add_f32_dpp v65, v65, v65 row_half_mirror row_mask:0xf bank_mask:0xf
	v_add_f32_dpp v66, v66, v66 row_half_mirror row_mask:0xf bank_mask:0xf
	v_add_f32_dpp v67, v67, v67 row_half_mirror row_mask:0xf bank_mask:0xf
	v_add_f32_dpp v68, v68, v68 row_half_mirror row_mask:0xf bank_mask:0xf
	v_add_f32_dpp v69, v69, v69 row_half_mirror row_mask:0xf bank_mask:0xf
	v_add_f32_dpp v70, v70, v70 row_half_mirror row_mask:0xf bank_mask:0xf
	v_add_f32_dpp v71, v71, v71 row_half_mirror row_mask:0xf bank_mask:0xf
	v_add_f32_dpp v72, v72, v72 row_half_mirror row_mask:0xf bank_mask:0xf
	v_add_f32_dpp v73, v73, v73 row_half_mirror row_mask:0xf bank_mask:0xf
	v_add_f32_dpp v74, v74, v74 row_half_mirror row_mask:0xf bank_mask:0xf
	v_add_f32_dpp v75, v75, v75 row_half_mirror row_mask:0xf bank_mask:0xf
	v_add_f32_dpp v76, v76, v76 row_half_mirror row_mask:0xf bank_mask:0xf
	v_add_f32_dpp v77, v77, v77 row_half_mirror row_mask:0xf bank_mask:0xf
	v_add_f32_dpp v78, v78, v78 row_half_mirror row_mask:0xf bank_mask:0xf
	v_add_f32_dpp v79, v79, v79 row_half_mirror row_mask:0xf bank_mask:0xf
	v_add_f32_dpp v64, v64, v64 row_mirror row_mask:0xf bank_mask:0xf
	v_add_f32_dpp v65, v65, v65 row_mirror row_mask:0xf bank_mask:0xf
	v_add_f32_dpp v66, v66, v66 row_mirror row_mask:0xf bank_mask:0xf
	v_add_f32_dpp v67, v67, v67 row_mirror row_mask:0xf bank_mask:0xf
	v_add_f32_dpp v68, v68, v68 row_mirror row_mask:0xf bank_mask:0xf
	v_add_f32_dpp v69, v69, v69 row_mirror row_mask:0xf bank_mask:0xf
	v_add_f32_dpp v70, v70, v70 row_mirror row_mask:0xf bank_mask:0xf
	v_add_f32_dpp v71, v71, v71 row_mirror row_mask:0xf bank_mask:0xf
	v_add_f32_dpp v72, v72, v72 row_mirror row_mask:0xf bank_mask:0xf
	v_add_f32_dpp v73, v73, v73 row_mirror row_mask:0xf bank_mask:0xf
	v_add_f32_dpp v74, v74, v74 row_mirror row_mask:0xf bank_mask:0xf
	v_add_f32_dpp v75, v75, v75 row_mirror row_mask:0xf bank_mask:0xf
	v_add_f32_dpp v76, v76, v76 row_mirror row_mask:0xf bank_mask:0xf
	v_add_f32_dpp v77, v77, v77 row_mirror row_mask:0xf bank_mask:0xf
	v_add_f32_dpp v78, v78, v78 row_mirror row_mask:0xf bank_mask:0xf
	v_add_f32_dpp v79, v79, v79 row_mirror row_mask:0xf bank_mask:0xf
	s_nop 1
	ds_bpermute_b32 v80, v6, v64
	ds_bpermute_b32 v81, v6, v65
	ds_bpermute_b32 v82, v6, v66
	ds_bpermute_b32 v83, v6, v67
	ds_bpermute_b32 v84, v6, v68
	ds_bpermute_b32 v85, v6, v69
	ds_bpermute_b32 v86, v6, v70
	ds_bpermute_b32 v87, v6, v71
	ds_bpermute_b32 v88, v6, v72
	ds_bpermute_b32 v89, v6, v73
	ds_bpermute_b32 v90, v6, v74
	ds_bpermute_b32 v91, v6, v75
	ds_bpermute_b32 v92, v6, v76
	ds_bpermute_b32 v93, v6, v77
	ds_bpermute_b32 v94, v6, v78
	ds_bpermute_b32 v95, v6, v79
	v_lshlrev_b32_e32 v0, 3, v189
	v_lshl_add_u32 v96, v188, 3, s69
	v_lshl_add_u32 v97, v187, 3, s69
	v_lshl_add_u32 v98, v186, 3, s69
	v_lshl_add_u32 v99, v185, 3, s69
	v_lshl_add_u32 v100, v184, 3, s69
	v_lshl_add_u32 v101, v183, 3, s69
	v_lshl_add_u32 v102, v182, 3, s69
	v_lshl_add_u32 v103, v181, 3, s69
	v_lshl_add_u32 v104, v180, 3, s69
	v_lshl_add_u32 v105, v179, 3, s69
	v_lshl_add_u32 v106, v178, 3, s69
	v_lshl_add_u32 v107, v177, 3, s69
	v_lshl_add_u32 v108, v176, 3, s69
	v_lshl_add_u32 v109, v175, 3, s69
	v_lshl_add_u32 v110, v174, 3, s69
	v_add_u32_e32 v111, s69, v0
	s_and_saveexec_b64 s[4:5], s[38:39]
	s_waitcnt lgkmcnt(15)
; DI int crow(int i, int h) { return (i & 3) + 8 * (i >> 2) + 4 * h; }
; DI void mlstm_x3(const Params& p, LAS unsigned char* lds, int item, int tid_in, int lane_in, int wave) {
;     ...
;     for (int i = 0; i < 16; ++i) { float q = hs[0][i] * hs[0][i] + hs[1][i] * hs[1][i];
; #pragma unroll
;         for (int o = 1; o < 32; o <<= 1) q += __int_as_float(__builtin_amdgcn_ds_bpermute((lane ^ o) << 2, __float_as_int(q)));
;         if (r_ == 0) s_ssq[(32 * ti + crow(i, h)) * 2 + eh] = q; }
	v_add_f32_e32 v64, v64, v80
	ds_write_b32 v96, v64
	s_waitcnt lgkmcnt(14)
	v_add_f32_e32 v65, v65, v81
	ds_write_b32 v97, v65
	s_waitcnt lgkmcnt(13)
	v_add_f32_e32 v66, v66, v82
	ds_write_b32 v98, v66
	s_waitcnt lgkmcnt(12)
	v_add_f32_e32 v67, v67, v83
	ds_write_b32 v99, v67
	s_waitcnt lgkmcnt(11)
	v_add_f32_e32 v68, v68, v84
	ds_write_b32 v100, v68
	s_waitcnt lgkmcnt(10)
	v_add_f32_e32 v69, v69, v85
	ds_write_b32 v101, v69
	s_waitcnt lgkmcnt(9)
	v_add_f32_e32 v70, v70, v86
	ds_write_b32 v102, v70
	s_waitcnt lgkmcnt(8)
	v_add_f32_e32 v71, v71, v87
	ds_write_b32 v103, v71
	s_waitcnt lgkmcnt(7)
	v_add_f32_e32 v72, v72, v88
	ds_write_b32 v104, v72
	s_waitcnt lgkmcnt(6)
	v_add_f32_e32 v73, v73, v89
	ds_write_b32 v105, v73
	s_waitcnt lgkmcnt(5)
	v_add_f32_e32 v74, v74, v90
	ds_write_b32 v106, v74
	s_waitcnt lgkmcnt(4)
	v_add_f32_e32 v75, v75, v91
	ds_write_b32 v107, v75
	s_waitcnt lgkmcnt(3)
	v_add_f32_e32 v76, v76, v92
	ds_write_b32 v108, v76
	s_waitcnt lgkmcnt(2)
	v_add_f32_e32 v77, v77, v93
	ds_write_b32 v109, v77
	s_waitcnt lgkmcnt(1)
	v_add_f32_e32 v78, v78, v94
	ds_write_b32 v110, v78
	s_waitcnt lgkmcnt(0)
	v_add_f32_e32 v79, v79, v95
	ds_write_b32 v111, v79
	s_nop 0
	s_branch .LBB0_686
	s_nop 0
	s_nop 0
	s_nop 0
	s_nop 0
	s_nop 0
	s_nop 0
	s_nop 0
	s_nop 0
	s_nop 0
	s_nop 0
	s_nop 0
	s_nop 0
	s_nop 0
	s_nop 0
	s_nop 0
	s_nop 0
	s_nop 0
	s_nop 0
	s_nop 0
	s_nop 0
	s_nop 0
	s_nop 0
	s_nop 0
	s_nop 0
	s_nop 0
	s_nop 0
	s_nop 0
	s_nop 0

; DI f32x16 zero16() { f32x16 z; for (int i = 0; i < 16; ++i) z[i] = 0.f; return z; }
; #define ATT_LOAD(t) do { int krow0, vkey0; ATT_TILE(t, krow0, vkey0); _Pragma("unroll") for (int i = 0; i < NPT; ++i) { const int id = tid + 512 * i; \
;         kr[i] = *(const u32x4*)(QKV + (size_t)(krow0 + id / CPR) * pitch + kcol + (id % CPR) * 8); \
;         vr[i] = *(const u32x4*)(VTb + (size_t)(id / VCR) * KVLEN + vkey0 + (id % VCR) * 8); } } while (0)
; template <int D, int MODE, int NSUB>
; DI void attn_item(const bf16* QKV, int pitch, int qcol0, int kcol0, const bf16* VT, bf16* O, int ocol0, const float* sink,
;                   LAS unsigned char* lds, int item, int tid_in, int lane_in, int wave) {
;     ...
;     int b, kvh, head, qrow, qpos = 0, nt, wstart = 0;
;     if (MODE == 0) { const int qb = item & 15; head = (item >> 4) & 7; b = item >> 7; kvh = head >> 2; qrow = NCTX + b * SEQ + qb * 256 + 32 * wave; nt = KVLEN / KT; }
;     else if (MODE == 1) { const int nb = item & 31, hp = (item >> 5) & 1; kvh = (item >> 6) & 1; b = item >> 7; head = kvh * 4 + hp * 2 + (wave >> 2);
;         qpos = nb * 128 + (wave & 3) * 32 + r; qrow = NCTX + b * SEQ + nb * 128 + (wave & 3) * 32;
;         wstart = nb > 0 ? (nb - 1) * 128 : 0; const int wend = nb < 31 ? (nb + 2) * 128 : SEQ; nt = (CTXL + wend - wstart) / KT; }
;     else { const int qh = item & 1, hp = (item >> 1) & 1; kvh = (item >> 2) & 1; b = item >> 3; head = kvh * 4 + hp * 2 + (wave >> 2); qrow = b * 256 + qh * 128 + (wave & 3) * 32; nt = CTXL / KT; }
;     const bf16* VTb = VT + (size_t)(b * 2 + kvh) * D * KVLEN;
;     const int kcol = kcol0 + kvh * D;
;     bf16x8 qf[NKS];
;     { const bf16* qp = QKV + (size_t)(qrow + r) * pitch + qcol0 + head * D + 8 * h;
; #pragma unroll
;         for (int ks = 0; ks < NKS; ++ks) qf[ks] = *(const bf16x8*)(qp + 16 * ks); }
;     const float scl = (D == 64 ? 0.125f : 0.08838834764831845f) * LOG2E;
;     constexpr float THR2 = 11.0f;
;     float mrun, lrun;
;     if (MODE == 0) { mrun = -INFINITY; lrun = 0.f; } else { mrun = sink[head] * LOG2E; lrun = h == 0 ? 1.f : 0.f; }
;     f32x16 o[NDT];
; #pragma unroll
;     for (int dt = 0; dt < NDT; ++dt) o[dt] = zero16();
;     u32x4 kr[NPT], vr[NPT];
;     ...
;     ATT_LOAD(0); ATT_STORE(0);
;     __syncthreads();
.LBB0_834:
	s_cmpk_gt_i32 s2, 0x3ff
	s_mov_b64 s[4:5], -1
	s_cbranch_scc0 .LBB0_846
	s_add_i32 s0, s2, 0xfffffc00
	s_and_b32 s4, s2, 2
	s_bfe_u32 s12, s2, 0x10002
	v_readlane_b32 s7, v254, 29
	s_lshr_b32 s5, s0, 3
	s_lshl_b32 s6, s12, 2
	s_add_i32 s4, s4, s7
	s_lshl_b32 s0, s0, 7
	s_add_i32 s6, s4, s6
	s_and_b32 s10, s0, 0x80
	s_lshl_b32 s0, s5, 7
	s_lshl_b32 s4, s12, 6
	s_or_b32 s0, s4, s0
	s_mulk_i32 s0, 0x1100
	s_lshl_b32 s7, s5, 8
	s_lshl_b64 s[4:5], s[0:1], 1
	v_readlane_b32 s22, v254, 14
	v_readlane_b32 s23, v254, 15
	s_add_u32 s4, s22, s4
	v_readlane_b32 s0, v254, 27
	v_mbcnt_lo_u32_b32 v0, -1, 0
	v_mbcnt_hi_u32_b32 v0, -1, v0
	s_addc_u32 s5, s23, s5
	v_add_u32_e32 v16, s46, v0
	s_or_b32 s0, s10, s0
	s_or_b32 s0, s0, s7
	v_and_b32_e32 v15, 31, v16
	v_or_b32_e32 v14, s0, v15
	v_mov_b64_e32 v[2:3], s[82:83]
	v_mad_u64_u32 v[2:3], s[10:11], v14, s8, v[2:3]
	s_lshl_b32 s0, s6, 7
	v_lshl_add_u64 v[2:3], v[2:3], 0, s[0:1]
	s_lshl_b32 s0, s6, 2
	v_ashrrev_i32_e32 v22, 31, v16
	v_mov_b32_e32 v17, s0
	s_lshl_b32 s0, s12, 7
	v_lshrrev_b32_e32 v18, 29, v22
	s_add_u32 s0, s82, s0
	v_add_u32_e32 v20, v16, v18
	s_addc_u32 s11, s83, 0
	v_ashrrev_i32_e32 v44, 3, v20
	v_and_b32_e32 v20, -8, v20
	s_waitcnt vmcnt(9)
	v_bfe_u32 v102, v16, 5, 1
	s_add_u32 s10, s0, 0x1400
	v_sub_u32_e32 v45, v16, v20
	v_lshrrev_b32_e32 v22, 28, v22
	v_lshlrev_b32_e32 v0, 4, v102
	s_addc_u32 s11, s11, 0
	v_lshlrev_b32_e32 v20, 3, v45
	v_add_u32_e32 v24, v16, v22
	v_lshl_add_u64 v[2:3], v[2:3], 0, v[0:1]
	v_add_u32_e32 v18, s7, v44
	v_mov_b64_e32 v[34:35], s[10:11]
	v_ashrrev_i32_e32 v21, 31, v20
	v_ashrrev_i32_e32 v46, 4, v24
	v_and_b32_e32 v24, -16, v24
	v_lshl_add_u64 v[4:5], v[2:3], 0, s[18:19]
	v_add_co_u32_e32 v2, vcc, s9, v2
	v_mad_i64_i32 v[18:19], s[10:11], v18, s8, v[34:35]
	v_lshlrev_b64 v[36:37], 1, v[20:21]
	v_sub_u32_e32 v47, v16, v24
	v_add_u32_e32 v16, 0x200, v16
	v_addc_co_u32_e32 v3, vcc, 0, v3, vcc
	v_lshl_add_u64 v[18:19], v[18:19], 0, v[36:37]
	v_ashrrev_i32_e32 v32, 31, v16
	global_load_dwordx4 v[80:83], v[2:3], off
	global_load_dwordx4 v[10:13], v[4:5], off offset:32
	global_load_dwordx4 v[6:9], v[4:5], off offset:64
	s_nop 0
	global_load_dwordx4 v[2:5], v[4:5], off offset:96
	v_mov_b64_e32 v[30:31], s[4:5]
	global_load_dwordx4 v[18:21], v[18:19], off
	v_lshlrev_b32_e32 v24, 3, v47
	v_lshrrev_b32_e32 v26, 29, v32
	v_mad_i64_i32 v[22:23], s[4:5], v46, s14, v[30:31]
	v_ashrrev_i32_e32 v25, 31, v24
	v_add_u32_e32 v28, v16, v26
	v_lshrrev_b32_e32 v32, 28, v32
	v_lshl_add_u64 v[38:39], v[24:25], 1, v[22:23]
	v_ashrrev_i32_e32 v48, 3, v28
	v_and_b32_e32 v28, -8, v28
	v_add_u32_e32 v32, v16, v32
	global_load_dwordx4 v[22:25], v[38:39], off
	v_sub_u32_e32 v49, v16, v28
	v_ashrrev_i32_e32 v50, 4, v32
	v_and_b32_e32 v32, -16, v32
	v_lshlrev_b32_e32 v28, 3, v49
	v_sub_u32_e32 v16, v16, v32
	v_add_u32_e32 v26, s7, v48
	v_ashrrev_i32_e32 v29, 31, v28
	v_lshlrev_b32_e32 v32, 3, v16
	v_mad_i64_i32 v[26:27], s[4:5], v26, s8, v[34:35]
	v_lshlrev_b64 v[40:41], 1, v[28:29]
	v_mad_i64_i32 v[30:31], s[4:5], v50, s14, v[30:31]
	v_ashrrev_i32_e32 v33, 31, v32
	v_lshl_add_u64 v[26:27], v[26:27], 0, v[40:41]
	v_lshl_add_u64 v[42:43], v[32:33], 1, v[30:31]
	global_load_dwordx4 v[26:29], v[26:27], off
	v_mul_lo_u32 v51, v44, s15
	global_load_dwordx4 v[30:33], v[42:43], off
	v_add_u32_e32 v51, 0, v51
	v_lshlrev_b32_e32 v45, 4, v45
	v_add_u32_e32 v104, v51, v45
	v_lshlrev_b32_e32 v106, 4, v47
	v_cmp_eq_u32_e32 vcc, 0, v102
	s_waitcnt vmcnt(16)
	v_lshlrev_b32_e32 v109, 4, v16
	s_bitset1_b32 s7, 7
	v_cndmask_b32_e64 v64, 0, 1.0, vcc
	v_cmp_lt_i32_e32 vcc, v127, v128
	v_readlane_b32 s48, v253, 29
	v_add_u32_e32 v0, 0, v0
	v_readlane_b32 s58, v253, 39
	v_readlane_b32 s59, v253, 40
	v_readlane_b32 s49, v253, 30
	v_readlane_b32 s50, v253, 31
	v_readlane_b32 s51, v253, 32
	v_readlane_b32 s52, v253, 33
	v_readlane_b32 s53, v253, 34
	global_load_dword v17, v17, s[58:59]
	v_readlane_b32 s54, v253, 35
	v_readlane_b32 s55, v253, 36
	v_readlane_b32 s56, v253, 37
	v_readlane_b32 s57, v253, 38
	v_readlane_b32 s60, v253, 41
	v_readlane_b32 s61, v253, 42
	v_readlane_b32 s62, v253, 43
	v_readlane_b32 s63, v253, 44
	s_waitcnt vmcnt(4)
	ds_write_b128 v104, v[18:21]
	v_mul_lo_u32 v18, v46, s16
	v_add_u32_e32 v105, 0, v18
	v_add3_u32 v18, v105, v106, s17
	v_lshlrev_b32_e32 v19, 4, v49
	s_waitcnt vmcnt(3)
	ds_write2_b64 v18, v[22:23], v[24:25] offset1:1
	v_mul_lo_u32 v18, v48, s15
	v_add_u32_e32 v18, 0, v18
	v_add_u32_e32 v107, v18, v19
	v_mul_lo_u32 v18, v50, s16
	v_add_u32_e32 v108, 0, v18
	v_add3_u32 v16, v108, v109, s17
	s_waitcnt vmcnt(2)
	ds_write_b128 v107, v[26:29]
	s_waitcnt vmcnt(1)
	ds_write2_b64 v16, v[30:31], v[32:33] offset1:1
	v_cndmask_b32_e32 v16, v126, v127, vcc
	v_lshlrev_b32_e32 v103, 2, v16
	v_add_u32_e32 v16, s7, v48
	v_mad_i64_i32 v[18:19], s[4:5], v16, s8, v[34:35]
	v_add_u32_e32 v16, s7, v44
	v_mad_i64_i32 v[20:21], s[4:5], v16, s8, v[34:35]
	v_lshl_add_u64 v[18:19], v[18:19], 0, v[40:41]
	v_lshl_add_u64 v[20:21], v[20:21], 0, v[36:37]
	v_mad_u32_u24 v16, v15, s15, v0
	s_waitcnt lgkmcnt(0)
	s_barrier
; template <int D, int MODE, int NSUB>
; DI void attn_item(const bf16* QKV, int pitch, int qcol0, int kcol0, const bf16* VT, bf16* O, int ocol0, const float* sink,
;                   LAS unsigned char* lds, int item, int tid_in, int lane_in, int wave) {
;     ...
;         if (t + 1 < nt) ATT_LOAD(t + 1);
;         const LAS bf16* Kt = (const LAS bf16*)(lds + (t & 1) * BUF); const LAS bf16* Vt = (const LAS bf16*)(lds + (t & 1) * BUF + KBYTES);
; #pragma unroll
;         for (int sub = 0; sub < NSUB; ++sub) {
;         f32x16 s[2];
; #pragma unroll
;         for (int q = 0; q < 2; ++q) { s[q] = zero16(); const LAS bf16* kp = Kt + (64 * sub + 32 * q + r) * KP + 8 * h;
; #pragma unroll
;             for (int ks = 0; ks < NKS; ++ks) s[q] = MFMA32(*(const LAS bf16x8*)(kp + 16 * ks), qf[ks], s[q]); }
;         if (MODE == 1 && KT * t >= CTXL) { const int kp0 = wstart + KT * t + 64 * sub - CTXL - qpos;
; #pragma unroll
;             for (int q = 0; q < 2; ++q)
; #pragma unroll
;                 for (int i = 0; i < 16; ++i) { const int d0 = kp0 + 32 * q + crow(i, h); if (d0 > 128 || d0 < -128) s[q][i] = -INFINITY; } }
;         float mx = s[0][0];
; #pragma unroll
;         for (int q = 0; q < 2; ++q)
; #pragma unroll
;             for (int i = 0; i < 16; ++i) mx = fmaxf(mx, s[q][i]);
;         mx = fmaxf(mx, __shfl_xor(mx, 32)) * scl;
;         if (!__all(mx - mrun <= THR2)) {
;             const float mnew = fmaxf(mrun, mx), alpha = __builtin_amdgcn_exp2f(mrun - mnew);
;             lrun *= alpha; mrun = mnew;
; #pragma unroll
;             for (int dt = 0; dt < NDT; ++dt)
; #pragma unroll
;                 for (int i = 0; i < 16; ++i) o[dt][i] *= alpha;
;         }
;         float ls = 0.f; const float nm = -mrun;
; #pragma unroll
;         for (int q = 0; q < 2; ++q)
; #pragma unroll
;             for (int i = 0; i < 16; ++i) { s[q][i] = __builtin_amdgcn_exp2f(fmaf(s[q][i], scl, nm)); ls += s[q][i]; }
;         lrun += ls;
; #pragma unroll
;         for (int q = 0; q < 2; ++q)
; #pragma unroll
;             for (int s2 = 0; s2 < 2; ++s2) {
;                 u32x4 pw; pw.x = cvtpk(s[q][8 * s2], s[q][8 * s2 + 1]); pw.y = cvtpk(s[q][8 * s2 + 2], s[q][8 * s2 + 3]); pw.z = cvtpk(s[q][8 * s2 + 4], s[q][8 * s2 + 5]); pw.w = cvtpk(s[q][8 * s2 + 6], s[q][8 * s2 + 7]);
;                 const bf16x8 pb = __builtin_bit_cast(bf16x8, pw);
; #pragma unroll
	global_load_dwordx4 v[96:99], v[20:21], off
	global_load_dwordx4 v[88:91], v[38:39], off offset:256
	global_load_dwordx4 v[92:95], v[18:19], off
	global_load_dwordx4 v[84:87], v[42:43], off offset:256
	ds_read_b128 v[172:175], v16
	ds_read_b128 v[176:179], v16 offset:32
	s_waitcnt lgkmcnt(1)
	v_mfma_f32_32x32x16_bf16 v[48:63], v[172:175], v[80:83], 0
	ds_read_b128 v[180:183], v16 offset:64
	s_waitcnt lgkmcnt(1)
	v_mfma_f32_32x32x16_bf16 v[48:63], v[176:179], v[10:13], v[48:63]
	s_waitcnt lgkmcnt(0)
	v_mfma_f32_32x32x16_bf16 v[48:63], v[180:183], v[6:9], v[48:63]
	ds_read_b128 v[184:187], v16 offset:96
	s_waitcnt lgkmcnt(0)
	v_mfma_f32_32x32x16_bf16 v[48:63], v[184:187], v[2:5], v[48:63]
	ds_read_b128 v[192:195], v16 offset:4608
	s_waitcnt lgkmcnt(0)
	v_mfma_f32_32x32x16_bf16 v[32:47], v[192:195], v[80:83], 0
	ds_read_b128 v[196:199], v16 offset:4640
	s_waitcnt lgkmcnt(0)
	v_mfma_f32_32x32x16_bf16 v[32:47], v[196:199], v[10:13], v[32:47]
	ds_read_b128 v[200:203], v16 offset:4672
	s_waitcnt lgkmcnt(0)
	v_mfma_f32_32x32x16_bf16 v[32:47], v[200:203], v[6:9], v[32:47]
	ds_read_b128 v[204:207], v16 offset:4704
	s_nop 1
	v_max_f32_e32 v16, v49, v49
	s_waitcnt lgkmcnt(0)
	v_mfma_f32_32x32x16_bf16 v[32:47], v[204:207], v[2:5], v[32:47]
	v_max_f32_e32 v18, v48, v48
	v_max_f32_e32 v16, v18, v16
	v_max3_f32 v16, v16, v50, v51
	v_max3_f32 v16, v16, v52, v53
	v_max3_f32 v16, v16, v54, v55
	v_max3_f32 v16, v16, v56, v57
	v_max3_f32 v16, v16, v58, v59
	v_max3_f32 v16, v16, v60, v61
	v_max3_f32 v16, v16, v62, v63
	s_nop 2
	v_max3_f32 v16, v16, v32, v33
	v_max3_f32 v16, v16, v34, v35
	v_max3_f32 v16, v16, v36, v37
	v_max3_f32 v16, v16, v38, v39
	v_max3_f32 v16, v16, v40, v41
	v_max3_f32 v16, v16, v42, v43
	v_max3_f32 v16, v16, v44, v45
	v_max3_f32 v16, v16, v46, v47
	ds_bpermute_b32 v18, v103, v16
	s_waitcnt lgkmcnt(0)
	v_max_f32_e32 v18, v18, v18
	v_max_f32_e32 v16, v16, v18
	s_waitcnt vmcnt(4)
	v_pk_mul_f32 v[100:101], v[16:17], s[20:21]
	s_nop 0
	v_sub_f32_e32 v16, v100, v101
	v_cmp_ge_f32_e32 vcc, s33, v16
	v_mov_b32_e32 v16, 0
	s_cmp_eq_u64 vcc, exec
	s_cbranch_scc1 .LBB0_837
	v_max_f32_e32 v16, v101, v101
	v_max_f32_e32 v17, v100, v100
	v_max_f32_e32 v17, v16, v17
	v_sub_f32_e32 v16, v101, v17
	v_exp_f32_e32 v18, v16
	v_mov_b32_e32 v101, v17
	v_mul_f32_e32 v16, 0, v18
	v_mul_f32_e32 v64, v64, v18
.LBB0_837:
	v_fma_f32 v48, v48, s20, -v101
	v_exp_f32_e32 v48, v48
	v_fma_f32 v49, v49, s20, -v101
	v_exp_f32_e32 v49, v49
	v_fma_f32 v50, v50, s20, -v101
	v_exp_f32_e32 v50, v50
	v_fma_f32 v51, v51, s20, -v101
	v_exp_f32_e32 v51, v51
	v_fma_f32 v52, v52, s20, -v101
	v_add_f32_e32 v67, 0, v48
	v_exp_f32_e32 v52, v52
	v_fma_f32 v53, v53, s20, -v101
	v_add_f32_e32 v67, v49, v67
	v_exp_f32_e32 v53, v53
	v_fma_f32 v54, v54, s20, -v101
	v_add_f32_e32 v67, v50, v67
	v_exp_f32_e32 v54, v54
	v_fma_f32 v55, v55, s20, -v101
	v_add_f32_e32 v67, v51, v67
	v_exp_f32_e32 v55, v55
	v_fma_f32 v56, v56, s20, -v101
	v_add_f32_e32 v67, v52, v67
	v_exp_f32_e32 v68, v56
	v_add_f32_e32 v67, v53, v67
	v_add_f32_e32 v67, v54, v67
	v_fma_f32 v32, v32, s20, -v101
	v_add_f32_e32 v67, v55, v67
	v_fma_f32 v57, v57, s20, -v101
	v_exp_f32_e32 v72, v32
	v_fma_f32 v32, v33, s20, -v101
	v_add_f32_e32 v56, v68, v67
	v_exp_f32_e32 v67, v57
	v_fma_f32 v57, v58, s20, -v101
	v_exp_f32_e32 v73, v32
	v_fma_f32 v32, v34, s20, -v101
	v_exp_f32_e32 v69, v57
	v_fma_f32 v57, v59, s20, -v101
	v_exp_f32_e32 v74, v32
	v_fma_f32 v32, v35, s20, -v101
	v_exp_f32_e32 v70, v57
	v_fma_f32 v57, v60, s20, -v101
	v_exp_f32_e32 v75, v32
	v_fma_f32 v32, v36, s20, -v101
	v_exp_f32_e32 v60, v57
	v_fma_f32 v57, v61, s20, -v101
	v_exp_f32_e32 v76, v32
	v_fma_f32 v32, v37, s20, -v101
	v_add_f32_e32 v56, v67, v56
	v_exp_f32_e32 v61, v57
	v_fma_f32 v57, v62, s20, -v101
	v_exp_f32_e32 v77, v32
	v_fma_f32 v32, v38, s20, -v101
	v_add_f32_e32 v56, v69, v56
	v_exp_f32_e32 v62, v57
	v_fma_f32 v57, v63, s20, -v101
	v_exp_f32_e32 v78, v32
	v_fma_f32 v32, v39, s20, -v101
	v_lshlrev_b32_e32 v17, 3, v102
	v_add_f32_e32 v56, v70, v56
	v_exp_f32_e32 v63, v57
	v_exp_f32_e32 v79, v32
	v_fma_f32 v32, v40, s20, -v101
	v_sub_u32_e32 v66, v0, v17
	v_add_f32_e32 v56, v60, v56
	v_exp_f32_e32 v111, v32
	v_fma_f32 v32, v41, s20, -v101
	v_mul_u32_u24_e32 v65, 0x90, v15
	v_add_f32_e32 v56, v61, v56
	v_exp_f32_e32 v112, v32
	v_fma_f32 v32, v42, s20, -v101
	v_mad_u32_u24 v15, v15, s16, v66
	v_add_f32_e32 v56, v62, v56
	v_exp_f32_e32 v113, v32
	v_fma_f32 v32, v43, s20, -v101
	v_add_u32_e32 v100, 0x4800, v15
	v_add_f32_e32 v71, v63, v56
	v_exp_f32_e32 v114, v32
	v_fma_f32 v32, v44, s20, -v101
	v_cvt_pk_bf16_f32 v48, v48, v49
	v_cvt_pk_bf16_f32 v49, v50, v51
	v_cvt_pk_bf16_f32 v50, v52, v53
	v_cvt_pk_bf16_f32 v51, v54, v55
	ds_read2_b64 v[172:175], v100 offset1:2
	ds_read2_b64 v[176:179], v100 offset0:4 offset1:6
	v_exp_f32_e32 v115, v32
	v_fma_f32 v32, v45, s20, -v101
	v_exp_f32_e32 v116, v32
	v_fma_f32 v32, v46, s20, -v101
	v_mov_b32_e32 v17, v16
	v_mov_b32_e32 v18, v16
	v_mov_b32_e32 v19, v16
	v_mov_b32_e32 v20, v16
	v_mov_b32_e32 v21, v16
	v_mov_b32_e32 v22, v16
	v_mov_b32_e32 v23, v16
	v_mov_b32_e32 v24, v16
	v_mov_b32_e32 v25, v16
	v_mov_b32_e32 v26, v16
	v_mov_b32_e32 v27, v16
	v_mov_b32_e32 v28, v16
	v_mov_b32_e32 v29, v16
	v_mov_b32_e32 v30, v16
	v_mov_b32_e32 v31, v16
	v_exp_f32_e32 v117, v32
	v_fma_f32 v32, v47, s20, -v101
	v_add_u32_e32 v110, 0x6800, v15
	ds_read2_b64 v[180:183], v110 offset0:32 offset1:34
	ds_read2_b64 v[184:187], v110 offset0:36 offset1:38
	ds_read2_b64 v[192:195], v100 offset0:8 offset1:10
	ds_read2_b64 v[196:199], v110 offset0:40 offset1:42
	v_exp_f32_e32 v118, v32
	s_waitcnt lgkmcnt(5)
; #define LAS __attribute__((address_space(3)))
; template <int D, int MODE, int NSUB>
; DI void attn_item(const bf16* QKV, int pitch, int qcol0, int kcol0, const bf16* VT, bf16* O, int ocol0, const float* sink,
;                   LAS unsigned char* lds, int item, int tid_in, int lane_in, int wave) {
;     ...
;         for (int sub = 0; sub < NSUB; ++sub) {
;         f32x16 s[2];
; #pragma unroll
;         for (int q = 0; q < 2; ++q) { s[q] = zero16(); const LAS bf16* kp = Kt + (64 * sub + 32 * q + r) * KP + 8 * h;
; #pragma unroll
;             for (int ks = 0; ks < NKS; ++ks) s[q] = MFMA32(*(const LAS bf16x8*)(kp + 16 * ks), qf[ks], s[q]); }
;         if (MODE == 1 && KT * t >= CTXL) { const int kp0 = wstart + KT * t + 64 * sub - CTXL - qpos;
; #pragma unroll
;             for (int q = 0; q < 2; ++q)
; #pragma unroll
;                 for (int i = 0; i < 16; ++i) { const int d0 = kp0 + 32 * q + crow(i, h); if (d0 > 128 || d0 < -128) s[q][i] = -INFINITY; } }
;         float mx = s[0][0];
; #pragma unroll
;         for (int q = 0; q < 2; ++q)
; #pragma unroll
;             for (int i = 0; i < 16; ++i) mx = fmaxf(mx, s[q][i]);
;         mx = fmaxf(mx, __shfl_xor(mx, 32)) * scl;
;         if (!__all(mx - mrun <= THR2)) {
;             const float mnew = fmaxf(mrun, mx), alpha = __builtin_amdgcn_exp2f(mrun - mnew);
;             lrun *= alpha; mrun = mnew;
; #pragma unroll
;             for (int dt = 0; dt < NDT; ++dt)
; #pragma unroll
;                 for (int i = 0; i < 16; ++i) o[dt][i] *= alpha;
;         }
;         float ls = 0.f; const float nm = -mrun;
; #pragma unroll
;         for (int q = 0; q < 2; ++q)
; #pragma unroll
;             for (int i = 0; i < 16; ++i) { s[q][i] = __builtin_amdgcn_exp2f(fmaf(s[q][i], scl, nm)); ls += s[q][i]; }
;         lrun += ls;
; #pragma unroll
;         for (int q = 0; q < 2; ++q)
; #pragma unroll
;             for (int s2 = 0; s2 < 2; ++s2) {
;                 u32x4 pw; pw.x = cvtpk(s[q][8 * s2], s[q][8 * s2 + 1]); pw.y = cvtpk(s[q][8 * s2 + 2], s[q][8 * s2 + 3]); pw.z = cvtpk(s[q][8 * s2 + 4], s[q][8 * s2 + 5]); pw.w = cvtpk(s[q][8 * s2 + 6], s[q][8 * s2 + 7]);
;                 const bf16x8 pb = __builtin_bit_cast(bf16x8, pw);
; #pragma unroll
;                 for (int dt = 0; dt < NDT; ++dt) { const LAS bf16* vp = Vt + (32 * dt + r) * VP + 64 * sub + 32 * q + 16 * s2 + 4 * h;
	v_mfma_f32_32x32x16_bf16 v[32:47], v[172:175], v[48:51], v[16:31]
	ds_read2_b64 v[200:203], v100 offset0:12 offset1:14
	v_add_u32_e32 v0, v0, v65
	s_waitcnt lgkmcnt(4)
	v_mfma_f32_32x32x16_bf16 v[16:31], v[180:183], v[48:51], v[16:31]
	ds_read2_b64 v[204:207], v110 offset0:44 offset1:46
	v_cvt_pk_bf16_f32 v48, v68, v67
	v_cvt_pk_bf16_f32 v49, v69, v70
	v_cvt_pk_bf16_f32 v50, v60, v61
	v_cvt_pk_bf16_f32 v51, v62, v63
	s_nop 0
	s_waitcnt lgkmcnt(4)
	v_mfma_f32_32x32x16_bf16 v[16:31], v[184:187], v[48:51], v[16:31]
	s_waitcnt lgkmcnt(6)
	v_mfma_f32_32x32x16_bf16 v[32:47], v[176:179], v[48:51], v[32:47]
	v_cvt_pk_bf16_f32 v48, v72, v73
	v_cvt_pk_bf16_f32 v49, v74, v75
	v_cvt_pk_bf16_f32 v50, v76, v77
	v_cvt_pk_bf16_f32 v51, v78, v79
	s_nop 0
	s_waitcnt lgkmcnt(3)
	v_mfma_f32_32x32x16_bf16 v[32:47], v[192:195], v[48:51], v[32:47]
	s_waitcnt lgkmcnt(2)
	v_mfma_f32_32x32x16_bf16 v[16:31], v[196:199], v[48:51], v[16:31]
	v_cvt_pk_bf16_f32 v48, v111, v112
	v_cvt_pk_bf16_f32 v49, v113, v114
	v_cvt_pk_bf16_f32 v50, v115, v116
	v_cvt_pk_bf16_f32 v51, v117, v118
	s_nop 0
	s_waitcnt lgkmcnt(1)
	v_mfma_f32_32x32x16_bf16 v[32:47], v[200:203], v[48:51], v[32:47]
	s_waitcnt lgkmcnt(0)
	v_mfma_f32_32x32x16_bf16 v[16:31], v[204:207], v[48:51], v[16:31]
	v_add_f32_e32 v48, v72, v71
	v_add_f32_e32 v48, v73, v48
	v_add_f32_e32 v48, v74, v48
	v_add_f32_e32 v48, v75, v48
	v_add_f32_e32 v48, v76, v48
	v_add_f32_e32 v48, v77, v48
	v_add_f32_e32 v48, v78, v48
	v_add_f32_e32 v48, v79, v48
	v_add_f32_e32 v48, v111, v48
	v_add_f32_e32 v48, v112, v48
	v_add_f32_e32 v48, v113, v48
	v_add_f32_e32 v48, v114, v48
	v_add_f32_e32 v48, v115, v48
	v_add_f32_e32 v48, v116, v48
	v_add_f32_e32 v48, v117, v48
	v_add_f32_e32 v48, v118, v48
	v_add_f32_e32 v111, v64, v48
	ds_read_b128 v[172:175], v0 offset:9216
	ds_read_b128 v[176:179], v0 offset:9248
	ds_read_b128 v[180:183], v0 offset:9280
	ds_read_b128 v[184:187], v0 offset:13856
	ds_read_b128 v[192:195], v0 offset:9312
	ds_read_b128 v[196:199], v0 offset:13824
	s_waitcnt lgkmcnt(5)
	v_mfma_f32_32x32x16_bf16 v[64:79], v[172:175], v[80:83], 0
	ds_read_b128 v[200:203], v0 offset:13888
	s_waitcnt lgkmcnt(5)
	v_mfma_f32_32x32x16_bf16 v[64:79], v[176:179], v[10:13], v[64:79]
	ds_read_b128 v[204:207], v0 offset:13920
	s_waitcnt lgkmcnt(5)
	v_mfma_f32_32x32x16_bf16 v[64:79], v[180:183], v[6:9], v[64:79]
	s_waitcnt lgkmcnt(3)
	v_mfma_f32_32x32x16_bf16 v[64:79], v[192:195], v[2:5], v[64:79]
	s_waitcnt lgkmcnt(2)
	v_mfma_f32_32x32x16_bf16 v[48:63], v[196:199], v[80:83], 0
	s_waitcnt lgkmcnt(4)
	v_mfma_f32_32x32x16_bf16 v[48:63], v[184:187], v[10:13], v[48:63]
	s_waitcnt lgkmcnt(1)
	v_mfma_f32_32x32x16_bf16 v[48:63], v[200:203], v[6:9], v[48:63]
	s_waitcnt lgkmcnt(0)
	v_mfma_f32_32x32x16_bf16 v[48:63], v[204:207], v[2:5], v[48:63]
	s_nop 1
	v_max_f32_e32 v112, v65, v65
	v_max_f32_e32 v113, v64, v64
	v_max_f32_e32 v112, v113, v112
	v_max3_f32 v112, v112, v66, v67
	v_max3_f32 v112, v112, v68, v69
	v_max3_f32 v112, v112, v70, v71
	v_max3_f32 v112, v112, v72, v73
	v_max3_f32 v112, v112, v74, v75
	v_max3_f32 v112, v112, v76, v77
	v_max3_f32 v112, v112, v78, v79
	v_max3_f32 v112, v112, v48, v49
	v_max3_f32 v112, v112, v50, v51
	v_max3_f32 v112, v112, v52, v53
	v_max3_f32 v112, v112, v54, v55
	v_max3_f32 v112, v112, v56, v57
	v_max3_f32 v112, v112, v58, v59
	v_max3_f32 v112, v112, v60, v61
	v_max3_f32 v112, v112, v62, v63
	ds_bpermute_b32 v113, v103, v112
	s_waitcnt lgkmcnt(0)
	v_max_f32_e32 v113, v113, v113
	v_max_f32_e32 v112, v112, v113
	v_fma_f32 v113, v112, s20, -v101
	v_cmp_ge_f32_e32 vcc, s33, v113
	s_cmp_eq_u64 vcc, exec
	s_cbranch_scc1 .LBB0_839
	v_mul_f32_e32 v112, 0x3e38aa3b, v112
	v_max_f32_e32 v112, v112, v112
	v_max_f32_e32 v113, v101, v101
	v_max_f32_e32 v113, v113, v112
	v_sub_f32_e32 v101, v101, v113
	v_exp_f32_e32 v112, v101
	v_mov_b32_e32 v101, v113
	v_pk_mul_f32 v[46:47], v[46:47], v[112:113] op_sel_hi:[1,0]
	v_pk_mul_f32 v[44:45], v[44:45], v[112:113] op_sel_hi:[1,0]
	v_pk_mul_f32 v[42:43], v[42:43], v[112:113] op_sel_hi:[1,0]
	v_pk_mul_f32 v[40:41], v[40:41], v[112:113] op_sel_hi:[1,0]
	v_pk_mul_f32 v[38:39], v[38:39], v[112:113] op_sel_hi:[1,0]
	v_pk_mul_f32 v[36:37], v[36:37], v[112:113] op_sel_hi:[1,0]
	v_pk_mul_f32 v[34:35], v[34:35], v[112:113] op_sel_hi:[1,0]
	v_pk_mul_f32 v[32:33], v[32:33], v[112:113] op_sel_hi:[1,0]
	v_pk_mul_f32 v[30:31], v[30:31], v[112:113] op_sel_hi:[1,0]
	v_pk_mul_f32 v[28:29], v[28:29], v[112:113] op_sel_hi:[1,0]
	v_pk_mul_f32 v[26:27], v[26:27], v[112:113] op_sel_hi:[1,0]
	v_pk_mul_f32 v[24:25], v[24:25], v[112:113] op_sel_hi:[1,0]
	v_pk_mul_f32 v[22:23], v[22:23], v[112:113] op_sel_hi:[1,0]
	v_pk_mul_f32 v[20:21], v[20:21], v[112:113] op_sel_hi:[1,0]
	v_pk_mul_f32 v[18:19], v[18:19], v[112:113] op_sel_hi:[1,0]
	v_pk_mul_f32 v[16:17], v[16:17], v[112:113] op_sel_hi:[1,0]
	v_mul_f32_e32 v111, v111, v112
	v_xor_b32_e32 v112, 0x80000000, v113
	s_branch .LBB0_840

; #define LAS __attribute__((address_space(3)))
; #define MFMA32(a, b, c) __builtin_amdgcn_mfma_f32_32x32x16_bf16((a), (b), (c), 0, 0, 0)
; DI unsigned cvtpk(float lo, float hi) { f32x2 v = {lo, hi}; bf16x2_t b = __builtin_convertvector(v, bf16x2_t); return __builtin_bit_cast(unsigned, b); }
; template <int D, int MODE, int NSUB>
; DI void attn_item(const bf16* QKV, int pitch, int qcol0, int kcol0, const bf16* VT, bf16* O, int ocol0, const float* sink,
;                   LAS unsigned char* lds, int item, int tid_in, int lane_in, int wave) {
;     ...
;             const float mnew = fmaxf(mrun, mx), alpha = __builtin_amdgcn_exp2f(mrun - mnew);
;             lrun *= alpha; mrun = mnew;
; #pragma unroll
;             for (int dt = 0; dt < NDT; ++dt)
; #pragma unroll
;                 for (int i = 0; i < 16; ++i) o[dt][i] *= alpha;
;         }
;         float ls = 0.f; const float nm = -mrun;
; #pragma unroll
;         for (int q = 0; q < 2; ++q)
; #pragma unroll
;             for (int i = 0; i < 16; ++i) { s[q][i] = __builtin_amdgcn_exp2f(fmaf(s[q][i], scl, nm)); ls += s[q][i]; }
;         lrun += ls;
; #pragma unroll
;         for (int q = 0; q < 2; ++q)
; #pragma unroll
;             for (int s2 = 0; s2 < 2; ++s2) {
;                 u32x4 pw; pw.x = cvtpk(s[q][8 * s2], s[q][8 * s2 + 1]); pw.y = cvtpk(s[q][8 * s2 + 2], s[q][8 * s2 + 3]); pw.z = cvtpk(s[q][8 * s2 + 4], s[q][8 * s2 + 5]); pw.w = cvtpk(s[q][8 * s2 + 6], s[q][8 * s2 + 7]);
;                 const bf16x8 pb = __builtin_bit_cast(bf16x8, pw);
; #pragma unroll
;                 for (int dt = 0; dt < NDT; ++dt) { const LAS bf16* vp = Vt + (32 * dt + r) * VP + 64 * sub + 32 * q + 16 * s2 + 4 * h;
;                     const s16x4 lo = *(const LAS s16x4*)vp, hi = *(const LAS s16x4*)(vp + 8);
;                     const bf16x8 a = __builtin_shufflevector(lo, hi, 0, 1, 2, 3, 4, 5, 6, 7);
;                     o[dt] = MFMA32(a, pb, o[dt]); }
;             }
;         }
;         if (t + 1 < nt) ATT_STORE((t + 1) & 1);
.LBB0_840:
	v_fmamk_f32 v48, v48, 0x3e38aa3b, v112
	v_exp_f32_e32 v114, v48
	v_fmamk_f32 v48, v49, 0x3e38aa3b, v112
	v_exp_f32_e32 v115, v48
	v_fmamk_f32 v48, v50, 0x3e38aa3b, v112
	v_exp_f32_e32 v116, v48
	v_fmamk_f32 v48, v51, 0x3e38aa3b, v112
	v_exp_f32_e32 v117, v48
	v_fmamk_f32 v48, v52, 0x3e38aa3b, v112
	v_exp_f32_e32 v118, v48
	v_fmamk_f32 v48, v53, 0x3e38aa3b, v112
	v_exp_f32_e32 v119, v48
	v_fmamk_f32 v48, v54, 0x3e38aa3b, v112
	v_exp_f32_e32 v120, v48
	v_fmamk_f32 v48, v55, 0x3e38aa3b, v112
	v_exp_f32_e32 v121, v48
	v_fmamk_f32 v48, v56, 0x3e38aa3b, v112
	v_exp_f32_e32 v122, v48
	v_fmamk_f32 v48, v57, 0x3e38aa3b, v112
	v_fmamk_f32 v64, v64, 0x3e38aa3b, v112
	v_fmamk_f32 v65, v65, 0x3e38aa3b, v112
	v_fmamk_f32 v66, v66, 0x3e38aa3b, v112
	v_fmamk_f32 v67, v67, 0x3e38aa3b, v112
	v_fmamk_f32 v68, v68, 0x3e38aa3b, v112
	v_fmamk_f32 v69, v69, 0x3e38aa3b, v112
	v_fmamk_f32 v70, v70, 0x3e38aa3b, v112
	v_fmamk_f32 v71, v71, 0x3e38aa3b, v112
	v_exp_f32_e32 v123, v48
	v_fmamk_f32 v48, v58, 0x3e38aa3b, v112
	v_exp_f32_e32 v64, v64
	v_exp_f32_e32 v65, v65
	v_exp_f32_e32 v66, v66
	v_exp_f32_e32 v67, v67
	v_exp_f32_e32 v68, v68
	v_exp_f32_e32 v69, v69
	v_exp_f32_e32 v70, v70
	v_exp_f32_e32 v71, v71
	v_exp_f32_e32 v124, v48
	v_fmamk_f32 v48, v59, 0x3e38aa3b, v112
	v_exp_f32_e32 v125, v48
	v_fmamk_f32 v48, v60, 0x3e38aa3b, v112
	ds_read2_b64 v[172:175], v100 offset0:16 offset1:18
	ds_read2_b64 v[176:179], v100 offset0:20 offset1:22
	ds_read2_b64 v[180:183], v110 offset0:48 offset1:50
	ds_read2_b64 v[184:187], v110 offset0:52 offset1:54
	ds_read2_b64 v[192:195], v100 offset0:24 offset1:26
	ds_read2_b64 v[196:199], v110 offset0:56 offset1:58
	v_exp_f32_e32 v60, v48
	v_fmamk_f32 v48, v61, 0x3e38aa3b, v112
	v_exp_f32_e32 v61, v48
	v_fmamk_f32 v48, v62, 0x3e38aa3b, v112
	v_exp_f32_e32 v62, v48
	v_cvt_pk_bf16_f32 v48, v64, v65
	v_cvt_pk_bf16_f32 v49, v66, v67
	v_cvt_pk_bf16_f32 v50, v68, v69
	v_cvt_pk_bf16_f32 v51, v70, v71
	v_fmamk_f32 v72, v72, 0x3e38aa3b, v112
	v_fmamk_f32 v73, v73, 0x3e38aa3b, v112
	s_waitcnt lgkmcnt(5)
	v_mfma_f32_32x32x16_bf16 v[32:47], v[172:175], v[48:51], v[32:47]
	ds_read2_b64 v[200:203], v100 offset0:28 offset1:30
	v_fmamk_f32 v74, v74, 0x3e38aa3b, v112
	v_fmamk_f32 v75, v75, 0x3e38aa3b, v112
	v_fmamk_f32 v76, v76, 0x3e38aa3b, v112
	v_fmamk_f32 v77, v77, 0x3e38aa3b, v112
	v_fmamk_f32 v78, v78, 0x3e38aa3b, v112
	v_fmamk_f32 v79, v79, 0x3e38aa3b, v112
	s_waitcnt lgkmcnt(4)
	v_mfma_f32_32x32x16_bf16 v[16:31], v[180:183], v[48:51], v[16:31]
	v_exp_f32_e32 v72, v72
	v_exp_f32_e32 v73, v73
	v_exp_f32_e32 v74, v74
	v_exp_f32_e32 v75, v75
	v_exp_f32_e32 v76, v76
	v_exp_f32_e32 v77, v77
	v_exp_f32_e32 v78, v78
	v_exp_f32_e32 v79, v79
	v_cvt_pk_bf16_f32 v48, v72, v73
	v_cvt_pk_bf16_f32 v49, v74, v75
	v_cvt_pk_bf16_f32 v50, v76, v77
	v_cvt_pk_bf16_f32 v51, v78, v79
	v_add_f32_e32 v113, 0, v64
	v_add_f32_e32 v113, v65, v113
	s_waitcnt lgkmcnt(3)
	v_mfma_f32_32x32x16_bf16 v[16:31], v[184:187], v[48:51], v[16:31]
	v_fmac_f32_e32 v112, 0x3e38aa3b, v63
	v_add_f32_e32 v113, v66, v113
	v_exp_f32_e32 v63, v112
	v_add_f32_e32 v113, v67, v113
	v_add_f32_e32 v113, v68, v113
	v_add_f32_e32 v113, v69, v113
	s_waitcnt lgkmcnt(5)
	v_mfma_f32_32x32x16_bf16 v[32:47], v[176:179], v[48:51], v[32:47]
	v_cvt_pk_bf16_f32 v48, v114, v115
	v_cvt_pk_bf16_f32 v49, v116, v117
	v_cvt_pk_bf16_f32 v50, v118, v119
	v_cvt_pk_bf16_f32 v51, v120, v121
	v_add_f32_e32 v113, v70, v113
	v_add_f32_e32 v113, v71, v113
	v_add_f32_e32 v113, v72, v113
	s_waitcnt lgkmcnt(2)
	v_mfma_f32_32x32x16_bf16 v[32:47], v[192:195], v[48:51], v[32:47]
	v_add_f32_e32 v113, v73, v113
	v_add_f32_e32 v113, v74, v113
	v_add_f32_e32 v113, v75, v113
	v_add_f32_e32 v113, v76, v113
	v_add_f32_e32 v113, v77, v113
	v_add_f32_e32 v113, v78, v113
	s_waitcnt lgkmcnt(1)
	v_mfma_f32_32x32x16_bf16 v[16:31], v[196:199], v[48:51], v[16:31]
	v_cvt_pk_bf16_f32 v48, v122, v123
	v_cvt_pk_bf16_f32 v49, v124, v125
	v_cvt_pk_bf16_f32 v50, v60, v61
	v_cvt_pk_bf16_f32 v51, v62, v63
	v_add_f32_e32 v113, v79, v113
	s_waitcnt lgkmcnt(0)
	v_mfma_f32_32x32x16_bf16 v[32:47], v[200:203], v[48:51], v[32:47]
	ds_read2_b64 v[52:55], v110 offset0:60 offset1:62
	s_waitcnt vmcnt(3)
	ds_write_b128 v104, v[96:99] offset:35328
	s_waitcnt lgkmcnt(1)
	v_mfma_f32_32x32x16_bf16 v[16:31], v[52:55], v[48:51], v[16:31]
	v_add_f32_e32 v48, v114, v113
	v_add_f32_e32 v48, v115, v48
	v_add_f32_e32 v48, v116, v48
	v_add_f32_e32 v48, v117, v48
	v_add_f32_e32 v48, v118, v48
	v_add_f32_e32 v48, v119, v48
	v_add_f32_e32 v48, v120, v48
	v_add_f32_e32 v48, v121, v48
	v_add_f32_e32 v48, v122, v48
	v_add_f32_e32 v48, v123, v48
	v_add_f32_e32 v48, v124, v48
	v_add_f32_e32 v48, v125, v48
	v_add_f32_e32 v48, v60, v48
	v_add_f32_e32 v48, v61, v48
	v_add_f32_e32 v48, v62, v48
	v_add_f32_e32 v48, v63, v48
	v_add_f32_e32 v100, v111, v48
	v_add3_u32 v48, v105, v106, s38
	s_waitcnt vmcnt(2)
	ds_write2_b64 v48, v[88:89], v[90:91] offset1:1
	s_waitcnt vmcnt(1)
	ds_write_b128 v107, v[92:95] offset:35328
	v_add3_u32 v48, v108, v109, s38
	s_waitcnt vmcnt(0)
	ds_write2_b64 v48, v[84:85], v[86:87] offset1:1
	s_waitcnt lgkmcnt(0)
	s_barrier
; #define LAS __attribute__((address_space(3)))
; template <int D, int MODE, int NSUB>
; DI void attn_item(const bf16* QKV, int pitch, int qcol0, int kcol0, const bf16* VT, bf16* O, int ocol0, const float* sink,
;                   LAS unsigned char* lds, int item, int tid_in, int lane_in, int wave) {
;     ...
;         for (int sub = 0; sub < NSUB; ++sub) {
;         f32x16 s[2];
; #pragma unroll
;         for (int q = 0; q < 2; ++q) { s[q] = zero16(); const LAS bf16* kp = Kt + (64 * sub + 32 * q + r) * KP + 8 * h;
; #pragma unroll
;             for (int ks = 0; ks < NKS; ++ks) s[q] = MFMA32(*(const LAS bf16x8*)(kp + 16 * ks), qf[ks], s[q]); }
;         if (MODE == 1 && KT * t >= CTXL) { const int kp0 = wstart + KT * t + 64 * sub - CTXL - qpos;
; #pragma unroll
;             for (int q = 0; q < 2; ++q)
; #pragma unroll
;                 for (int i = 0; i < 16; ++i) { const int d0 = kp0 + 32 * q + crow(i, h); if (d0 > 128 || d0 < -128) s[q][i] = -INFINITY; } }
;         float mx = s[0][0];
; #pragma unroll
;         for (int q = 0; q < 2; ++q)
; #pragma unroll
;             for (int i = 0; i < 16; ++i) mx = fmaxf(mx, s[q][i]);
;         mx = fmaxf(mx, __shfl_xor(mx, 32)) * scl;
;         if (!__all(mx - mrun <= THR2)) {
;             const float mnew = fmaxf(mrun, mx), alpha = __builtin_amdgcn_exp2f(mrun - mnew);
;             lrun *= alpha; mrun = mnew;
; #pragma unroll
;             for (int dt = 0; dt < NDT; ++dt)
; #pragma unroll
;                 for (int i = 0; i < 16; ++i) o[dt][i] *= alpha;
;         }
;         float ls = 0.f; const float nm = -mrun;
; #pragma unroll
;         for (int q = 0; q < 2; ++q)
; #pragma unroll
;             for (int i = 0; i < 16; ++i) { s[q][i] = __builtin_amdgcn_exp2f(fmaf(s[q][i], scl, nm)); ls += s[q][i]; }
;         lrun += ls;
; #pragma unroll
;         for (int q = 0; q < 2; ++q)
; #pragma unroll
;             for (int s2 = 0; s2 < 2; ++s2) {
;                 u32x4 pw; pw.x = cvtpk(s[q][8 * s2], s[q][8 * s2 + 1]); pw.y = cvtpk(s[q][8 * s2 + 2], s[q][8 * s2 + 3]); pw.z = cvtpk(s[q][8 * s2 + 4], s[q][8 * s2 + 5]); pw.w = cvtpk(s[q][8 * s2 + 6], s[q][8 * s2 + 7]);
;                 const bf16x8 pb = __builtin_bit_cast(bf16x8, pw);
; #pragma unroll
;                 for (int dt = 0; dt < NDT; ++dt) { const LAS bf16* vp = Vt + (32 * dt + r) * VP + 64 * sub + 32 * q + 16 * s2 + 4 * h;
	ds_read_b128 v[172:175], v0 offset:35328
	ds_read_b128 v[176:179], v0 offset:35360
	ds_read_b128 v[180:183], v0 offset:35392
	ds_read_b128 v[184:187], v0 offset:39968
	ds_read_b128 v[192:195], v0 offset:35424
	ds_read_b128 v[196:199], v0 offset:39936
	s_waitcnt lgkmcnt(5)
	v_mfma_f32_32x32x16_bf16 v[64:79], v[172:175], v[80:83], 0
	ds_read_b128 v[200:203], v0 offset:40000
	s_waitcnt lgkmcnt(5)
	v_mfma_f32_32x32x16_bf16 v[64:79], v[176:179], v[10:13], v[64:79]
	ds_read_b128 v[204:207], v0 offset:40032
	s_waitcnt lgkmcnt(5)
	v_mfma_f32_32x32x16_bf16 v[64:79], v[180:183], v[6:9], v[64:79]
	s_waitcnt lgkmcnt(3)
	v_mfma_f32_32x32x16_bf16 v[64:79], v[192:195], v[2:5], v[64:79]
	s_waitcnt lgkmcnt(2)
	v_mfma_f32_32x32x16_bf16 v[48:63], v[196:199], v[80:83], 0
	s_waitcnt lgkmcnt(4)
	v_mfma_f32_32x32x16_bf16 v[48:63], v[184:187], v[10:13], v[48:63]
	s_waitcnt lgkmcnt(1)
	v_mfma_f32_32x32x16_bf16 v[48:63], v[200:203], v[6:9], v[48:63]
	s_waitcnt lgkmcnt(0)
	v_mfma_f32_32x32x16_bf16 v[48:63], v[204:207], v[2:5], v[48:63]
	s_nop 1
	v_max_f32_e32 v84, v65, v65
	v_max_f32_e32 v85, v64, v64
	v_max_f32_e32 v84, v85, v84
	v_max3_f32 v84, v84, v66, v67
	v_max3_f32 v84, v84, v68, v69
	v_max3_f32 v84, v84, v70, v71
	v_max3_f32 v84, v84, v72, v73
	v_max3_f32 v84, v84, v74, v75
	v_max3_f32 v84, v84, v76, v77
	v_max3_f32 v84, v84, v78, v79
	v_max3_f32 v84, v84, v48, v49
	v_max3_f32 v84, v84, v50, v51
	v_max3_f32 v84, v84, v52, v53
	v_max3_f32 v84, v84, v54, v55
	v_max3_f32 v84, v84, v56, v57
	v_max3_f32 v84, v84, v58, v59
	v_max3_f32 v84, v84, v60, v61
	v_max3_f32 v84, v84, v62, v63
	ds_bpermute_b32 v85, v103, v84
	s_waitcnt lgkmcnt(0)
	v_max_f32_e32 v85, v85, v85
	v_max_f32_e32 v84, v84, v85
	v_fma_f32 v85, v84, s20, -v101
	v_cmp_ge_f32_e32 vcc, s33, v85
	s_cmp_eq_u64 vcc, exec
	s_cbranch_scc1 .LBB0_842
	v_mul_f32_e32 v84, 0x3e38aa3b, v84
	v_max_f32_e32 v84, v84, v84
	v_max_f32_e32 v85, v101, v101
	v_max_f32_e32 v85, v85, v84
	v_sub_f32_e32 v84, v101, v85
	v_exp_f32_e32 v84, v84
	v_mov_b32_e32 v101, v85
	v_pk_mul_f32 v[46:47], v[46:47], v[84:85] op_sel_hi:[1,0]
	v_pk_mul_f32 v[44:45], v[44:45], v[84:85] op_sel_hi:[1,0]
	v_pk_mul_f32 v[42:43], v[42:43], v[84:85] op_sel_hi:[1,0]
	v_pk_mul_f32 v[40:41], v[40:41], v[84:85] op_sel_hi:[1,0]
	v_pk_mul_f32 v[38:39], v[38:39], v[84:85] op_sel_hi:[1,0]
	v_pk_mul_f32 v[36:37], v[36:37], v[84:85] op_sel_hi:[1,0]
	v_pk_mul_f32 v[34:35], v[34:35], v[84:85] op_sel_hi:[1,0]
	v_pk_mul_f32 v[32:33], v[32:33], v[84:85] op_sel_hi:[1,0]
	v_pk_mul_f32 v[30:31], v[30:31], v[84:85] op_sel_hi:[1,0]
	v_pk_mul_f32 v[28:29], v[28:29], v[84:85] op_sel_hi:[1,0]
	v_pk_mul_f32 v[26:27], v[26:27], v[84:85] op_sel_hi:[1,0]
	v_pk_mul_f32 v[24:25], v[24:25], v[84:85] op_sel_hi:[1,0]
	v_pk_mul_f32 v[22:23], v[22:23], v[84:85] op_sel_hi:[1,0]
	v_pk_mul_f32 v[20:21], v[20:21], v[84:85] op_sel_hi:[1,0]
	v_pk_mul_f32 v[18:19], v[18:19], v[84:85] op_sel_hi:[1,0]
	v_pk_mul_f32 v[16:17], v[16:17], v[84:85] op_sel_hi:[1,0]
	v_mul_f32_e32 v100, v100, v84
.LBB0_842:
	v_fma_f32 v64, v64, s20, -v101
	v_exp_f32_e32 v64, v64
	v_fma_f32 v65, v65, s20, -v101
	v_exp_f32_e32 v65, v65
	v_fma_f32 v66, v66, s20, -v101
	v_exp_f32_e32 v66, v66
	v_fma_f32 v67, v67, s20, -v101
	v_exp_f32_e32 v67, v67
	v_fma_f32 v68, v68, s20, -v101
	v_add_f32_e32 v84, 0, v64
	v_exp_f32_e32 v68, v68
	v_fma_f32 v69, v69, s20, -v101
	v_add_f32_e32 v84, v65, v84
	v_exp_f32_e32 v69, v69
	v_fma_f32 v70, v70, s20, -v101
	v_add_f32_e32 v84, v66, v84
	v_exp_f32_e32 v70, v70
	v_fma_f32 v71, v71, s20, -v101
	v_add_f32_e32 v84, v67, v84
	v_exp_f32_e32 v71, v71
	v_fma_f32 v72, v72, s20, -v101
	v_fma_f32 v48, v48, s20, -v101
	v_add_f32_e32 v84, v68, v84
	v_exp_f32_e32 v72, v72
	v_fma_f32 v73, v73, s20, -v101
	v_exp_f32_e32 v87, v48
	v_fma_f32 v48, v49, s20, -v101
	v_add_f32_e32 v84, v69, v84
	v_exp_f32_e32 v73, v73
	v_fma_f32 v74, v74, s20, -v101
	v_exp_f32_e32 v88, v48
	v_fma_f32 v48, v50, s20, -v101
	v_add_f32_e32 v84, v70, v84
	v_exp_f32_e32 v74, v74
	v_fma_f32 v75, v75, s20, -v101
	v_exp_f32_e32 v89, v48
	v_fma_f32 v48, v51, s20, -v101
	v_add_f32_e32 v84, v71, v84
	v_exp_f32_e32 v75, v75
	v_fma_f32 v76, v76, s20, -v101
	v_exp_f32_e32 v90, v48
	v_fma_f32 v48, v52, s20, -v101
	v_add_f32_e32 v84, v72, v84
	v_exp_f32_e32 v76, v76
	v_fma_f32 v77, v77, s20, -v101
	v_exp_f32_e32 v91, v48
	v_fma_f32 v48, v53, s20, -v101
	v_add_f32_e32 v84, v73, v84
	v_exp_f32_e32 v77, v77
	v_fma_f32 v78, v78, s20, -v101
	v_exp_f32_e32 v92, v48
	v_fma_f32 v48, v54, s20, -v101
	v_add_f32_e32 v84, v74, v84
	v_exp_f32_e32 v78, v78
	v_fma_f32 v79, v79, s20, -v101
	v_exp_f32_e32 v93, v48
	v_fma_f32 v48, v55, s20, -v101
	v_add_f32_e32 v84, v75, v84
	v_exp_f32_e32 v79, v79
	v_exp_f32_e32 v94, v48
	v_fma_f32 v48, v56, s20, -v101
	v_add_f32_e32 v84, v76, v84
	v_exp_f32_e32 v95, v48
	v_fma_f32 v48, v57, s20, -v101
	v_add_f32_e32 v84, v77, v84
	v_exp_f32_e32 v96, v48
	v_fma_f32 v48, v58, s20, -v101
	v_add_f32_e32 v84, v78, v84
	v_exp_f32_e32 v97, v48
	v_fma_f32 v48, v59, s20, -v101
	v_add_f32_e32 v86, v79, v84
	v_exp_f32_e32 v98, v48
	v_fma_f32 v48, v60, s20, -v101
	v_add_u32_e32 v84, 0xd000, v15
	v_exp_f32_e32 v60, v48
	v_fma_f32 v48, v61, s20, -v101
	ds_read2_b64 v[172:175], v84 offset0:64 offset1:66
	ds_read2_b64 v[176:179], v84 offset0:68 offset1:70
	v_exp_f32_e32 v61, v48
	v_fma_f32 v48, v62, s20, -v101
	v_exp_f32_e32 v62, v48
	v_fma_f32 v48, v63, s20, -v101
	v_exp_f32_e32 v63, v48
	v_cvt_pk_bf16_f32 v48, v64, v65
	v_cvt_pk_bf16_f32 v49, v66, v67
	v_cvt_pk_bf16_f32 v50, v68, v69
	v_cvt_pk_bf16_f32 v51, v70, v71
	v_add_u32_e32 v85, 0xf000, v15
	ds_read2_b64 v[180:183], v85 offset0:96 offset1:98
	ds_read2_b64 v[184:187], v85 offset0:100 offset1:102
	ds_read2_b64 v[192:195], v84 offset0:72 offset1:74
	ds_read2_b64 v[196:199], v85 offset0:104 offset1:106
	v_add_f32_e32 v15, v87, v86
	s_waitcnt lgkmcnt(5)
; #define LAS __attribute__((address_space(3)))
; template <int D, int MODE, int NSUB>
; DI void attn_item(const bf16* QKV, int pitch, int qcol0, int kcol0, const bf16* VT, bf16* O, int ocol0, const float* sink,
;                   LAS unsigned char* lds, int item, int tid_in, int lane_in, int wave) {
;     ...
;         for (int sub = 0; sub < NSUB; ++sub) {
;         f32x16 s[2];
; #pragma unroll
;         for (int q = 0; q < 2; ++q) { s[q] = zero16(); const LAS bf16* kp = Kt + (64 * sub + 32 * q + r) * KP + 8 * h;
; #pragma unroll
;             for (int ks = 0; ks < NKS; ++ks) s[q] = MFMA32(*(const LAS bf16x8*)(kp + 16 * ks), qf[ks], s[q]); }
;         if (MODE == 1 && KT * t >= CTXL) { const int kp0 = wstart + KT * t + 64 * sub - CTXL - qpos;
; #pragma unroll
;             for (int q = 0; q < 2; ++q)
; #pragma unroll
;                 for (int i = 0; i < 16; ++i) { const int d0 = kp0 + 32 * q + crow(i, h); if (d0 > 128 || d0 < -128) s[q][i] = -INFINITY; } }
;         float mx = s[0][0];
; #pragma unroll
;         for (int q = 0; q < 2; ++q)
; #pragma unroll
;             for (int i = 0; i < 16; ++i) mx = fmaxf(mx, s[q][i]);
;         mx = fmaxf(mx, __shfl_xor(mx, 32)) * scl;
;         if (!__all(mx - mrun <= THR2)) {
;             const float mnew = fmaxf(mrun, mx), alpha = __builtin_amdgcn_exp2f(mrun - mnew);
;             lrun *= alpha; mrun = mnew;
; #pragma unroll
;             for (int dt = 0; dt < NDT; ++dt)
; #pragma unroll
;                 for (int i = 0; i < 16; ++i) o[dt][i] *= alpha;
;         }
;         float ls = 0.f; const float nm = -mrun;
; #pragma unroll
;         for (int q = 0; q < 2; ++q)
; #pragma unroll
;             for (int i = 0; i < 16; ++i) { s[q][i] = __builtin_amdgcn_exp2f(fmaf(s[q][i], scl, nm)); ls += s[q][i]; }
;         lrun += ls;
; #pragma unroll
;         for (int q = 0; q < 2; ++q)
; #pragma unroll
;             for (int s2 = 0; s2 < 2; ++s2) {
;                 u32x4 pw; pw.x = cvtpk(s[q][8 * s2], s[q][8 * s2 + 1]); pw.y = cvtpk(s[q][8 * s2 + 2], s[q][8 * s2 + 3]); pw.z = cvtpk(s[q][8 * s2 + 4], s[q][8 * s2 + 5]); pw.w = cvtpk(s[q][8 * s2 + 6], s[q][8 * s2 + 7]);
;                 const bf16x8 pb = __builtin_bit_cast(bf16x8, pw);
; #pragma unroll
;                 for (int dt = 0; dt < NDT; ++dt) { const LAS bf16* vp = Vt + (32 * dt + r) * VP + 64 * sub + 32 * q + 16 * s2 + 4 * h;
	v_mfma_f32_32x32x16_bf16 v[32:47], v[172:175], v[48:51], v[32:47]
	ds_read2_b64 v[200:203], v84 offset0:76 offset1:78
	v_add_f32_e32 v15, v88, v15
	v_add_f32_e32 v15, v89, v15
	v_add_f32_e32 v15, v90, v15
	v_add_f32_e32 v15, v91, v15
	v_add_f32_e32 v15, v92, v15
	v_add_f32_e32 v15, v93, v15
	s_waitcnt lgkmcnt(4)
	v_mfma_f32_32x32x16_bf16 v[16:31], v[180:183], v[48:51], v[16:31]
	ds_read2_b64 v[204:207], v85 offset0:108 offset1:110
	v_cvt_pk_bf16_f32 v48, v72, v73
	v_cvt_pk_bf16_f32 v49, v74, v75
	v_cvt_pk_bf16_f32 v50, v76, v77
	v_cvt_pk_bf16_f32 v51, v78, v79
	v_add_f32_e32 v15, v94, v15
	v_add_f32_e32 v15, v95, v15
	s_waitcnt lgkmcnt(4)
	v_mfma_f32_32x32x16_bf16 v[16:31], v[184:187], v[48:51], v[16:31]
	v_add_f32_e32 v15, v96, v15
	v_add_f32_e32 v15, v97, v15
	v_add_f32_e32 v15, v98, v15
	v_add_f32_e32 v15, v60, v15
	v_add_f32_e32 v15, v61, v15
	v_add_f32_e32 v15, v62, v15
	s_waitcnt lgkmcnt(6)
	v_mfma_f32_32x32x16_bf16 v[32:47], v[176:179], v[48:51], v[32:47]
	v_cvt_pk_bf16_f32 v48, v87, v88
	v_cvt_pk_bf16_f32 v49, v89, v90
	v_cvt_pk_bf16_f32 v50, v91, v92
	v_cvt_pk_bf16_f32 v51, v93, v94
	v_add_f32_e32 v15, v63, v15
	v_add_f32_e32 v86, v100, v15
	s_waitcnt lgkmcnt(3)
	v_mfma_f32_32x32x16_bf16 v[32:47], v[192:195], v[48:51], v[32:47]
	s_waitcnt lgkmcnt(2)
	v_mfma_f32_32x32x16_bf16 v[16:31], v[196:199], v[48:51], v[16:31]
	v_cvt_pk_bf16_f32 v48, v95, v96
	v_cvt_pk_bf16_f32 v49, v97, v98
	v_cvt_pk_bf16_f32 v50, v60, v61
	v_cvt_pk_bf16_f32 v51, v62, v63
	s_nop 0
	s_waitcnt lgkmcnt(1)
	v_mfma_f32_32x32x16_bf16 v[32:47], v[200:203], v[48:51], v[32:47]
	s_waitcnt lgkmcnt(0)
	v_mfma_f32_32x32x16_bf16 v[16:31], v[204:207], v[48:51], v[16:31]
	ds_read_b128 v[208:211], v0 offset:44544
	ds_read_b128 v[212:215], v0 offset:44576
	s_waitcnt lgkmcnt(1)
	v_mfma_f32_32x32x16_bf16 v[64:79], v[208:211], v[80:83], 0
	ds_read_b128 v[220:223], v0 offset:44608
	s_waitcnt lgkmcnt(1)
	v_mfma_f32_32x32x16_bf16 v[64:79], v[212:215], v[10:13], v[64:79]
	s_waitcnt lgkmcnt(0)
	v_mfma_f32_32x32x16_bf16 v[64:79], v[220:223], v[6:9], v[64:79]
	ds_read_b128 v[224:227], v0 offset:44640
	s_waitcnt lgkmcnt(0)
	v_mfma_f32_32x32x16_bf16 v[64:79], v[224:227], v[2:5], v[64:79]
	ds_read_b128 v[228:231], v0 offset:49152
	s_waitcnt lgkmcnt(0)
	v_mfma_f32_32x32x16_bf16 v[48:63], v[228:231], v[80:83], 0
	ds_read_b128 v[232:235], v0 offset:49184
	s_waitcnt lgkmcnt(0)
	v_mfma_f32_32x32x16_bf16 v[48:63], v[232:235], v[10:13], v[48:63]
	ds_read_b128 v[236:239], v0 offset:49216
	s_waitcnt lgkmcnt(0)
	v_mfma_f32_32x32x16_bf16 v[48:63], v[236:239], v[6:9], v[48:63]
	ds_read_b128 v[240:243], v0 offset:49248
	s_nop 1
	v_max_f32_e32 v0, v65, v65
	s_waitcnt lgkmcnt(0)
	v_mfma_f32_32x32x16_bf16 v[48:63], v[240:243], v[2:5], v[48:63]
	v_max_f32_e32 v2, v64, v64
	v_max_f32_e32 v0, v2, v0
	v_max3_f32 v0, v0, v66, v67
	v_max3_f32 v0, v0, v68, v69
	v_max3_f32 v0, v0, v70, v71
	v_max3_f32 v0, v0, v72, v73
	v_max3_f32 v0, v0, v74, v75
	v_max3_f32 v0, v0, v76, v77
	v_max3_f32 v0, v0, v78, v79
	s_nop 2
	v_max3_f32 v0, v0, v48, v49
	v_max3_f32 v0, v0, v50, v51
	v_max3_f32 v0, v0, v52, v53
	v_max3_f32 v0, v0, v54, v55
	v_max3_f32 v0, v0, v56, v57
	v_max3_f32 v0, v0, v58, v59
	v_max3_f32 v0, v0, v60, v61
	v_max3_f32 v0, v0, v62, v63
	ds_bpermute_b32 v2, v103, v0
	s_waitcnt lgkmcnt(0)
	v_max_f32_e32 v2, v2, v2
	v_max_f32_e32 v0, v0, v2
	v_fma_f32 v2, v0, s20, -v101
	v_cmp_ge_f32_e32 vcc, s33, v2
	s_cmp_eq_u64 vcc, exec
	s_cbranch_scc1 .LBB0_844
	v_mul_f32_e32 v0, 0x3e38aa3b, v0
	v_max_f32_e64 v0, -v0, -v0
	v_max_f32_e64 v2, -v101, -v101
	v_min_f32_e32 v0, v2, v0
	v_add_f32_e32 v2, v101, v0
	v_exp_f32_e32 v2, v2
	s_nop 0
	v_pk_mul_f32 v[46:47], v[46:47], v[2:3] op_sel_hi:[1,0]
	v_pk_mul_f32 v[44:45], v[44:45], v[2:3] op_sel_hi:[1,0]
	v_pk_mul_f32 v[42:43], v[42:43], v[2:3] op_sel_hi:[1,0]
	v_pk_mul_f32 v[40:41], v[40:41], v[2:3] op_sel_hi:[1,0]
	v_pk_mul_f32 v[38:39], v[38:39], v[2:3] op_sel_hi:[1,0]
	v_pk_mul_f32 v[36:37], v[36:37], v[2:3] op_sel_hi:[1,0]
	v_pk_mul_f32 v[34:35], v[34:35], v[2:3] op_sel_hi:[1,0]
	v_pk_mul_f32 v[32:33], v[32:33], v[2:3] op_sel_hi:[1,0]
	v_pk_mul_f32 v[30:31], v[30:31], v[2:3] op_sel_hi:[1,0]
	v_pk_mul_f32 v[28:29], v[28:29], v[2:3] op_sel_hi:[1,0]
	v_pk_mul_f32 v[26:27], v[26:27], v[2:3] op_sel_hi:[1,0]
	v_pk_mul_f32 v[24:25], v[24:25], v[2:3] op_sel_hi:[1,0]
	v_pk_mul_f32 v[22:23], v[22:23], v[2:3] op_sel_hi:[1,0]
	v_pk_mul_f32 v[20:21], v[20:21], v[2:3] op_sel_hi:[1,0]
	v_pk_mul_f32 v[18:19], v[18:19], v[2:3] op_sel_hi:[1,0]
	v_pk_mul_f32 v[16:17], v[16:17], v[2:3] op_sel_hi:[1,0]
	v_mul_f32_e32 v86, v86, v2
	s_branch .LBB0_845

; #define LAS __attribute__((address_space(3)))
; #define MFMA32(a, b, c) __builtin_amdgcn_mfma_f32_32x32x16_bf16((a), (b), (c), 0, 0, 0)
; DI unsigned cvtpk(float lo, float hi) { f32x2 v = {lo, hi}; bf16x2_t b = __builtin_convertvector(v, bf16x2_t); return __builtin_bit_cast(unsigned, b); }
; template <int D, int MODE, int NSUB>
; DI void attn_item(const bf16* QKV, int pitch, int qcol0, int kcol0, const bf16* VT, bf16* O, int ocol0, const float* sink,
;                   LAS unsigned char* lds, int item, int tid_in, int lane_in, int wave) {
;     ...
;         float ls = 0.f; const float nm = -mrun;
; #pragma unroll
;         for (int q = 0; q < 2; ++q)
; #pragma unroll
;             for (int i = 0; i < 16; ++i) { s[q][i] = __builtin_amdgcn_exp2f(fmaf(s[q][i], scl, nm)); ls += s[q][i]; }
;         lrun += ls;
; #pragma unroll
;         for (int q = 0; q < 2; ++q)
; #pragma unroll
;             for (int s2 = 0; s2 < 2; ++s2) {
;                 u32x4 pw; pw.x = cvtpk(s[q][8 * s2], s[q][8 * s2 + 1]); pw.y = cvtpk(s[q][8 * s2 + 2], s[q][8 * s2 + 3]); pw.z = cvtpk(s[q][8 * s2 + 4], s[q][8 * s2 + 5]); pw.w = cvtpk(s[q][8 * s2 + 6], s[q][8 * s2 + 7]);
;                 const bf16x8 pb = __builtin_bit_cast(bf16x8, pw);
; #pragma unroll
;                 for (int dt = 0; dt < NDT; ++dt) { const LAS bf16* vp = Vt + (32 * dt + r) * VP + 64 * sub + 32 * q + 16 * s2 + 4 * h;
;                     const s16x4 lo = *(const LAS s16x4*)vp, hi = *(const LAS s16x4*)(vp + 8);
;                     const bf16x8 a = __builtin_shufflevector(lo, hi, 0, 1, 2, 3, 4, 5, 6, 7);
;                     o[dt] = MFMA32(a, pb, o[dt]); }
;             }
;         }
;         if (t + 1 < nt) ATT_STORE((t + 1) & 1);
;         __syncthreads();
;     }
;     ...
;     const float inv = 1.f / (lrun + __shfl_xor(lrun, 32));
;     bf16* op = O + (size_t)(qrow + r) * DM + ocol0 + head * D + 4 * h;
.LBB0_845:
	v_fmamk_f32 v2, v64, 0x3e38aa3b, v0
	v_exp_f32_e32 v64, v2
	v_fmamk_f32 v2, v65, 0x3e38aa3b, v0
	v_exp_f32_e32 v65, v2
	v_fmamk_f32 v2, v66, 0x3e38aa3b, v0
	v_exp_f32_e32 v66, v2
	v_fmamk_f32 v2, v67, 0x3e38aa3b, v0
	v_exp_f32_e32 v67, v2
	v_fmamk_f32 v2, v68, 0x3e38aa3b, v0
	v_exp_f32_e32 v68, v2
	v_fmamk_f32 v2, v69, 0x3e38aa3b, v0
	v_exp_f32_e32 v69, v2
	v_fmamk_f32 v2, v70, 0x3e38aa3b, v0
	v_exp_f32_e32 v70, v2
	v_fmamk_f32 v2, v71, 0x3e38aa3b, v0
	v_exp_f32_e32 v71, v2
	v_fmamk_f32 v2, v72, 0x3e38aa3b, v0
	v_exp_f32_e32 v72, v2
	v_fmamk_f32 v2, v73, 0x3e38aa3b, v0
	v_exp_f32_e32 v73, v2
	v_fmamk_f32 v2, v74, 0x3e38aa3b, v0
	v_exp_f32_e32 v74, v2
	v_fmamk_f32 v2, v75, 0x3e38aa3b, v0
	v_exp_f32_e32 v75, v2
	v_fmamk_f32 v2, v76, 0x3e38aa3b, v0
	v_exp_f32_e32 v76, v2
	v_fmamk_f32 v2, v77, 0x3e38aa3b, v0
	v_exp_f32_e32 v77, v2
	v_fmamk_f32 v2, v78, 0x3e38aa3b, v0
	v_exp_f32_e32 v78, v2
	v_fmamk_f32 v2, v79, 0x3e38aa3b, v0
	v_exp_f32_e32 v79, v2
	v_fmamk_f32 v2, v48, 0x3e38aa3b, v0
	v_exp_f32_e32 v48, v2
	v_fmamk_f32 v2, v49, 0x3e38aa3b, v0
	v_exp_f32_e32 v49, v2
	v_fmamk_f32 v2, v50, 0x3e38aa3b, v0
	v_exp_f32_e32 v50, v2
	v_fmamk_f32 v2, v51, 0x3e38aa3b, v0
	v_exp_f32_e32 v51, v2
	v_fmamk_f32 v2, v52, 0x3e38aa3b, v0
	v_exp_f32_e32 v52, v2
	v_fmamk_f32 v2, v53, 0x3e38aa3b, v0
	v_exp_f32_e32 v53, v2
	v_fmamk_f32 v2, v54, 0x3e38aa3b, v0
	v_exp_f32_e32 v54, v2
	v_fmamk_f32 v2, v55, 0x3e38aa3b, v0
	v_exp_f32_e32 v55, v2
	v_fmamk_f32 v2, v56, 0x3e38aa3b, v0
	v_exp_f32_e32 v56, v2
	v_fmamk_f32 v2, v57, 0x3e38aa3b, v0
	v_exp_f32_e32 v57, v2
	v_fmamk_f32 v2, v58, 0x3e38aa3b, v0
	v_exp_f32_e32 v58, v2
	v_fmamk_f32 v2, v59, 0x3e38aa3b, v0
	v_exp_f32_e32 v59, v2
	v_fmamk_f32 v2, v60, 0x3e38aa3b, v0
	ds_read2_b64 v[172:175], v84 offset0:80 offset1:82
	ds_read2_b64 v[176:179], v84 offset0:84 offset1:86
	ds_read2_b64 v[180:183], v85 offset0:112 offset1:114
	ds_read2_b64 v[184:187], v85 offset0:116 offset1:118
	ds_read2_b64 v[192:195], v84 offset0:88 offset1:90
	ds_read2_b64 v[196:199], v85 offset0:120 offset1:122
	v_exp_f32_e32 v60, v2
	v_fmamk_f32 v2, v61, 0x3e38aa3b, v0
	v_exp_f32_e32 v61, v2
	v_fmamk_f32 v2, v62, 0x3e38aa3b, v0
	v_exp_f32_e32 v62, v2
	v_cvt_pk_bf16_f32 v2, v64, v65
	v_cvt_pk_bf16_f32 v3, v66, v67
	v_cvt_pk_bf16_f32 v4, v68, v69
	v_cvt_pk_bf16_f32 v5, v70, v71
	v_fmac_f32_e32 v0, 0x3e38aa3b, v63
	v_exp_f32_e32 v0, v0
	s_waitcnt lgkmcnt(5)
	v_mfma_f32_32x32x16_bf16 v[32:47], v[172:175], v[2:5], v[32:47]
	ds_read2_b64 v[200:203], v84 offset0:92 offset1:94
	v_mov_b32_e32 v15, v1
	v_readlane_b32 s4, v254, 31
	s_lshl_b32 s0, s6, 6
	v_readlane_b32 s5, v254, 32
	s_lshl_b32 s0, s0, 1
	s_waitcnt lgkmcnt(4)
	v_mfma_f32_32x32x16_bf16 v[16:31], v[180:183], v[2:5], v[16:31]
	v_cvt_pk_bf16_f32 v2, v72, v73
	v_cvt_pk_bf16_f32 v3, v74, v75
	v_cvt_pk_bf16_f32 v4, v76, v77
	v_cvt_pk_bf16_f32 v5, v78, v79
	s_nop 0
	s_waitcnt lgkmcnt(3)
	v_mfma_f32_32x32x16_bf16 v[16:31], v[184:187], v[2:5], v[16:31]
	s_waitcnt lgkmcnt(5)
	v_mfma_f32_32x32x16_bf16 v[32:47], v[176:179], v[2:5], v[32:47]
	v_cvt_pk_bf16_f32 v2, v48, v49
	v_cvt_pk_bf16_f32 v3, v50, v51
	v_cvt_pk_bf16_f32 v4, v52, v53
	v_cvt_pk_bf16_f32 v5, v54, v55
	s_nop 0
	s_waitcnt lgkmcnt(2)
	v_mfma_f32_32x32x16_bf16 v[32:47], v[192:195], v[2:5], v[32:47]
	s_waitcnt lgkmcnt(1)
	v_mfma_f32_32x32x16_bf16 v[16:31], v[196:199], v[2:5], v[16:31]
	v_cvt_pk_bf16_f32 v2, v56, v57
	v_cvt_pk_bf16_f32 v3, v58, v59
	v_cvt_pk_bf16_f32 v4, v60, v61
	v_cvt_pk_bf16_f32 v5, v62, v0
	s_nop 0
	s_waitcnt lgkmcnt(0)
	v_mfma_f32_32x32x16_bf16 v[32:47], v[200:203], v[2:5], v[32:47]
	ds_read2_b64 v[6:9], v85 offset0:124 offset1:126
	s_waitcnt lgkmcnt(0)
	s_barrier
	v_mfma_f32_32x32x16_bf16 v[16:31], v[6:9], v[2:5], v[16:31]
	v_add_f32_e32 v2, 0, v64
	v_add_f32_e32 v2, v65, v2
	v_add_f32_e32 v2, v66, v2
	v_add_f32_e32 v2, v67, v2
	v_add_f32_e32 v2, v68, v2
	v_add_f32_e32 v2, v69, v2
	v_add_f32_e32 v2, v70, v2
	v_add_f32_e32 v2, v71, v2
	v_add_f32_e32 v2, v72, v2
	v_add_f32_e32 v2, v73, v2
	v_add_f32_e32 v2, v74, v2
	v_add_f32_e32 v2, v75, v2
	v_add_f32_e32 v2, v76, v2
	v_add_f32_e32 v2, v77, v2
	v_add_f32_e32 v2, v78, v2
	v_add_f32_e32 v2, v79, v2
	v_add_f32_e32 v2, v48, v2
	v_add_f32_e32 v2, v49, v2
	v_add_f32_e32 v2, v50, v2
	v_add_f32_e32 v2, v51, v2
	v_add_f32_e32 v2, v52, v2
	v_add_f32_e32 v2, v53, v2
	v_add_f32_e32 v2, v54, v2
	v_add_f32_e32 v2, v55, v2
	v_add_f32_e32 v2, v56, v2
	v_add_f32_e32 v2, v57, v2
	v_add_f32_e32 v2, v58, v2
	v_add_f32_e32 v2, v59, v2
	v_add_f32_e32 v2, v60, v2
	v_add_f32_e32 v2, v61, v2
	v_add_f32_e32 v2, v62, v2
	v_add_f32_e32 v0, v0, v2
	v_add_f32_e32 v0, v86, v0
	ds_bpermute_b32 v2, v103, v0
	s_waitcnt lgkmcnt(0)
	v_add_f32_e32 v4, v0, v2
	v_lshlrev_b64 v[2:3], 11, v[14:15]
	v_lshl_add_u64 v[2:3], s[4:5], 0, v[2:3]
	v_lshl_add_u64 v[2:3], v[2:3], 0, s[0:1]
	v_lshl_add_u64 v[2:3], v[2:3], 0, s[36:37]
	v_lshlrev_b32_e32 v0, 2, v102
	s_mov_b64 s[4:5], 0

; #define LAS __attribute__((address_space(3)))
; #define MFMA32(a, b, c) __builtin_amdgcn_mfma_f32_32x32x16_bf16((a), (b), (c), 0, 0, 0)
; DI int crow(int i, int h) { return (i & 3) + 8 * (i >> 2) + 4 * h; }
; DI f32x16 zero16() { f32x16 z; for (int i = 0; i < 16; ++i) z[i] = 0.f; return z; }
; template <int D, int MODE, int NSUB>
; DI void attn_item(const bf16* QKV, int pitch, int qcol0, int kcol0, const bf16* VT, bf16* O, int ocol0, const float* sink,
;                   LAS unsigned char* lds, int item, int tid_in, int lane_in, int wave) {
;     ...
;         for (int sub = 0; sub < NSUB; ++sub) {
;         f32x16 s[2];
; #pragma unroll
;         for (int q = 0; q < 2; ++q) { s[q] = zero16(); const LAS bf16* kp = Kt + (64 * sub + 32 * q + r) * KP + 8 * h;
; #pragma unroll
;             for (int ks = 0; ks < NKS; ++ks) s[q] = MFMA32(*(const LAS bf16x8*)(kp + 16 * ks), qf[ks], s[q]); }
;         if (MODE == 1 && KT * t >= CTXL) { const int kp0 = wstart + KT * t + 64 * sub - CTXL - qpos;
; #pragma unroll
;             for (int q = 0; q < 2; ++q)
; #pragma unroll
;                 for (int i = 0; i < 16; ++i) { const int d0 = kp0 + 32 * q + crow(i, h); if (d0 > 128 || d0 < -128) s[q][i] = -INFINITY; } }
.LBB0_853:
	s_bitcmp1_b32 s4, 0
	s_cselect_b32 s4, 0x8a00, 0
	s_add_i32 s31, s4, 0
	v_lshl_add_u32 v0, v140, 1, s31
	v_add_u32_e32 v4, v0, v142
	ds_read_b128 v[172:175], v4
	ds_read_b128 v[176:179], v4 offset:32
	ds_read_b128 v[180:183], v4 offset:64
	ds_read_b128 v[184:187], v4 offset:96
	ds_read_b128 v[192:195], v4 offset:4608
	ds_read_b128 v[196:199], v4 offset:4640
	s_cmpk_gt_u32 s6, 0xff
	s_cselect_b64 s[4:5], -1, 0
	s_cmpk_lt_u32 s6, 0x100
	s_waitcnt lgkmcnt(5)
	v_mfma_f32_32x32x16_bf16 v[64:79], v[172:175], v[96:99], 0
	ds_read_b128 v[200:203], v4 offset:4672
	v_add_u32_e32 v3, s6, v144
	s_waitcnt lgkmcnt(5)
	v_mfma_f32_32x32x16_bf16 v[64:79], v[176:179], v[88:91], v[64:79]
	ds_read_b128 v[204:207], v4 offset:4704
	s_waitcnt lgkmcnt(5)
	v_mfma_f32_32x32x16_bf16 v[64:79], v[180:183], v[92:95], v[64:79]
	s_waitcnt lgkmcnt(4)
	v_mfma_f32_32x32x16_bf16 v[64:79], v[184:187], v[100:103], v[64:79]
	s_waitcnt lgkmcnt(3)
	v_mfma_f32_32x32x16_bf16 v[48:63], v[192:195], v[96:99], 0
	s_waitcnt lgkmcnt(2)
	v_mfma_f32_32x32x16_bf16 v[48:63], v[196:199], v[88:91], v[48:63]
	s_waitcnt lgkmcnt(1)
	v_mfma_f32_32x32x16_bf16 v[48:63], v[200:203], v[92:95], v[48:63]
	s_waitcnt lgkmcnt(0)
	v_mfma_f32_32x32x16_bf16 v[48:63], v[204:207], v[100:103], v[48:63]
	s_cbranch_scc1 .LBB0_855
	v_add_u32_e32 v0, 0xfffffe7f, v3
	v_cmp_gt_u32_e32 vcc, s39, v0
	v_add_u32_e32 v0, 0xfffffe80, v3
	s_nop 0
	v_cndmask_b32_e32 v64, v64, v129, vcc
	v_cmp_lt_u32_e32 vcc, s40, v0
	v_add_u32_e32 v0, 0xfffffe81, v3
	s_nop 0
	v_cndmask_b32_e32 v65, v129, v65, vcc
	v_cmp_lt_u32_e32 vcc, s40, v0
	v_add_u32_e32 v0, 0xfffffe82, v3
	s_nop 0
	v_cndmask_b32_e32 v66, v129, v66, vcc
	v_cmp_lt_u32_e32 vcc, s40, v0
	v_add_u32_e32 v0, 0xfffffe87, v3
	s_nop 0
	v_cndmask_b32_e32 v67, v129, v67, vcc
	v_cmp_lt_u32_e32 vcc, s40, v0
	v_add_u32_e32 v0, 0xfffffe88, v3
	s_nop 0
	v_cndmask_b32_e32 v68, v129, v68, vcc
	v_cmp_lt_u32_e32 vcc, s40, v0
	v_add_u32_e32 v0, 0xfffffe89, v3
	s_nop 0
	v_cndmask_b32_e32 v69, v129, v69, vcc
	v_cmp_lt_u32_e32 vcc, s40, v0
	v_add_u32_e32 v0, 0xfffffe8a, v3
	s_nop 0
	v_cndmask_b32_e32 v70, v129, v70, vcc
	v_cmp_lt_u32_e32 vcc, s40, v0
	v_add_u32_e32 v0, 0xfffffe8f, v3
	s_nop 0
	v_cndmask_b32_e32 v71, v129, v71, vcc
	v_cmp_lt_u32_e32 vcc, s40, v0
	v_add_u32_e32 v0, 0xfffffe90, v3
	s_nop 0
	v_cndmask_b32_e32 v72, v129, v72, vcc
	v_cmp_lt_u32_e32 vcc, s40, v0
	v_add_u32_e32 v0, 0xfffffe91, v3
	s_nop 0
	v_cndmask_b32_e32 v73, v129, v73, vcc
	v_cmp_lt_u32_e32 vcc, s40, v0
	v_add_u32_e32 v0, 0xfffffe92, v3
	s_nop 0
	v_cndmask_b32_e32 v74, v129, v74, vcc
	v_cmp_lt_u32_e32 vcc, s40, v0
	v_add_u32_e32 v0, 0xfffffe97, v3
	s_nop 0
	v_cndmask_b32_e32 v75, v129, v75, vcc
	v_cmp_lt_u32_e32 vcc, s40, v0
	v_add_u32_e32 v0, 0xfffffe98, v3
	s_nop 0
	v_cndmask_b32_e32 v76, v129, v76, vcc
	v_cmp_lt_u32_e32 vcc, s40, v0
	v_add_u32_e32 v0, 0xfffffe99, v3
	s_nop 0
	v_cndmask_b32_e32 v77, v129, v77, vcc
	v_cmp_lt_u32_e32 vcc, s40, v0
	v_add_u32_e32 v0, 0xfffffe9a, v3
	s_nop 0
	v_cndmask_b32_e32 v78, v129, v78, vcc
	v_cmp_lt_u32_e32 vcc, s40, v0
	v_add_u32_e32 v0, 0xfffffe9f, v3
	s_nop 0
	v_cndmask_b32_e32 v79, v129, v79, vcc
	v_cmp_lt_u32_e32 vcc, s40, v0
	v_add_u32_e32 v0, 0xfffffea0, v3
	s_nop 0
	v_cndmask_b32_e32 v48, v129, v48, vcc
	v_cmp_lt_u32_e32 vcc, s40, v0
	v_add_u32_e32 v0, 0xfffffea1, v3
	s_nop 0
	v_cndmask_b32_e32 v49, v129, v49, vcc
	v_cmp_lt_u32_e32 vcc, s40, v0
	v_add_u32_e32 v0, 0xfffffea2, v3
	s_nop 0
	v_cndmask_b32_e32 v50, v129, v50, vcc
	v_cmp_lt_u32_e32 vcc, s40, v0
	v_add_u32_e32 v0, 0xfffffea7, v3
	s_nop 0
	v_cndmask_b32_e32 v51, v129, v51, vcc
	v_cmp_lt_u32_e32 vcc, s40, v0
	v_add_u32_e32 v0, 0xfffffea8, v3
	s_nop 0
	v_cndmask_b32_e32 v52, v129, v52, vcc
	v_cmp_lt_u32_e32 vcc, s40, v0
	v_add_u32_e32 v0, 0xfffffea9, v3
	s_nop 0
	v_cndmask_b32_e32 v53, v129, v53, vcc
	v_cmp_lt_u32_e32 vcc, s40, v0
	v_add_u32_e32 v0, 0xfffffeaa, v3
	s_nop 0
	v_cndmask_b32_e32 v54, v129, v54, vcc
	v_cmp_lt_u32_e32 vcc, s40, v0
	v_add_u32_e32 v0, 0xfffffeaf, v3
	s_nop 0
	v_cndmask_b32_e32 v55, v129, v55, vcc
	v_cmp_lt_u32_e32 vcc, s40, v0
	v_add_u32_e32 v0, 0xfffffeb0, v3
	s_nop 0
	v_cndmask_b32_e32 v56, v129, v56, vcc
	v_cmp_lt_u32_e32 vcc, s40, v0
	v_add_u32_e32 v0, 0xfffffeb1, v3
	s_nop 0
	v_cndmask_b32_e32 v57, v129, v57, vcc
	v_cmp_lt_u32_e32 vcc, s40, v0
	v_add_u32_e32 v0, 0xfffffeb2, v3
	s_nop 0
	v_cndmask_b32_e32 v58, v129, v58, vcc
	v_cmp_lt_u32_e32 vcc, s40, v0
	v_add_u32_e32 v0, 0xfffffeb7, v3
	s_nop 0
	v_cndmask_b32_e32 v59, v129, v59, vcc
	v_cmp_lt_u32_e32 vcc, s40, v0
	v_add_u32_e32 v0, 0xfffffeb8, v3
	s_nop 0
	v_cndmask_b32_e32 v60, v129, v60, vcc
	v_cmp_lt_u32_e32 vcc, s40, v0
	v_add_u32_e32 v0, 0xfffffeb9, v3
	s_nop 0
	v_cndmask_b32_e32 v61, v129, v61, vcc
	v_cmp_lt_u32_e32 vcc, s40, v0
	v_add_u32_e32 v0, 0xfffffeba, v3
	s_nop 0
	v_cndmask_b32_e32 v62, v129, v62, vcc
	v_cmp_lt_u32_e32 vcc, s40, v0
	s_nop 1
	v_cndmask_b32_e32 v63, v129, v63, vcc

; #define LAS __attribute__((address_space(3)))
; #define MFMA32(a, b, c) __builtin_amdgcn_mfma_f32_32x32x16_bf16((a), (b), (c), 0, 0, 0)
; DI unsigned cvtpk(float lo, float hi) { f32x2 v = {lo, hi}; bf16x2_t b = __builtin_convertvector(v, bf16x2_t); return __builtin_bit_cast(unsigned, b); }
; DI f32x16 zero16() { f32x16 z; for (int i = 0; i < 16; ++i) z[i] = 0.f; return z; }
; template <int D, int MODE, int NSUB>
; DI void attn_item(const bf16* QKV, int pitch, int qcol0, int kcol0, const bf16* VT, bf16* O, int ocol0, const float* sink,
;                   LAS unsigned char* lds, int item, int tid_in, int lane_in, int wave) {
;     ...
;         for (int q = 0; q < 2; ++q) { s[q] = zero16(); const LAS bf16* kp = Kt + (64 * sub + 32 * q + r) * KP + 8 * h;
; #pragma unroll
;             for (int ks = 0; ks < NKS; ++ks) s[q] = MFMA32(*(const LAS bf16x8*)(kp + 16 * ks), qf[ks], s[q]); }
;     ...
;         float ls = 0.f; const float nm = -mrun;
; #pragma unroll
;         for (int q = 0; q < 2; ++q)
; #pragma unroll
;             for (int i = 0; i < 16; ++i) { s[q][i] = __builtin_amdgcn_exp2f(fmaf(s[q][i], scl, nm)); ls += s[q][i]; }
;         lrun += ls;
; #pragma unroll
;         for (int q = 0; q < 2; ++q)
; #pragma unroll
;             for (int s2 = 0; s2 < 2; ++s2) {
;                 u32x4 pw; pw.x = cvtpk(s[q][8 * s2], s[q][8 * s2 + 1]); pw.y = cvtpk(s[q][8 * s2 + 2], s[q][8 * s2 + 3]); pw.z = cvtpk(s[q][8 * s2 + 4], s[q][8 * s2 + 5]); pw.w = cvtpk(s[q][8 * s2 + 6], s[q][8 * s2 + 7]);
;                 const bf16x8 pb = __builtin_bit_cast(bf16x8, pw);
; #pragma unroll
;                 for (int dt = 0; dt < NDT; ++dt) { const LAS bf16* vp = Vt + (32 * dt + r) * VP + 64 * sub + 32 * q + 16 * s2 + 4 * h;
;                     const s16x4 lo = *(const LAS s16x4*)vp, hi = *(const LAS s16x4*)(vp + 8);
;                     const bf16x8 a = __builtin_shufflevector(lo, hi, 0, 1, 2, 3, 4, 5, 6, 7);
;                     o[dt] = MFMA32(a, pb, o[dt]); }
.LBB0_857:
	v_fma_f32 v2, v64, s20, -v145
	v_exp_f32_e32 v5, v2
	v_fma_f32 v2, v65, s20, -v145
	v_exp_f32_e32 v6, v2
	v_fma_f32 v2, v66, s20, -v145
	v_exp_f32_e32 v7, v2
	v_fma_f32 v2, v67, s20, -v145
	v_exp_f32_e32 v8, v2
	v_fma_f32 v2, v68, s20, -v145
	v_exp_f32_e32 v10, v2
	v_fma_f32 v2, v69, s20, -v145
	v_exp_f32_e32 v12, v2
	v_fma_f32 v2, v70, s20, -v145
	v_exp_f32_e32 v14, v2
	v_fma_f32 v2, v71, s20, -v145
	v_exp_f32_e32 v147, v2
	v_fma_f32 v2, v72, s20, -v145
	v_exp_f32_e32 v148, v2
	v_fma_f32 v2, v73, s20, -v145
	v_exp_f32_e32 v149, v2
	v_fma_f32 v2, v74, s20, -v145
	v_exp_f32_e32 v150, v2
	v_fma_f32 v2, v75, s20, -v145
	v_exp_f32_e32 v151, v2
	v_fma_f32 v2, v76, s20, -v145
	v_exp_f32_e32 v152, v2
	v_fma_f32 v2, v77, s20, -v145
	v_exp_f32_e32 v153, v2
	v_fma_f32 v2, v78, s20, -v145
	v_exp_f32_e32 v154, v2
	v_fma_f32 v2, v79, s20, -v145
	v_exp_f32_e32 v155, v2
	v_fma_f32 v2, v48, s20, -v145
	v_exp_f32_e32 v156, v2
	v_fma_f32 v2, v49, s20, -v145
	v_exp_f32_e32 v157, v2
	v_fma_f32 v2, v50, s20, -v145
	v_exp_f32_e32 v158, v2
	v_fma_f32 v2, v51, s20, -v145
	v_exp_f32_e32 v159, v2
	v_fma_f32 v2, v52, s20, -v145
	v_exp_f32_e32 v160, v2
	v_fma_f32 v2, v53, s20, -v145
	v_exp_f32_e32 v161, v2
	v_fma_f32 v2, v54, s20, -v145
	v_exp_f32_e32 v162, v2
	v_fma_f32 v2, v55, s20, -v145
	v_exp_f32_e32 v163, v2
	v_fma_f32 v2, v56, s20, -v145
	v_exp_f32_e32 v164, v2
	v_fma_f32 v2, v57, s20, -v145
	v_exp_f32_e32 v165, v2
	v_fma_f32 v2, v58, s20, -v145
	v_exp_f32_e32 v166, v2
	v_fma_f32 v2, v59, s20, -v145
	v_exp_f32_e32 v167, v2
	v_fma_f32 v2, v60, s20, -v145
	v_exp_f32_e32 v9, v2
	v_fma_f32 v2, v61, s20, -v145
	v_exp_f32_e32 v11, v2
	v_fma_f32 v2, v62, s20, -v145
	v_add_u32_e32 v0, s31, v140
	v_exp_f32_e32 v13, v2
	v_fma_f32 v2, v63, s20, -v145
	v_exp_f32_e32 v15, v2
	v_add_u32_e32 v2, v0, v143
	v_add_u32_e32 v0, 0x4800, v2
	ds_read2_b64 v[172:175], v0 offset1:2
	ds_read2_b64 v[176:179], v0 offset0:4 offset1:6
	v_cvt_pk_bf16_f32 v48, v5, v6
	v_cvt_pk_bf16_f32 v49, v7, v8
	v_cvt_pk_bf16_f32 v50, v10, v12
	v_cvt_pk_bf16_f32 v51, v14, v147
	v_add_u32_e32 v2, 0x6800, v2
	ds_read2_b64 v[180:183], v2 offset0:32 offset1:34
	ds_read2_b64 v[184:187], v2 offset0:36 offset1:38
	ds_read2_b64 v[192:195], v0 offset0:8 offset1:10
	ds_read2_b64 v[196:199], v2 offset0:40 offset1:42
	s_andn2_b64 vcc, exec, s[4:5]
	s_waitcnt lgkmcnt(5)
	v_mfma_f32_32x32x16_bf16 v[32:47], v[172:175], v[48:51], v[32:47]
	ds_read2_b64 v[200:203], v0 offset0:12 offset1:14
	s_waitcnt lgkmcnt(4)
	v_mfma_f32_32x32x16_bf16 v[16:31], v[180:183], v[48:51], v[16:31]
	ds_read2_b64 v[204:207], v2 offset0:44 offset1:46
	ds_read_b128 v[208:211], v4 offset:9216
	v_cvt_pk_bf16_f32 v48, v148, v149
	v_cvt_pk_bf16_f32 v49, v150, v151
	v_cvt_pk_bf16_f32 v50, v152, v153
	v_cvt_pk_bf16_f32 v51, v154, v155
	s_nop 0
	s_waitcnt lgkmcnt(5)
	v_mfma_f32_32x32x16_bf16 v[16:31], v[184:187], v[48:51], v[16:31]
	ds_read_b128 v[212:215], v4 offset:9248
	s_waitcnt lgkmcnt(8)
	v_mfma_f32_32x32x16_bf16 v[32:47], v[176:179], v[48:51], v[32:47]
	v_cvt_pk_bf16_f32 v48, v156, v157
	v_cvt_pk_bf16_f32 v49, v158, v159
	v_cvt_pk_bf16_f32 v50, v160, v161
	v_cvt_pk_bf16_f32 v51, v162, v163
	s_nop 0
	s_waitcnt lgkmcnt(5)
	v_mfma_f32_32x32x16_bf16 v[32:47], v[192:195], v[48:51], v[32:47]
	ds_read_b128 v[220:223], v4 offset:13856
	s_waitcnt lgkmcnt(5)
	v_mfma_f32_32x32x16_bf16 v[16:31], v[196:199], v[48:51], v[16:31]
	ds_read_b128 v[224:227], v4 offset:9280
	v_cvt_pk_bf16_f32 v48, v164, v165
	v_cvt_pk_bf16_f32 v49, v166, v167
	v_cvt_pk_bf16_f32 v50, v9, v11
	v_cvt_pk_bf16_f32 v51, v13, v15
	s_nop 0
	s_waitcnt lgkmcnt(5)
	v_mfma_f32_32x32x16_bf16 v[32:47], v[200:203], v[48:51], v[32:47]
	ds_read_b128 v[228:231], v4 offset:9312
	s_waitcnt lgkmcnt(5)
	v_mfma_f32_32x32x16_bf16 v[16:31], v[204:207], v[48:51], v[16:31]
	ds_read_b128 v[232:235], v4 offset:13824
	s_waitcnt lgkmcnt(5)
	v_mfma_f32_32x32x16_bf16 v[64:79], v[208:211], v[96:99], 0
	ds_read_b128 v[236:239], v4 offset:13888
	s_waitcnt lgkmcnt(5)
	v_mfma_f32_32x32x16_bf16 v[64:79], v[212:215], v[88:91], v[64:79]
	ds_read_b128 v[240:243], v4 offset:13920
	s_waitcnt lgkmcnt(4)
	v_mfma_f32_32x32x16_bf16 v[64:79], v[224:227], v[92:95], v[64:79]
	s_waitcnt lgkmcnt(3)
	v_mfma_f32_32x32x16_bf16 v[64:79], v[228:231], v[100:103], v[64:79]
	s_waitcnt lgkmcnt(2)
	v_mfma_f32_32x32x16_bf16 v[48:63], v[232:235], v[96:99], 0
	s_waitcnt lgkmcnt(5)
	v_mfma_f32_32x32x16_bf16 v[48:63], v[220:223], v[88:91], v[48:63]
	s_waitcnt lgkmcnt(1)
	v_mfma_f32_32x32x16_bf16 v[48:63], v[236:239], v[92:95], v[48:63]
	s_waitcnt lgkmcnt(0)
	v_mfma_f32_32x32x16_bf16 v[48:63], v[240:243], v[100:103], v[48:63]
	s_cbranch_vccnz .LBB0_859
; DI int crow(int i, int h) { return (i & 3) + 8 * (i >> 2) + 4 * h; }
; template <int D, int MODE, int NSUB>
; DI void attn_item(const bf16* QKV, int pitch, int qcol0, int kcol0, const bf16* VT, bf16* O, int ocol0, const float* sink,
;                   LAS unsigned char* lds, int item, int tid_in, int lane_in, int wave) {
;     ...
;         if (MODE == 1 && KT * t >= CTXL) { const int kp0 = wstart + KT * t + 64 * sub - CTXL - qpos;
; #pragma unroll
;             for (int q = 0; q < 2; ++q)
; #pragma unroll
;                 for (int i = 0; i < 16; ++i) { const int d0 = kp0 + 32 * q + crow(i, h); if (d0 > 128 || d0 < -128) s[q][i] = -INFINITY; } }
	v_add_u32_e32 v4, 0xfffffebf, v3
	v_cmp_gt_u32_e32 vcc, s39, v4
	v_add_u32_e32 v4, 0xfffffec0, v3
	s_nop 0
	v_cndmask_b32_e32 v64, v64, v129, vcc
	v_cmp_lt_u32_e32 vcc, s40, v4
	v_add_u32_e32 v4, 0xfffffec1, v3
	s_nop 0
	v_cndmask_b32_e32 v65, v129, v65, vcc
	v_cmp_lt_u32_e32 vcc, s40, v4
	v_add_u32_e32 v4, 0xfffffec2, v3
	s_nop 0
	v_cndmask_b32_e32 v66, v129, v66, vcc
	v_cmp_lt_u32_e32 vcc, s40, v4
	v_add_u32_e32 v4, 0xfffffec7, v3
	s_nop 0
	v_cndmask_b32_e32 v67, v129, v67, vcc
	v_cmp_lt_u32_e32 vcc, s40, v4
	v_add_u32_e32 v4, 0xfffffec8, v3
	s_nop 0
	v_cndmask_b32_e32 v68, v129, v68, vcc
	v_cmp_lt_u32_e32 vcc, s40, v4
	v_add_u32_e32 v4, 0xfffffec9, v3
	s_nop 0
	v_cndmask_b32_e32 v69, v129, v69, vcc
	v_cmp_lt_u32_e32 vcc, s40, v4
	v_add_u32_e32 v4, 0xfffffeca, v3
	s_nop 0
	v_cndmask_b32_e32 v70, v129, v70, vcc
	v_cmp_lt_u32_e32 vcc, s40, v4
	v_add_u32_e32 v4, 0xfffffecf, v3
	s_nop 0
	v_cndmask_b32_e32 v71, v129, v71, vcc
	v_cmp_lt_u32_e32 vcc, s40, v4
	v_add_u32_e32 v4, 0xfffffed0, v3
	s_nop 0
	v_cndmask_b32_e32 v72, v129, v72, vcc
	v_cmp_lt_u32_e32 vcc, s40, v4
	v_add_u32_e32 v4, 0xfffffed1, v3
	s_nop 0
	v_cndmask_b32_e32 v73, v129, v73, vcc
	v_cmp_lt_u32_e32 vcc, s40, v4
	v_add_u32_e32 v4, 0xfffffed2, v3
	s_nop 0
	v_cndmask_b32_e32 v74, v129, v74, vcc
	v_cmp_lt_u32_e32 vcc, s40, v4
	v_add_u32_e32 v4, 0xfffffed7, v3
	s_nop 0
	v_cndmask_b32_e32 v75, v129, v75, vcc
	v_cmp_lt_u32_e32 vcc, s40, v4
	v_add_u32_e32 v4, 0xfffffed8, v3
	s_nop 0
	v_cndmask_b32_e32 v76, v129, v76, vcc
	v_cmp_lt_u32_e32 vcc, s40, v4
	v_add_u32_e32 v4, 0xfffffed9, v3
	s_nop 0
	v_cndmask_b32_e32 v77, v129, v77, vcc
	v_cmp_lt_u32_e32 vcc, s40, v4
	v_add_u32_e32 v4, 0xfffffeda, v3
	s_nop 0
	v_cndmask_b32_e32 v78, v129, v78, vcc
	v_cmp_lt_u32_e32 vcc, s40, v4
	v_add_u32_e32 v4, 0xfffffedf, v3
	s_nop 0
	v_cndmask_b32_e32 v79, v129, v79, vcc
	v_cmp_lt_u32_e32 vcc, s40, v4
	v_add_u32_e32 v4, 0xfffffee0, v3
	s_nop 0
	v_cndmask_b32_e32 v48, v129, v48, vcc
	v_cmp_lt_u32_e32 vcc, s40, v4
	v_add_u32_e32 v4, 0xfffffee1, v3
	s_nop 0
	v_cndmask_b32_e32 v49, v129, v49, vcc
	v_cmp_lt_u32_e32 vcc, s40, v4
	v_add_u32_e32 v4, 0xfffffee2, v3
	s_nop 0
	v_cndmask_b32_e32 v50, v129, v50, vcc
	v_cmp_lt_u32_e32 vcc, s40, v4
	v_add_u32_e32 v4, 0xfffffee7, v3
	s_nop 0
	v_cndmask_b32_e32 v51, v129, v51, vcc
	v_cmp_lt_u32_e32 vcc, s40, v4
	v_add_u32_e32 v4, 0xfffffee8, v3
	s_nop 0
	v_cndmask_b32_e32 v52, v129, v52, vcc
	v_cmp_lt_u32_e32 vcc, s40, v4
	v_add_u32_e32 v4, 0xfffffee9, v3
	s_nop 0
	v_cndmask_b32_e32 v53, v129, v53, vcc
	v_cmp_lt_u32_e32 vcc, s40, v4
	v_add_u32_e32 v4, 0xfffffeea, v3
	s_nop 0
	v_cndmask_b32_e32 v54, v129, v54, vcc
	v_cmp_lt_u32_e32 vcc, s40, v4
	v_add_u32_e32 v4, 0xfffffeef, v3
	s_nop 0
	v_cndmask_b32_e32 v55, v129, v55, vcc
	v_cmp_lt_u32_e32 vcc, s40, v4
	v_add_u32_e32 v4, 0xfffffef0, v3
	s_nop 0
	v_cndmask_b32_e32 v56, v129, v56, vcc
	v_cmp_lt_u32_e32 vcc, s40, v4
	v_add_u32_e32 v4, 0xfffffef1, v3
	s_nop 0
	v_cndmask_b32_e32 v57, v129, v57, vcc
	v_cmp_lt_u32_e32 vcc, s40, v4
	v_add_u32_e32 v4, 0xfffffef2, v3
	s_nop 0
	v_cndmask_b32_e32 v58, v129, v58, vcc
	v_cmp_lt_u32_e32 vcc, s40, v4
	v_add_u32_e32 v4, 0xfffffef7, v3
	s_nop 0
	v_cndmask_b32_e32 v59, v129, v59, vcc
	v_cmp_lt_u32_e32 vcc, s40, v4
	v_add_u32_e32 v4, 0xfffffef8, v3
	s_nop 0
	v_cndmask_b32_e32 v60, v129, v60, vcc
	v_cmp_lt_u32_e32 vcc, s40, v4
	v_add_u32_e32 v4, 0xfffffef9, v3
	v_add_u32_e32 v3, 0xfffffefa, v3
	v_cndmask_b32_e32 v61, v129, v61, vcc
	v_cmp_lt_u32_e32 vcc, s40, v4
	s_nop 1
	v_cndmask_b32_e32 v62, v129, v62, vcc
	v_cmp_lt_u32_e32 vcc, s40, v3
	s_nop 1
	v_cndmask_b32_e32 v63, v129, v63, vcc

; #define LAS __attribute__((address_space(3)))
; #define MFMA32(a, b, c) __builtin_amdgcn_mfma_f32_32x32x16_bf16((a), (b), (c), 0, 0, 0)
; DI unsigned cvtpk(float lo, float hi) { f32x2 v = {lo, hi}; bf16x2_t b = __builtin_convertvector(v, bf16x2_t); return __builtin_bit_cast(unsigned, b); }
; template <int D, int MODE, int NSUB>
; DI void attn_item(const bf16* QKV, int pitch, int qcol0, int kcol0, const bf16* VT, bf16* O, int ocol0, const float* sink,
;                   LAS unsigned char* lds, int item, int tid_in, int lane_in, int wave) {
;     ...
;         float ls = 0.f; const float nm = -mrun;
; #pragma unroll
;         for (int q = 0; q < 2; ++q)
; #pragma unroll
;             for (int i = 0; i < 16; ++i) { s[q][i] = __builtin_amdgcn_exp2f(fmaf(s[q][i], scl, nm)); ls += s[q][i]; }
;         lrun += ls;
; #pragma unroll
;         for (int q = 0; q < 2; ++q)
; #pragma unroll
;             for (int s2 = 0; s2 < 2; ++s2) {
;                 u32x4 pw; pw.x = cvtpk(s[q][8 * s2], s[q][8 * s2 + 1]); pw.y = cvtpk(s[q][8 * s2 + 2], s[q][8 * s2 + 3]); pw.z = cvtpk(s[q][8 * s2 + 4], s[q][8 * s2 + 5]); pw.w = cvtpk(s[q][8 * s2 + 6], s[q][8 * s2 + 7]);
;                 const bf16x8 pb = __builtin_bit_cast(bf16x8, pw);
; #pragma unroll
;                 for (int dt = 0; dt < NDT; ++dt) { const LAS bf16* vp = Vt + (32 * dt + r) * VP + 64 * sub + 32 * q + 16 * s2 + 4 * h;
;                     const s16x4 lo = *(const LAS s16x4*)vp, hi = *(const LAS s16x4*)(vp + 8);
;                     const bf16x8 a = __builtin_shufflevector(lo, hi, 0, 1, 2, 3, 4, 5, 6, 7);
;                     o[dt] = MFMA32(a, pb, o[dt]); }
;             }
;         }
;         if (t + 1 < nt) ATT_STORE((t + 1) & 1);
.LBB0_862:
	v_fmamk_f32 v4, v64, 0x3e38aa3b, v146
	v_fmamk_f32 v5, v65, 0x3e38aa3b, v146
	v_fmamk_f32 v6, v66, 0x3e38aa3b, v146
	v_fmamk_f32 v7, v67, 0x3e38aa3b, v146
	v_fmamk_f32 v8, v68, 0x3e38aa3b, v146
	v_fmamk_f32 v9, v69, 0x3e38aa3b, v146
	v_fmamk_f32 v10, v70, 0x3e38aa3b, v146
	v_fmamk_f32 v11, v71, 0x3e38aa3b, v146
	v_exp_f32_e32 v4, v4
	v_exp_f32_e32 v5, v5
	v_exp_f32_e32 v6, v6
	v_exp_f32_e32 v7, v7
	v_exp_f32_e32 v8, v8
	v_exp_f32_e32 v9, v9
	v_exp_f32_e32 v10, v10
	v_exp_f32_e32 v11, v11
	v_fmamk_f32 v12, v72, 0x3e38aa3b, v146
	v_fmamk_f32 v13, v73, 0x3e38aa3b, v146
	v_fmamk_f32 v14, v74, 0x3e38aa3b, v146
	v_fmamk_f32 v15, v75, 0x3e38aa3b, v146
	v_fmamk_f32 v64, v76, 0x3e38aa3b, v146
	v_fmamk_f32 v65, v77, 0x3e38aa3b, v146
	v_fmamk_f32 v66, v78, 0x3e38aa3b, v146
	v_fmamk_f32 v67, v79, 0x3e38aa3b, v146
	ds_read2_b64 v[172:175], v0 offset0:16 offset1:18
	ds_read2_b64 v[176:179], v0 offset0:20 offset1:22
	ds_read2_b64 v[180:183], v2 offset0:48 offset1:50
	ds_read2_b64 v[184:187], v2 offset0:52 offset1:54
	ds_read2_b64 v[192:195], v0 offset0:24 offset1:26
	ds_read2_b64 v[196:199], v2 offset0:56 offset1:58
	v_cvt_pk_bf16_f32 v68, v4, v5
	v_cvt_pk_bf16_f32 v69, v6, v7
	v_cvt_pk_bf16_f32 v70, v8, v9
	v_cvt_pk_bf16_f32 v71, v10, v11
	v_exp_f32_e32 v12, v12
	v_exp_f32_e32 v13, v13
	s_waitcnt lgkmcnt(5)
	v_mfma_f32_32x32x16_bf16 v[32:47], v[172:175], v[68:71], v[32:47]
	ds_read2_b64 v[200:203], v0 offset0:28 offset1:30
	v_exp_f32_e32 v14, v14
	v_exp_f32_e32 v15, v15
	v_exp_f32_e32 v64, v64
	v_exp_f32_e32 v65, v65
	v_exp_f32_e32 v66, v66
	v_exp_f32_e32 v67, v67
	s_waitcnt lgkmcnt(4)
	v_mfma_f32_32x32x16_bf16 v[16:31], v[180:183], v[68:71], v[16:31]
	ds_read2_b64 v[204:207], v2 offset0:60 offset1:62
	v_cvt_pk_bf16_f32 v68, v12, v13
	v_cvt_pk_bf16_f32 v69, v14, v15
	v_cvt_pk_bf16_f32 v70, v64, v65
	v_cvt_pk_bf16_f32 v71, v66, v67
	v_fmamk_f32 v48, v48, 0x3e38aa3b, v146
	v_fmamk_f32 v49, v49, 0x3e38aa3b, v146
	s_waitcnt lgkmcnt(4)
	v_mfma_f32_32x32x16_bf16 v[16:31], v[184:187], v[68:71], v[16:31]
	v_fmamk_f32 v50, v50, 0x3e38aa3b, v146
	v_fmamk_f32 v51, v51, 0x3e38aa3b, v146
	v_fmamk_f32 v52, v52, 0x3e38aa3b, v146
	v_fmamk_f32 v53, v53, 0x3e38aa3b, v146
	v_fmamk_f32 v54, v54, 0x3e38aa3b, v146
	v_fmamk_f32 v55, v55, 0x3e38aa3b, v146
	s_waitcnt lgkmcnt(6)
	v_mfma_f32_32x32x16_bf16 v[32:47], v[176:179], v[68:71], v[32:47]
	v_exp_f32_e32 v48, v48
	v_exp_f32_e32 v49, v49
	v_exp_f32_e32 v50, v50
	v_exp_f32_e32 v51, v51
	v_exp_f32_e32 v52, v52
	v_exp_f32_e32 v53, v53
	v_exp_f32_e32 v54, v54
	v_exp_f32_e32 v55, v55
	v_cvt_pk_bf16_f32 v68, v48, v49
	v_cvt_pk_bf16_f32 v69, v50, v51
	v_cvt_pk_bf16_f32 v70, v52, v53
	v_cvt_pk_bf16_f32 v71, v54, v55
	v_fmamk_f32 v56, v56, 0x3e38aa3b, v146
	v_fmamk_f32 v57, v57, 0x3e38aa3b, v146
	s_waitcnt lgkmcnt(3)
	v_mfma_f32_32x32x16_bf16 v[32:47], v[192:195], v[68:71], v[32:47]
	v_fmamk_f32 v58, v58, 0x3e38aa3b, v146
	v_fmamk_f32 v59, v59, 0x3e38aa3b, v146
	v_fmamk_f32 v60, v60, 0x3e38aa3b, v146
	v_fmamk_f32 v61, v61, 0x3e38aa3b, v146
	v_fmamk_f32 v62, v62, 0x3e38aa3b, v146
	v_fmac_f32_e32 v146, 0x3e38aa3b, v63
	s_waitcnt lgkmcnt(2)
	v_mfma_f32_32x32x16_bf16 v[16:31], v[196:199], v[68:71], v[16:31]
	v_exp_f32_e32 v56, v56
	v_exp_f32_e32 v57, v57
	v_exp_f32_e32 v58, v58
	v_exp_f32_e32 v59, v59
	v_exp_f32_e32 v60, v60
	v_exp_f32_e32 v61, v61
	v_exp_f32_e32 v62, v62
	v_exp_f32_e32 v63, v146
	v_cvt_pk_bf16_f32 v68, v56, v57
	v_cvt_pk_bf16_f32 v69, v58, v59
	v_cvt_pk_bf16_f32 v70, v60, v61
	v_cvt_pk_bf16_f32 v71, v62, v63
	s_andn2_b64 vcc, exec, s[12:13]
	s_waitcnt lgkmcnt(1)
	v_mfma_f32_32x32x16_bf16 v[32:47], v[200:203], v[68:71], v[32:47]
	s_waitcnt lgkmcnt(0)
	v_mfma_f32_32x32x16_bf16 v[16:31], v[204:207], v[68:71], v[16:31]
	s_cbranch_vccnz .LBB0_864
	s_bitcmp1_b32 s35, 0
	s_cselect_b32 s4, 0x8a00, 0
	s_add_i32 s4, s4, 0
	v_add3_u32 v0, s4, v131, v132
	s_waitcnt vmcnt(3)
	ds_write_b128 v0, v[80:83]
	v_add_u32_e32 v0, s4, v133
	v_add3_u32 v0, v0, v134, s17
	s_waitcnt vmcnt(2)
	ds_write2_b64 v0, v[84:85], v[86:87] offset1:1
	v_add3_u32 v0, s4, v135, v136
	s_waitcnt vmcnt(1)
	ds_write_b128 v0, v[104:107]
	v_add_u32_e32 v0, s4, v137
	v_add3_u32 v0, v0, v138, s17
	s_waitcnt vmcnt(0)
	ds_write2_b64 v0, v[108:109], v[110:111] offset1:1
